# attention items: next item's K/V/Q prefetched into free VGPRs during current item's compute; staging barrier moved to loop header
# speedup vs baseline: 1.0043x; 1.0043x over previous
.LBB0_1268:
	ds_read_b128 v[170:173], v169
	ds_read_b128 v[174:177], v169 offset:16
	ds_read_b128 v[178:181], v169 offset:32
	ds_read_b128 v[182:185], v169 offset:48
	s_add_i32 s8, s8, -1
	s_waitcnt lgkmcnt(3)
	v_lshlrev_b32_e32 v186, 16, v170
	v_and_b32_e32 v187, 0xffff0000, v170
	v_lshlrev_b32_e32 v170, 16, v171
	v_and_b32_e32 v171, 0xffff0000, v171
	v_pk_add_f32 v[158:159], v[158:159], v[170:171]
	v_lshlrev_b32_e32 v170, 16, v172
	v_and_b32_e32 v171, 0xffff0000, v172
	v_pk_add_f32 v[156:157], v[156:157], v[170:171]
	v_lshlrev_b32_e32 v170, 16, v173
	v_and_b32_e32 v171, 0xffff0000, v173
	v_pk_add_f32 v[154:155], v[154:155], v[170:171]
	s_waitcnt lgkmcnt(2)
	v_lshlrev_b32_e32 v170, 16, v174
	v_and_b32_e32 v171, 0xffff0000, v174
	v_pk_add_f32 v[152:153], v[152:153], v[170:171]
	v_lshlrev_b32_e32 v170, 16, v175
	v_and_b32_e32 v171, 0xffff0000, v175
	v_pk_add_f32 v[150:151], v[150:151], v[170:171]
	v_lshlrev_b32_e32 v170, 16, v176
	v_and_b32_e32 v171, 0xffff0000, v176
	v_pk_add_f32 v[148:149], v[148:149], v[170:171]
	v_lshlrev_b32_e32 v170, 16, v177
	v_and_b32_e32 v171, 0xffff0000, v177
	v_pk_add_f32 v[146:147], v[146:147], v[170:171]
	s_waitcnt lgkmcnt(1)
	v_lshlrev_b32_e32 v170, 16, v178
	v_and_b32_e32 v171, 0xffff0000, v178
	v_pk_add_f32 v[144:145], v[144:145], v[170:171]
	v_lshlrev_b32_e32 v170, 16, v179
	v_and_b32_e32 v171, 0xffff0000, v179
	v_pk_add_f32 v[142:143], v[142:143], v[170:171]
	v_lshlrev_b32_e32 v170, 16, v180
	v_and_b32_e32 v171, 0xffff0000, v180
	v_pk_add_f32 v[140:141], v[140:141], v[170:171]
	v_lshlrev_b32_e32 v170, 16, v181
	v_and_b32_e32 v171, 0xffff0000, v181
	v_pk_add_f32 v[138:139], v[138:139], v[170:171]
	s_waitcnt lgkmcnt(0)
	v_lshlrev_b32_e32 v170, 16, v182
	v_and_b32_e32 v171, 0xffff0000, v182
	v_pk_add_f32 v[136:137], v[136:137], v[170:171]
	v_lshlrev_b32_e32 v170, 16, v183
	v_and_b32_e32 v171, 0xffff0000, v183
	v_pk_add_f32 v[134:135], v[134:135], v[170:171]
	v_lshlrev_b32_e32 v170, 16, v184
	v_and_b32_e32 v171, 0xffff0000, v184
	v_pk_add_f32 v[132:133], v[132:133], v[170:171]
	v_lshlrev_b32_e32 v170, 16, v185
	v_and_b32_e32 v171, 0xffff0000, v185
	v_pk_add_f32 v[160:161], v[160:161], v[186:187]
	v_pk_add_f32 v[130:131], v[130:131], v[170:171]
	v_add_u32_e32 v169, 0xfffffef0, v169
	s_cmp_lg_u32 s8, 0
	s_cbranch_scc1 .LBB0_1268
	v_readlane_b32 s8, v253, 39
	v_add3_u32 v182, 0, v166, v167
	s_mov_b64 s[10:11], 0x11101000
	v_add_u32_e32 v168, s8, v168
	v_readlane_b32 s8, v253, 27
	s_mov_b32 s72, 0
	s_nop 0
	v_min_i32_e32 v168, s8, v168
	v_cvt_f32_i32_e32 v170, v168
	ds_read_b128 v[166:169], v182 offset:4080
	v_div_scale_f32 v171, s[8:9], v170, v170, 1.0
	v_rcp_f32_e32 v172, v171
	v_div_scale_f32 v173, vcc, 1.0, v170, 1.0
	s_waitcnt lgkmcnt(0)
	v_lshlrev_b32_e32 v184, 16, v166
	v_fma_f32 v174, -v171, v172, 1.0
	v_fmac_f32_e32 v172, v174, v172
	v_mul_f32_e32 v174, v173, v172
	v_fma_f32 v175, -v171, v174, v173
	v_fmac_f32_e32 v174, v175, v172
	v_fma_f32 v171, -v171, v174, v173
	v_div_fmas_f32 v171, v171, v172, v174
	v_div_fixup_f32 v183, v171, v170, 1.0
	v_fma_f32 v160, v183, v160, -v184
	v_and_b32_e32 v166, 0xffff0000, v166
	v_fma_f32 v161, v183, v161, -v166
	v_cvt_pk_bf16_f32 v166, v160, v161
	v_lshlrev_b32_e32 v160, 16, v167
	v_fma_f32 v158, v183, v158, -v160
	v_and_b32_e32 v160, 0xffff0000, v167
	v_fma_f32 v159, v183, v159, -v160
	v_cvt_pk_bf16_f32 v167, v158, v159
	v_lshlrev_b32_e32 v158, 16, v168
	ds_read_b128 v[170:173], v182 offset:4096
	ds_read_b128 v[174:177], v182 offset:4112
	ds_read_b128 v[178:181], v182 offset:4128
	v_fma_f32 v156, v183, v156, -v158
	v_and_b32_e32 v158, 0xffff0000, v168
	v_fma_f32 v157, v183, v157, -v158
	v_cvt_pk_bf16_f32 v168, v156, v157
	v_lshlrev_b32_e32 v156, 16, v169
	v_fma_f32 v154, v183, v154, -v156
	v_and_b32_e32 v156, 0xffff0000, v169
	v_fma_f32 v155, v183, v155, -v156
	v_cvt_pk_bf16_f32 v169, v154, v155
	s_waitcnt lgkmcnt(2)
	v_lshlrev_b32_e32 v154, 16, v170
	v_fma_f32 v152, v183, v152, -v154
	v_and_b32_e32 v154, 0xffff0000, v170
	v_fma_f32 v153, v183, v153, -v154
	v_cvt_pk_bf16_f32 v152, v152, v153
	v_lshlrev_b32_e32 v153, 16, v171
	v_fma_f32 v150, v183, v150, -v153
	v_and_b32_e32 v153, 0xffff0000, v171
	v_fma_f32 v151, v183, v151, -v153
	v_cvt_pk_bf16_f32 v153, v150, v151
	v_lshlrev_b32_e32 v150, 16, v172
	v_fma_f32 v148, v183, v148, -v150
	v_and_b32_e32 v150, 0xffff0000, v172
	v_fma_f32 v149, v183, v149, -v150
	v_cvt_pk_bf16_f32 v154, v148, v149
	v_lshlrev_b32_e32 v148, 16, v173
	v_fma_f32 v146, v183, v146, -v148
	v_and_b32_e32 v148, 0xffff0000, v173
	v_fma_f32 v147, v183, v147, -v148
	v_cvt_pk_bf16_f32 v155, v146, v147
	s_waitcnt lgkmcnt(1)
	v_lshlrev_b32_e32 v146, 16, v174
	v_fma_f32 v144, v183, v144, -v146
	v_and_b32_e32 v146, 0xffff0000, v174
	v_fma_f32 v145, v183, v145, -v146
	v_cvt_pk_bf16_f32 v144, v144, v145
	v_lshlrev_b32_e32 v145, 16, v175
	v_fma_f32 v142, v183, v142, -v145
	v_and_b32_e32 v145, 0xffff0000, v175
	v_fma_f32 v143, v183, v143, -v145
	v_cvt_pk_bf16_f32 v145, v142, v143
	v_lshlrev_b32_e32 v142, 16, v176
	v_fma_f32 v140, v183, v140, -v142
	v_and_b32_e32 v142, 0xffff0000, v176
	v_fma_f32 v141, v183, v141, -v142
	v_cvt_pk_bf16_f32 v146, v140, v141
	v_lshlrev_b32_e32 v140, 16, v177
	v_fma_f32 v138, v183, v138, -v140
	v_and_b32_e32 v140, 0xffff0000, v177
	v_fma_f32 v139, v183, v139, -v140
	v_cvt_pk_bf16_f32 v147, v138, v139
	s_waitcnt lgkmcnt(0)
	v_lshlrev_b32_e32 v138, 16, v178
	v_fma_f32 v136, v183, v136, -v138
	v_and_b32_e32 v138, 0xffff0000, v178
	v_fma_f32 v137, v183, v137, -v138
	v_cvt_pk_bf16_f32 v136, v136, v137
	v_lshlrev_b32_e32 v137, 16, v179
	v_fma_f32 v134, v183, v134, -v137
	v_and_b32_e32 v137, 0xffff0000, v179
	v_fma_f32 v135, v183, v135, -v137
	v_cvt_pk_bf16_f32 v137, v134, v135
	v_lshlrev_b32_e32 v134, 16, v180
	v_fma_f32 v132, v183, v132, -v134
	v_and_b32_e32 v134, 0xffff0000, v180
	v_fma_f32 v133, v183, v133, -v134
	v_cvt_pk_bf16_f32 v138, v132, v133
	v_lshlrev_b32_e32 v132, 16, v181
	v_fma_f32 v130, v183, v130, -v132
	v_and_b32_e32 v132, 0xffff0000, v181
	s_ashr_i32 s8, s15, 2
	v_fma_f32 v131, v183, v131, -v132
	v_and_or_b32 v142, s8, -16, v165
	v_cvt_pk_bf16_f32 v139, v130, v131
	v_mul_lo_u32 v130, v142, s33
	v_and_b32_e32 v131, 48, v164
	v_add3_u32 v143, 0, v130, v131
	ds_write_b128 v182, v[166:169] offset:40960
	ds_write_b128 v182, v[152:155] offset:40976
	ds_write_b128 v182, v[144:147] offset:40992
	ds_write_b128 v182, v[136:139] offset:41008
	s_waitcnt lgkmcnt(0)
	s_barrier
	ds_read_b128 v[134:137], v143 offset:40960
	ds_read_b128 v[130:133], v143 offset:41024
	s_waitcnt vmcnt(31) lgkmcnt(1)
	v_mfma_f32_16x16x32_bf16 v[114:117], v[114:117], v[134:137], 0
	v_readlane_b32 s8, v253, 32
	s_waitcnt vmcnt(30) lgkmcnt(0)
	v_mfma_f32_16x16x32_bf16 v[138:141], v[110:113], v[130:133], v[114:117]
	s_nop 4
	ds_read_b128 v[114:117], v143 offset:41088
	ds_read_b128 v[110:113], v143 offset:41152
	s_waitcnt vmcnt(29) lgkmcnt(1)
	v_mfma_f32_16x16x32_bf16 v[106:109], v[106:109], v[114:117], v[138:141]
	s_waitcnt vmcnt(28) lgkmcnt(0)
	v_mfma_f32_16x16x32_bf16 v[102:105], v[102:105], v[110:113], v[106:109]
	s_waitcnt vmcnt(1)
	v_mfma_f32_16x16x32_bf16 v[106:109], v[126:129], v[134:137], 0
	v_add_u32_e32 v126, s8, v142
	v_mfma_f32_16x16x32_bf16 v[106:109], v[122:125], v[130:133], v[106:109]
	v_mov_b64_e32 v[122:123], s[24:25]
	v_mad_i64_i32 v[122:123], s[8:9], v126, s70, v[122:123]
	v_mfma_f32_16x16x32_bf16 v[106:109], v[118:121], v[114:117], v[106:109]
	v_readlane_b32 s8, v253, 29
	s_lshl_b32 s28, s8, 1
	v_lshl_add_u64 v[122:123], v[122:123], 0, s[28:29]
	v_mfma_f32_16x16x32_bf16 v[118:121], v[98:101], v[134:137], 0
	v_lshlrev_b32_e32 v124, 3, v163
	v_mov_b32_e32 v125, v33
	v_lshl_add_u64 v[100:101], v[122:123], 0, v[124:125]
	v_mfma_f32_16x16x32_bf16 v[94:97], v[94:97], v[130:133], v[118:121]
	s_mov_b32 s9, 0x11101000
	v_lshl_add_u64 v[98:99], v[100:101], 0, s[10:11]
	v_add_co_u32_e32 v100, vcc, s9, v100
	v_mfma_f32_16x16x32_bf16 v[90:93], v[90:93], v[114:117], v[94:97]
	s_lshl_b32 s8, s8, 2
	v_addc_co_u32_e32 v101, vcc, 0, v101, vcc
	v_mfma_f32_16x16x32_bf16 v[94:97], v[82:85], v[134:137], 0
	s_add_u32 s10, s2, s8
	global_load_dwordx2 v[118:119], v[98:99], off offset:32
	global_load_dwordx2 v[120:121], v[98:99], off offset:64
	global_load_dwordx2 v[122:123], v[98:99], off offset:96
	global_load_dwordx2 v[124:125], v[98:99], off offset:128
	global_load_dwordx2 v[84:85], v[100:101], off
	global_load_dwordx2 v[126:127], v[98:99], off offset:160
	global_load_dwordx2 v[128:129], v[98:99], off offset:192
	global_load_dwordx2 v[82:83], v[98:99], off offset:224
	v_mfma_f32_16x16x32_bf16 v[78:81], v[78:81], v[130:133], v[94:97]
	s_addc_u32 s11, s14, 0
	s_lshl_b32 s8, s18, 11
	v_mfma_f32_16x16x32_bf16 v[74:77], v[74:77], v[114:117], v[78:81]
	s_mov_b32 s2, 0
	s_waitcnt vmcnt(3)
	v_lshlrev_b32_e32 v94, 16, v84
	s_nop 1
	global_load_dwordx4 v[78:81], v32, s[10:11]
	v_mfma_f32_16x16x32_bf16 v[70:73], v[70:73], v[134:137], 0
	s_waitcnt vmcnt(0)
	v_mul_f32_e32 v78, v102, v78
	v_mfma_f32_16x16x32_bf16 v[66:69], v[66:69], v[130:133], v[70:73]
	v_mul_f32_e32 v78, v78, v94
	v_mfma_f32_16x16x32_bf16 v[58:61], v[58:61], v[114:117], v[66:69]
	s_nop 2
	v_mul_f32_e32 v70, v103, v79
	v_and_b32_e32 v71, 0xffff0000, v84
	v_mul_f32_e32 v70, v70, v71
	v_mfma_f32_16x16x32_bf16 v[66:69], v[86:89], v[134:137], 0
	v_mul_f32_e32 v71, v104, v80
	v_lshlrev_b32_e32 v72, 16, v85
	v_mul_f32_e32 v71, v71, v72
	v_mfma_f32_16x16x32_bf16 v[62:65], v[62:65], v[130:133], v[66:69]
	v_mul_f32_e32 v72, v105, v81
	v_and_b32_e32 v73, 0xffff0000, v85
	v_cvt_pk_bf16_f32 v70, v78, v70
	v_mfma_f32_16x16x32_bf16 v[50:53], v[50:53], v[114:117], v[62:65]
	s_nop 0
	v_mul_f32_e32 v66, v72, v73
	v_cvt_pk_bf16_f32 v71, v71, v66
	global_store_dwordx2 v[100:101], v[70:71], off
	v_mfma_f32_16x16x32_bf16 v[38:41], v[38:41], v[110:113], v[106:109]
	s_nop 0
	global_load_dwordx4 v[62:65], v32, s[10:11] offset:64
	v_lshlrev_b32_e32 v66, 16, v118
	v_and_b32_e32 v67, 0xffff0000, v118
	v_mfma_f32_16x16x32_bf16 v[54:57], v[54:57], v[134:137], 0
	v_mfma_f32_16x16x32_bf16 v[20:23], v[20:23], v[110:113], v[90:93]
	s_waitcnt vmcnt(0)
	s_nop 0
	v_mul_f32_e32 v38, v38, v62
	v_mul_f32_e32 v39, v39, v63
	v_mul_f32_e32 v38, v38, v66
	v_mul_f32_e32 v40, v40, v64
	v_mul_f32_e32 v39, v39, v67
	v_cvt_pk_bf16_f32 v62, v38, v39
	v_lshlrev_b32_e32 v38, 16, v119
	v_mul_f32_e32 v63, v40, v38
	v_mul_f32_e32 v64, v41, v65
	v_mfma_f32_16x16x32_bf16 v[38:41], v[46:49], v[130:133], v[54:57]
	v_and_b32_e32 v65, 0xffff0000, v119
	v_mul_f32_e32 v46, v64, v65
	v_cvt_pk_bf16_f32 v63, v63, v46
	global_store_dwordx2 v[98:99], v[62:63], off offset:32
	v_mfma_f32_16x16x32_bf16 v[38:41], v[42:45], v[114:117], v[38:41]
	global_load_dwordx4 v[42:45], v32, s[10:11] offset:128
	v_lshlrev_b32_e32 v46, 16, v120
	v_and_b32_e32 v47, 0xffff0000, v120
	v_lshlrev_b32_e32 v48, 16, v121
	v_and_b32_e32 v49, 0xffff0000, v121
	v_mfma_f32_16x16x32_bf16 v[16:19], v[16:19], v[110:113], v[74:77]
	s_waitcnt vmcnt(0)
	v_mul_f32_e32 v20, v20, v42
	v_mul_f32_e32 v21, v21, v43
	v_mul_f32_e32 v22, v22, v44
	v_mul_f32_e32 v23, v23, v45
	v_mul_f32_e32 v20, v20, v46
	v_mul_f32_e32 v21, v21, v47
	v_mul_f32_e32 v22, v22, v48
	v_mul_f32_e32 v23, v23, v49
	v_cvt_pk_bf16_f32 v20, v20, v21
	v_cvt_pk_bf16_f32 v21, v22, v23
	global_store_dwordx2 v[98:99], v[20:21], off offset:64
	global_load_dwordx4 v[20:23], v32, s[10:11] offset:192
	v_lshlrev_b32_e32 v42, 16, v122
	v_and_b32_e32 v43, 0xffff0000, v122
	v_lshlrev_b32_e32 v44, 16, v123
	v_and_b32_e32 v45, 0xffff0000, v123
	v_mfma_f32_16x16x32_bf16 v[8:11], v[8:11], v[134:137], 0
	s_waitcnt vmcnt(0)
	v_mul_f32_e32 v16, v16, v20
	v_mul_f32_e32 v17, v17, v21
	v_mul_f32_e32 v18, v18, v22
	v_mul_f32_e32 v19, v19, v23
	v_mul_f32_e32 v16, v16, v42
	v_mul_f32_e32 v17, v17, v43
	v_mul_f32_e32 v18, v18, v44
	v_mul_f32_e32 v19, v19, v45
	v_cvt_pk_bf16_f32 v16, v16, v17
	v_cvt_pk_bf16_f32 v17, v18, v19
	global_store_dwordx2 v[98:99], v[16:17], off offset:96
	global_load_dwordx4 v[16:19], v32, s[10:11] offset:256
	v_mfma_f32_16x16x32_bf16 v[20:23], v[34:37], v[110:113], v[58:61]
	v_lshlrev_b32_e32 v34, 16, v124
	v_and_b32_e32 v35, 0xffff0000, v124
	v_lshlrev_b32_e32 v36, 16, v125
	v_and_b32_e32 v37, 0xffff0000, v125
	v_mfma_f32_16x16x32_bf16 v[4:7], v[4:7], v[130:133], v[8:11]
	s_waitcnt vmcnt(0)
	s_nop 1
	v_mul_f32_e32 v16, v20, v16
	v_mul_f32_e32 v17, v21, v17
	v_mul_f32_e32 v18, v22, v18
	v_mul_f32_e32 v19, v23, v19
	v_mul_f32_e32 v16, v16, v34
	v_mul_f32_e32 v17, v17, v35
	v_mul_f32_e32 v18, v18, v36
	v_mul_f32_e32 v19, v19, v37
	v_cvt_pk_bf16_f32 v16, v16, v17
	v_cvt_pk_bf16_f32 v17, v18, v19
	global_store_dwordx2 v[98:99], v[16:17], off offset:128
	global_load_dwordx4 v[16:19], v32, s[10:11] offset:320
	v_mfma_f32_16x16x32_bf16 v[20:23], v[28:31], v[110:113], v[50:53]
	v_lshlrev_b32_e32 v28, 16, v126
	v_and_b32_e32 v29, 0xffff0000, v126
	v_lshlrev_b32_e32 v30, 16, v127
	v_and_b32_e32 v31, 0xffff0000, v127
	v_mfma_f32_16x16x32_bf16 v[0:3], v[0:3], v[114:117], v[4:7]
	s_waitcnt vmcnt(0)
	s_nop 1
	v_mul_f32_e32 v16, v20, v16
	v_mul_f32_e32 v17, v21, v17
	v_mul_f32_e32 v18, v22, v18
	v_mul_f32_e32 v19, v23, v19
	v_mul_f32_e32 v16, v16, v28
	v_mul_f32_e32 v17, v17, v29
	v_mul_f32_e32 v18, v18, v30
	v_mul_f32_e32 v19, v19, v31
	v_cvt_pk_bf16_f32 v16, v16, v17
	v_cvt_pk_bf16_f32 v17, v18, v19
	global_store_dwordx2 v[98:99], v[16:17], off offset:160
	global_load_dwordx4 v[16:19], v32, s[10:11] offset:384
	v_mfma_f32_16x16x32_bf16 v[20:23], v[24:27], v[110:113], v[38:41]
	v_lshlrev_b32_e32 v24, 16, v128
	v_and_b32_e32 v25, 0xffff0000, v128
	v_lshlrev_b32_e32 v26, 16, v129
	v_and_b32_e32 v27, 0xffff0000, v129
	v_mfma_f32_16x16x32_bf16 v[0:3], v[12:15], v[110:113], v[0:3]
	v_lshlrev_b32_e32 v4, 16, v82
	v_and_b32_e32 v5, 0xffff0000, v82
	v_lshlrev_b32_e32 v6, 16, v83
	v_and_b32_e32 v7, 0xffff0000, v83
	s_waitcnt vmcnt(0)
	v_mul_f32_e32 v16, v20, v16
	v_mul_f32_e32 v17, v21, v17
	v_mul_f32_e32 v18, v22, v18
	v_mul_f32_e32 v19, v23, v19
	v_mul_f32_e32 v16, v16, v24
	v_mul_f32_e32 v17, v17, v25
	v_mul_f32_e32 v18, v18, v26
	v_mul_f32_e32 v19, v19, v27
	v_cvt_pk_bf16_f32 v16, v16, v17
	v_cvt_pk_bf16_f32 v17, v18, v19
	global_store_dwordx2 v[98:99], v[16:17], off offset:192
	global_load_dwordx4 v[16:19], v32, s[10:11] offset:448
	v_xor_b32_e32 v20, 16, v226
	v_xor_b32_e32 v21, 32, v226
	v_cmp_lt_i32_e32 vcc, v20, v162
	v_readlane_b32 s10, v251, 33
	v_readlane_b32 s11, v251, 34
	v_cndmask_b32_e32 v20, v226, v20, vcc
	v_cmp_lt_i32_e32 vcc, v21, v162
	s_add_u32 s66, s10, s8
	v_lshlrev_b32_e32 v100, 2, v20
	v_cndmask_b32_e32 v8, v226, v21, vcc
	v_lshlrev_b32_e32 v101, 2, v8
	s_addc_u32 s67, s11, 0
	s_waitcnt vmcnt(0)
	v_mul_f32_e32 v0, v0, v16
	v_mul_f32_e32 v1, v1, v17
	v_mul_f32_e32 v2, v2, v18
	v_mul_f32_e32 v3, v3, v19
	v_mul_f32_e32 v0, v0, v4
	v_mul_f32_e32 v1, v1, v5
	v_mul_f32_e32 v2, v2, v6
	v_mul_f32_e32 v3, v3, v7
	v_cvt_pk_bf16_f32 v0, v0, v1
	v_cvt_pk_bf16_f32 v1, v2, v3
	global_store_dwordx2 v[98:99], v[0:1], off offset:224
	s_barrier
	s_mov_b32 s48, 0
	s_branch .Lpf_issue
.Lpf_ret_pre:
	s_branch .LBB0_1272
.LBB0_1270:
	s_or_b64 exec, exec, s[10:11]
	s_barrier

.LBB0_1272:
	v_lshrrev_b32_e32 v227, 4, v218
	v_and_b32_e32 v244, 15, v218
	v_lshlrev_b32_e32 v244, 4, v244
	v_mul_u32_u24_e32 v245, 0x120, v227
	v_add3_u32 v245, s27, v244, v245
	v_mad_u32_u24 v244, v227, s33, v244
	s_cmp_lg_u32 s72, 0
	s_cbranch_scc1 .Lpf_wait_cnt
	s_waitcnt vmcnt(0)
.Lpf_wait_cnt:
	s_waitcnt vmcnt(8)
	ds_write_b128 v244, v[154:157]
	ds_write_b128 v245, v[158:161]
	ds_write_b128 v244, v[162:165] offset:8704
	ds_write_b128 v245, v[166:169] offset:9216
	ds_write_b128 v244, v[170:173] offset:17408
	ds_write_b128 v245, v[174:177] offset:18432
	ds_write_b128 v244, v[178:181] offset:26112
	ds_write_b128 v245, v[182:185] offset:27648
	ds_write_b128 v244, v[186:189] offset:34816
	ds_write_b128 v245, v[190:193] offset:36864
	ds_write_b128 v244, v[194:197] offset:43520
	ds_write_b128 v245, v[198:201] offset:46080
	ds_write_b128 v244, v[202:205] offset:52224
	ds_write_b128 v245, v[206:209] offset:55296
	ds_write_b128 v244, v[210:213] offset:60928
	ds_write_b128 v245, v[214:217] offset:64512
	s_waitcnt lgkmcnt(0)
	s_barrier
	s_and_b32 s8, s2, 2
	v_readlane_b32 s9, v252, 56
	s_or_b32 s74, s8, s9
	v_mov_b32_e32 v99, v218
	s_lshl_b32 s8, s74, 7
	v_readlane_b32 s9, v252, 55
	s_or_b32 s8, s9, s8
	v_readfirstlane_b32 s76, v99
	v_readlane_b32 s9, v253, 22
	s_ashr_i32 s73, s76, 6
	s_or_b32 s75, s8, s9
	v_and_b32_e32 v98, 63, v99
	s_cmp_gt_u32 s72, 1
	s_mov_b64 s[10:11], -1
	s_cbranch_scc0 .LBB0_1352
	s_cmp_gt_u32 s72, 3
	s_cbranch_scc0 .LBB0_1314
	s_lshl_b32 s77, s75, 7
	s_and_b32 s12, s77, 0x180
	v_ashrrev_i32_e32 v104, 4, v99
	s_movk_i32 s9, 0x120
	s_cmp_gt_u32 s72, 5
	v_mul_lo_u32 v102, v104, s33
	v_mul_lo_u32 v103, v104, s9
	s_cbranch_scc0 .LBB0_1276
	s_lshl_b32 s10, s8, 5
	s_lshl_b32 s28, s12, 1
	s_add_u32 s8, s66, s28
	v_lshl_add_u32 v0, s74, 8, v104
	v_lshlrev_b32_e32 v1, 4, v99
	s_addc_u32 s9, s67, 0
	v_and_b32_e32 v32, 0xf0, v1
	v_ashrrev_i32_e32 v1, 31, v0
	v_lshl_add_u64 v[2:3], s[8:9], 0, v[32:33]
	v_lshlrev_b64 v[0:1], 13, v[0:1]
	v_lshl_add_u64 v[0:1], v[2:3], 0, v[0:1]
	s_mov_b64 s[8:9], 0x40000
	v_lshl_add_u64 v[2:3], v[0:1], 0, s[8:9]
	s_mov_b32 s8, 0x40000
	v_add_co_u32_e32 v12, vcc, s8, v0
	s_mov_b64 s[8:9], 0x80000
	s_nop 0
	v_addc_co_u32_e32 v13, vcc, 0, v1, vcc
	s_nop 0
	s_nop 0
	v_lshl_add_u64 v[2:3], v[0:1], 0, s[8:9]
	s_mov_b32 s8, 0x80000
	v_add_co_u32_e32 v20, vcc, s8, v0
	s_mov_b64 s[8:9], 0xc0000
	s_nop 0
	v_addc_co_u32_e32 v21, vcc, 0, v1, vcc
	s_nop 0
	v_lshl_add_u64 v[2:3], v[0:1], 0, s[8:9]
	s_mov_b32 s8, 0xc0000
	v_add_co_u32_e32 v28, vcc, s8, v0
	s_mov_b64 s[8:9], 0x100000
	s_nop 0
	v_addc_co_u32_e32 v29, vcc, 0, v1, vcc
	v_add_co_u32_e32 v38, vcc, s79, v0
	s_nop 0
	v_lshl_add_u64 v[2:3], v[0:1], 0, s[8:9]
	v_addc_co_u32_e32 v39, vcc, 0, v1, vcc
	s_mov_b64 s[8:9], 0x140000
	s_nop 0
	v_lshl_add_u64 v[2:3], v[0:1], 0, s[8:9]
	s_mov_b32 s8, 0x140000
	v_add_co_u32_e32 v46, vcc, s8, v0
	s_mov_b64 s[8:9], 0x180000
	s_nop 0
	v_addc_co_u32_e32 v47, vcc, 0, v1, vcc
	s_nop 0
	v_lshl_add_u64 v[2:3], v[0:1], 0, s[8:9]
	s_mov_b32 s8, 0x180000
	v_add_co_u32_e32 v54, vcc, s8, v0
	s_mov_b64 s[8:9], 0x1c0000
	s_nop 0
	v_addc_co_u32_e32 v55, vcc, 0, v1, vcc
	s_nop 0
	v_lshl_add_u64 v[2:3], v[0:1], 0, s[8:9]
	s_mov_b32 s8, 0x1c0000
	v_add_co_u32_e32 v0, vcc, s8, v0
	s_and_b32 s10, s10, 0x3f80
	s_nop 0
	v_addc_co_u32_e32 v1, vcc, 0, v1, vcc
	v_readlane_b32 s8, v252, 31
	s_add_u32 s8, s8, s28
	v_readlane_b32 s9, v252, 32
	s_addc_u32 s9, s9, 0
	s_lshl_b32 s11, s73, 4
	v_and_b32_e32 v108, 15, v99
	s_add_i32 s11, s11, s10
	v_or_b32_e32 v82, s11, v108
	v_mov_b64_e32 v[0:1], s[8:9]
	v_mad_i64_i32 v[0:1], s[8:9], v82, s70, v[0:1]
	v_and_b32_e32 v106, 48, v99
	v_mov_b32_e32 v107, v33
	v_lshl_add_u64 v[70:71], v[0:1], 0, v[106:107]
	v_add3_u32 v83, 0, v32, v102
	s_nop 0
	v_lshrrev_b32_e32 v105, 2, v98
	v_add3_u32 v4, s27, v32, v103
	v_lshrrev_b32_e32 v6, 1, v98
	v_and_b32_e32 v32, 24, v6
	v_mov_b64_e32 v[4:5], s[24:25]
	v_mad_i64_i32 v[4:5], s[8:9], v82, s70, v[4:5]
	v_lshl_add_u64 v[4:5], v[4:5], 0, s[28:29]
	v_lshl_add_u64 v[4:5], v[4:5], 0, v[32:33]
	s_mov_b64 s[8:9], 0x11103000
	v_lshl_add_u64 v[78:79], v[4:5], 0, s[8:9]
	s_mov_b32 s8, 0x11103000
	v_add_co_u32_e32 v94, vcc, s8, v4
	s_waitcnt lgkmcnt(0)
	s_nop 0
	v_addc_co_u32_e32 v95, vcc, 0, v5, vcc
	v_mov_b64_e32 v[0:1], v[228:229]
	v_mov_b64_e32 v[2:3], v[230:231]
	v_mov_b64_e32 v[62:63], v[232:233]
	v_mov_b64_e32 v[64:65], v[234:235]
	v_mov_b64_e32 v[66:67], v[236:237]
	v_mov_b64_e32 v[68:69], v[238:239]
	v_mov_b64_e32 v[70:71], v[240:241]
	v_mov_b64_e32 v[72:73], v[242:243]
	s_add_u32 s48, s72, 1
	s_cmp_lt_u32 s48, 8
	s_cbranch_scc1 .Lpf_issue
.Lpf_ret_k3:
	global_load_dwordx2 v[96:97], v[94:95], off
	global_load_dwordx2 v[92:93], v[78:79], off offset:32
	global_load_dwordx2 v[90:91], v[78:79], off offset:64
	global_load_dwordx2 v[88:89], v[78:79], off offset:96
	global_load_dwordx2 v[86:87], v[78:79], off offset:128
	global_load_dwordx2 v[84:85], v[78:79], off offset:160
	global_load_dwordx2 v[82:83], v[78:79], off offset:192
	global_load_dwordx2 v[80:81], v[78:79], off offset:224
	v_add_u32_e32 v32, 0, v106
	v_mad_u32_u24 v126, v108, s33, v32
	ds_read_b128 v[4:7], v126
	ds_read_b128 v[8:11], v126 offset:64
	ds_read_b128 v[12:15], v126 offset:128
	ds_read_b128 v[16:19], v126 offset:192
	ds_read_b128 v[20:23], v126 offset:4352
	ds_read_b128 v[24:27], v126 offset:4416
	ds_read_b128 v[28:31], v126 offset:4480
	ds_read_b128 v[34:37], v126 offset:4544
	s_waitcnt lgkmcnt(7)
	v_mfma_f32_16x16x32_bf16 v[4:7], v[4:7], v[0:3], 0
	s_waitcnt lgkmcnt(6)
	v_mfma_f32_16x16x32_bf16 v[4:7], v[8:11], v[62:65], v[4:7]
	s_waitcnt lgkmcnt(5)
	v_mfma_f32_16x16x32_bf16 v[4:7], v[12:15], v[66:69], v[4:7]
	s_waitcnt lgkmcnt(4)
	v_mfma_f32_16x16x32_bf16 v[74:77], v[16:19], v[70:73], v[4:7]
	s_waitcnt lgkmcnt(3)
	v_mfma_f32_16x16x32_bf16 v[4:7], v[20:23], v[0:3], 0
	s_waitcnt lgkmcnt(2)
	v_mfma_f32_16x16x32_bf16 v[4:7], v[24:27], v[62:65], v[4:7]
	s_waitcnt lgkmcnt(1)
	v_mfma_f32_16x16x32_bf16 v[4:7], v[28:31], v[66:69], v[4:7]
	s_waitcnt lgkmcnt(0)
	v_mfma_f32_16x16x32_bf16 v[58:61], v[34:37], v[70:73], v[4:7]
	v_or_b32_e32 v20, 48, v98
	v_mad_u32_u24 v34, v20, s33, v32
	s_nop 3
	ds_read_b128 v[4:7], v126 offset:8704
	ds_read_b128 v[8:11], v126 offset:8768
	ds_read_b128 v[12:15], v126 offset:8832
	ds_read_b128 v[16:19], v126 offset:8896
	ds_read_b128 v[20:23], v34
	ds_read_b128 v[24:27], v34 offset:64
	ds_read_b128 v[28:31], v34 offset:128
	ds_read_b128 v[34:37], v34 offset:192
	s_waitcnt lgkmcnt(7)
	v_mfma_f32_16x16x32_bf16 v[4:7], v[4:7], v[0:3], 0
	s_waitcnt lgkmcnt(6)
	v_mfma_f32_16x16x32_bf16 v[4:7], v[8:11], v[62:65], v[4:7]
	s_waitcnt lgkmcnt(5)
	v_mfma_f32_16x16x32_bf16 v[4:7], v[12:15], v[66:69], v[4:7]
	s_waitcnt lgkmcnt(4)
	v_mfma_f32_16x16x32_bf16 v[54:57], v[16:19], v[70:73], v[4:7]
	s_waitcnt lgkmcnt(3)
	v_mfma_f32_16x16x32_bf16 v[4:7], v[20:23], v[0:3], 0
	s_waitcnt lgkmcnt(2)
	v_mfma_f32_16x16x32_bf16 v[4:7], v[24:27], v[62:65], v[4:7]
	s_waitcnt lgkmcnt(1)
	v_mfma_f32_16x16x32_bf16 v[4:7], v[28:31], v[66:69], v[4:7]
	s_waitcnt lgkmcnt(0)
	v_mfma_f32_16x16x32_bf16 v[50:53], v[34:37], v[70:73], v[4:7]
	s_nop 5
	ds_read_b128 v[4:7], v126 offset:17408
	ds_read_b128 v[8:11], v126 offset:17472
	ds_read_b128 v[12:15], v126 offset:17536
	ds_read_b128 v[16:19], v126 offset:17600
	ds_read_b128 v[20:23], v126 offset:21760
	ds_read_b128 v[24:27], v126 offset:21824
	ds_read_b128 v[28:31], v126 offset:21888
	ds_read_b128 v[34:37], v126 offset:21952
	s_waitcnt lgkmcnt(7)
	v_mfma_f32_16x16x32_bf16 v[4:7], v[4:7], v[0:3], 0
	s_waitcnt lgkmcnt(6)
	v_mfma_f32_16x16x32_bf16 v[4:7], v[8:11], v[62:65], v[4:7]
	s_waitcnt lgkmcnt(5)
	v_mfma_f32_16x16x32_bf16 v[4:7], v[12:15], v[66:69], v[4:7]
	s_waitcnt lgkmcnt(4)
	v_mfma_f32_16x16x32_bf16 v[46:49], v[16:19], v[70:73], v[4:7]
	s_waitcnt lgkmcnt(3)
	v_mfma_f32_16x16x32_bf16 v[4:7], v[20:23], v[0:3], 0
	s_waitcnt lgkmcnt(2)
	v_mfma_f32_16x16x32_bf16 v[4:7], v[24:27], v[62:65], v[4:7]
	s_waitcnt lgkmcnt(1)
	v_mfma_f32_16x16x32_bf16 v[4:7], v[28:31], v[66:69], v[4:7]
	s_waitcnt lgkmcnt(0)
	v_mfma_f32_16x16x32_bf16 v[42:45], v[34:37], v[70:73], v[4:7]
	v_or_b32_e32 v20, 0x70, v98
	v_mad_u32_u24 v34, v20, s33, v32
	s_nop 3
	ds_read_b128 v[4:7], v126 offset:26112
	ds_read_b128 v[8:11], v126 offset:26176
	ds_read_b128 v[12:15], v126 offset:26240
	ds_read_b128 v[16:19], v126 offset:26304
	ds_read_b128 v[20:23], v34
	ds_read_b128 v[24:27], v34 offset:64
	ds_read_b128 v[28:31], v34 offset:128
	ds_read_b128 v[34:37], v34 offset:192
	s_waitcnt lgkmcnt(7)
	v_mfma_f32_16x16x32_bf16 v[4:7], v[4:7], v[0:3], 0
	s_waitcnt lgkmcnt(6)
	v_mfma_f32_16x16x32_bf16 v[4:7], v[8:11], v[62:65], v[4:7]
	s_waitcnt lgkmcnt(5)
	v_mfma_f32_16x16x32_bf16 v[4:7], v[12:15], v[66:69], v[4:7]
	s_waitcnt lgkmcnt(4)
	v_mfma_f32_16x16x32_bf16 v[38:41], v[16:19], v[70:73], v[4:7]
	s_waitcnt lgkmcnt(3)
	v_mfma_f32_16x16x32_bf16 v[4:7], v[20:23], v[0:3], 0
	s_waitcnt lgkmcnt(2)
	v_mfma_f32_16x16x32_bf16 v[4:7], v[24:27], v[62:65], v[4:7]
	s_waitcnt lgkmcnt(1)
	v_mfma_f32_16x16x32_bf16 v[4:7], v[28:31], v[66:69], v[4:7]
	s_waitcnt lgkmcnt(0)
	v_mfma_f32_16x16x32_bf16 v[34:37], v[34:37], v[70:73], v[4:7]
	s_nop 5
	ds_read_b128 v[4:7], v126 offset:34816
	ds_read_b128 v[8:11], v126 offset:34880
	ds_read_b128 v[12:15], v126 offset:34944
	ds_read_b128 v[16:19], v126 offset:35008
	ds_read_b128 v[20:23], v126 offset:39168
	ds_read_b128 v[24:27], v126 offset:39232
	ds_read_b128 v[106:109], v126 offset:39296
	ds_read_b128 v[110:113], v126 offset:39360
	s_waitcnt lgkmcnt(7)
	v_mfma_f32_16x16x32_bf16 v[4:7], v[4:7], v[0:3], 0
	s_waitcnt lgkmcnt(6)
	v_mfma_f32_16x16x32_bf16 v[4:7], v[8:11], v[62:65], v[4:7]
	s_waitcnt lgkmcnt(5)
	v_mfma_f32_16x16x32_bf16 v[4:7], v[12:15], v[66:69], v[4:7]
	s_waitcnt lgkmcnt(4)
	v_mfma_f32_16x16x32_bf16 v[28:31], v[16:19], v[70:73], v[4:7]
	s_waitcnt lgkmcnt(3)
	v_mfma_f32_16x16x32_bf16 v[4:7], v[20:23], v[0:3], 0
	s_waitcnt lgkmcnt(2)
	v_mfma_f32_16x16x32_bf16 v[4:7], v[24:27], v[62:65], v[4:7]
	s_waitcnt lgkmcnt(1)
	v_mfma_f32_16x16x32_bf16 v[4:7], v[106:109], v[66:69], v[4:7]
	s_waitcnt lgkmcnt(0)
	v_mfma_f32_16x16x32_bf16 v[24:27], v[110:113], v[70:73], v[4:7]
	v_or_b32_e32 v20, 0xb0, v98
	v_mad_u32_u24 v20, v20, s33, v32
	s_nop 3
	ds_read_b128 v[4:7], v126 offset:43520
	ds_read_b128 v[8:11], v126 offset:43584
	ds_read_b128 v[12:15], v126 offset:43648
	ds_read_b128 v[16:19], v126 offset:43712
	ds_read_b128 v[106:109], v20
	ds_read_b128 v[110:113], v20 offset:64
	ds_read_b128 v[114:117], v20 offset:128
	ds_read_b128 v[118:121], v20 offset:192
	s_waitcnt lgkmcnt(7)
	v_mfma_f32_16x16x32_bf16 v[4:7], v[4:7], v[0:3], 0
	s_waitcnt lgkmcnt(6)
	v_mfma_f32_16x16x32_bf16 v[4:7], v[8:11], v[62:65], v[4:7]
	s_waitcnt lgkmcnt(5)
	v_mfma_f32_16x16x32_bf16 v[4:7], v[12:15], v[66:69], v[4:7]
	s_waitcnt lgkmcnt(4)
	v_mfma_f32_16x16x32_bf16 v[20:23], v[16:19], v[70:73], v[4:7]
	s_waitcnt lgkmcnt(3)
	v_mfma_f32_16x16x32_bf16 v[4:7], v[106:109], v[0:3], 0
	s_waitcnt lgkmcnt(2)
	v_mfma_f32_16x16x32_bf16 v[4:7], v[110:113], v[62:65], v[4:7]
	s_waitcnt lgkmcnt(1)
	v_mfma_f32_16x16x32_bf16 v[4:7], v[114:117], v[66:69], v[4:7]
	s_waitcnt lgkmcnt(0)
	v_mfma_f32_16x16x32_bf16 v[16:19], v[118:121], v[70:73], v[4:7]
	s_nop 5
	ds_read_b128 v[4:7], v126 offset:52224
	ds_read_b128 v[8:11], v126 offset:52288
	ds_read_b128 v[12:15], v126 offset:52352
	ds_read_b128 v[106:109], v126 offset:52416
	ds_read_b128 v[110:113], v126 offset:56576
	ds_read_b128 v[114:117], v126 offset:56640
	ds_read_b128 v[118:121], v126 offset:56704
	ds_read_b128 v[122:125], v126 offset:56768
	s_waitcnt lgkmcnt(7)
	v_mfma_f32_16x16x32_bf16 v[4:7], v[4:7], v[0:3], 0
	s_waitcnt lgkmcnt(6)
	v_mfma_f32_16x16x32_bf16 v[4:7], v[8:11], v[62:65], v[4:7]
	s_waitcnt lgkmcnt(5)
	v_mfma_f32_16x16x32_bf16 v[4:7], v[12:15], v[66:69], v[4:7]
	s_waitcnt lgkmcnt(4)
	v_mfma_f32_16x16x32_bf16 v[12:15], v[106:109], v[70:73], v[4:7]
	s_waitcnt lgkmcnt(3)
	v_mfma_f32_16x16x32_bf16 v[4:7], v[110:113], v[0:3], 0
	s_waitcnt lgkmcnt(2)
	v_mfma_f32_16x16x32_bf16 v[4:7], v[114:117], v[62:65], v[4:7]
	s_waitcnt lgkmcnt(1)
	v_mfma_f32_16x16x32_bf16 v[4:7], v[118:121], v[66:69], v[4:7]
	s_waitcnt lgkmcnt(0)
	v_mfma_f32_16x16x32_bf16 v[8:11], v[122:125], v[70:73], v[4:7]
	v_or_b32_e32 v118, 0xf0, v98
	v_mad_u32_u24 v32, v118, s33, v32
	s_nop 3
	ds_read_b128 v[4:7], v126 offset:60928
	ds_read_b128 v[106:109], v126 offset:60992
	ds_read_b128 v[110:113], v126 offset:61056
	ds_read_b128 v[114:117], v126 offset:61120
	ds_read_b128 v[118:121], v32
	ds_read_b128 v[122:125], v32 offset:64
	ds_read_b128 v[126:129], v32 offset:128
	ds_read_b128 v[130:133], v32 offset:192
	s_waitcnt lgkmcnt(7)
	v_mfma_f32_16x16x32_bf16 v[4:7], v[4:7], v[0:3], 0
	s_waitcnt lgkmcnt(3)
	v_mfma_f32_16x16x32_bf16 v[0:3], v[118:121], v[0:3], 0
	v_mfma_f32_16x16x32_bf16 v[4:7], v[106:109], v[62:65], v[4:7]
	s_waitcnt lgkmcnt(2)
	v_mfma_f32_16x16x32_bf16 v[0:3], v[122:125], v[62:65], v[0:3]
	v_mfma_f32_16x16x32_bf16 v[4:7], v[110:113], v[66:69], v[4:7]
	s_waitcnt lgkmcnt(1)
	v_mfma_f32_16x16x32_bf16 v[0:3], v[126:129], v[66:69], v[0:3]
	v_mfma_f32_16x16x32_bf16 v[4:7], v[114:117], v[70:73], v[4:7]
	s_waitcnt lgkmcnt(0)
	v_mfma_f32_16x16x32_bf16 v[0:3], v[130:133], v[70:73], v[0:3]
	v_max_f32_e32 v32, v75, v75
	v_max_f32_e32 v62, v74, v74
	v_max_f32_e32 v32, v62, v32
	v_max_f32_e32 v62, v77, v77
	v_max_f32_e32 v63, v76, v76
	v_max_f32_e32 v62, v63, v62
	s_mov_b32 s8, 0xff61b1e6
	v_max3_f32 v32, v32, v62, s8
	v_max_f32_e32 v62, v59, v59
	v_max_f32_e32 v63, v58, v58
	v_max_f32_e32 v62, v63, v62
	v_max_f32_e32 v63, v61, v61
	v_max_f32_e32 v64, v60, v60
	v_max_f32_e32 v63, v64, v63
	v_max3_f32 v32, v62, v63, v32
	v_max_f32_e32 v62, v55, v55
	v_max_f32_e32 v63, v54, v54
	v_max_f32_e32 v62, v63, v62
	v_max_f32_e32 v63, v57, v57
	v_max_f32_e32 v64, v56, v56
	v_max_f32_e32 v63, v64, v63
	v_max3_f32 v32, v62, v63, v32
	v_max_f32_e32 v62, v51, v51
	v_max_f32_e32 v63, v50, v50
	v_max_f32_e32 v62, v63, v62
	v_max_f32_e32 v63, v53, v53
	v_max_f32_e32 v64, v52, v52
	v_max_f32_e32 v63, v64, v63
	v_max3_f32 v32, v62, v63, v32
	v_max_f32_e32 v62, v47, v47
	v_max_f32_e32 v63, v46, v46
	v_max_f32_e32 v62, v63, v62
	v_max_f32_e32 v63, v49, v49
	v_max_f32_e32 v64, v48, v48
	v_max_f32_e32 v63, v64, v63
	v_max3_f32 v32, v62, v63, v32
	v_max_f32_e32 v62, v43, v43
	v_max_f32_e32 v63, v42, v42
	v_max_f32_e32 v62, v63, v62
	v_max_f32_e32 v63, v45, v45
	v_max_f32_e32 v64, v44, v44
	v_max_f32_e32 v63, v64, v63
	v_max3_f32 v32, v62, v63, v32
	v_max_f32_e32 v62, v39, v39
	v_max_f32_e32 v63, v38, v38
	v_max_f32_e32 v62, v63, v62
	v_max_f32_e32 v63, v41, v41
	v_max_f32_e32 v64, v40, v40
	v_max_f32_e32 v63, v64, v63
	v_max3_f32 v32, v62, v63, v32
	v_max_f32_e32 v62, v35, v35
	v_max_f32_e32 v63, v34, v34
	v_max_f32_e32 v62, v63, v62
	v_max_f32_e32 v63, v37, v37
	v_max_f32_e32 v64, v36, v36
	v_max_f32_e32 v63, v64, v63
	v_max3_f32 v32, v62, v63, v32
	v_max_f32_e32 v62, v29, v29
	v_max_f32_e32 v63, v28, v28
	v_max_f32_e32 v62, v63, v62
	v_max_f32_e32 v63, v31, v31
	v_max_f32_e32 v64, v30, v30
	v_max_f32_e32 v63, v64, v63
	v_max3_f32 v32, v62, v63, v32
	v_max_f32_e32 v62, v25, v25
	v_max_f32_e32 v63, v24, v24
	v_max_f32_e32 v62, v63, v62
	v_max_f32_e32 v63, v27, v27
	v_max_f32_e32 v64, v26, v26
	v_max_f32_e32 v63, v64, v63
	v_max3_f32 v32, v62, v63, v32
	v_max_f32_e32 v62, v21, v21
	v_max_f32_e32 v63, v20, v20
	v_max_f32_e32 v62, v63, v62
	v_max_f32_e32 v63, v23, v23
	v_max_f32_e32 v64, v22, v22
	v_max_f32_e32 v63, v64, v63
	v_max3_f32 v32, v62, v63, v32
	v_max_f32_e32 v62, v17, v17
	v_max_f32_e32 v63, v16, v16
	v_max_f32_e32 v62, v63, v62
	v_max_f32_e32 v63, v19, v19
	v_max_f32_e32 v64, v18, v18
	v_max_f32_e32 v63, v64, v63
	v_max3_f32 v32, v62, v63, v32
	v_max_f32_e32 v62, v13, v13
	v_max_f32_e32 v63, v12, v12
	v_max_f32_e32 v62, v63, v62
	v_max_f32_e32 v63, v15, v15
	v_max_f32_e32 v64, v14, v14
	v_max_f32_e32 v63, v64, v63
	v_max3_f32 v32, v62, v63, v32
	v_max_f32_e32 v62, v9, v9
	v_max_f32_e32 v63, v8, v8
	v_max_f32_e32 v62, v63, v62
	v_max_f32_e32 v63, v11, v11
	v_max_f32_e32 v64, v10, v10
	v_max_f32_e32 v63, v64, v63
	v_max3_f32 v32, v62, v63, v32
	v_max_f32_e32 v62, v5, v5
	v_max_f32_e32 v63, v4, v4
	v_max_f32_e32 v62, v63, v62
	v_max_f32_e32 v63, v7, v7
	v_max_f32_e32 v64, v6, v6
	v_max_f32_e32 v63, v64, v63
	v_max3_f32 v32, v62, v63, v32
	v_max_f32_e32 v62, v1, v1
	v_max_f32_e32 v63, v0, v0
	v_max_f32_e32 v62, v63, v62
	v_max_f32_e32 v63, v3, v3
	v_max_f32_e32 v64, v2, v2
	v_max_f32_e32 v63, v64, v63
	v_max3_f32 v32, v62, v63, v32
	ds_bpermute_b32 v62, v100, v32
	s_waitcnt lgkmcnt(0)
	v_max_f32_e32 v62, v62, v62
	v_max_f32_e32 v32, v32, v62
	ds_bpermute_b32 v62, v101, v32
	s_waitcnt lgkmcnt(0)
	v_max_f32_e32 v62, v62, v62
	v_max_f32_e32 v66, v32, v62
	v_sub_f32_e32 v32, v74, v66
	v_exp_f32_e32 v62, v32
	v_sub_f32_e32 v63, v75, v66
	v_exp_f32_e32 v63, v63
	v_sub_f32_e32 v64, v76, v66
	v_exp_f32_e32 v64, v64
	v_sub_f32_e32 v65, v77, v66
	v_exp_f32_e32 v65, v65
	v_sub_f32_e32 v58, v58, v66
	v_add_f32_e32 v32, 0, v62
	v_exp_f32_e32 v67, v58
	v_sub_f32_e32 v58, v59, v66
	v_add_f32_e32 v32, v63, v32
	v_exp_f32_e32 v68, v58
	v_sub_f32_e32 v58, v60, v66
	v_add_f32_e32 v32, v64, v32
	v_exp_f32_e32 v60, v58
	v_sub_f32_e32 v58, v61, v66
	v_add_f32_e32 v32, v65, v32
	v_exp_f32_e32 v61, v58
	v_sub_f32_e32 v54, v54, v66
	v_add_f32_e32 v32, v67, v32
	v_exp_f32_e32 v54, v54
	v_sub_f32_e32 v55, v55, v66
	v_add_f32_e32 v32, v68, v32
	v_exp_f32_e32 v55, v55
	v_sub_f32_e32 v56, v56, v66
	v_add_f32_e32 v32, v60, v32
	v_exp_f32_e32 v56, v56
	v_sub_f32_e32 v57, v57, v66
	v_add_f32_e32 v32, v61, v32
	v_exp_f32_e32 v57, v57
	v_sub_f32_e32 v50, v50, v66
	v_add_f32_e32 v32, v54, v32
	v_exp_f32_e32 v58, v50
	v_sub_f32_e32 v50, v51, v66
	v_add_f32_e32 v32, v55, v32
	v_exp_f32_e32 v59, v50
	v_sub_f32_e32 v50, v52, v66
	v_add_f32_e32 v32, v56, v32
	v_exp_f32_e32 v52, v50
	v_sub_f32_e32 v50, v53, v66
	v_add_f32_e32 v32, v57, v32
	v_exp_f32_e32 v53, v50
	v_sub_f32_e32 v46, v46, v66
	v_add_f32_e32 v32, v58, v32
	v_exp_f32_e32 v46, v46
	v_sub_f32_e32 v47, v47, v66
	v_add_f32_e32 v32, v59, v32
	v_exp_f32_e32 v47, v47
	v_sub_f32_e32 v48, v48, v66
	v_add_f32_e32 v32, v52, v32
	v_exp_f32_e32 v48, v48
	v_sub_f32_e32 v49, v49, v66
	v_add_f32_e32 v32, v53, v32
	v_exp_f32_e32 v49, v49
	v_sub_f32_e32 v42, v42, v66
	v_add_f32_e32 v32, v46, v32
	v_exp_f32_e32 v50, v42
	v_sub_f32_e32 v42, v43, v66
	v_add_f32_e32 v32, v47, v32
	v_exp_f32_e32 v51, v42
	v_sub_f32_e32 v42, v44, v66
	v_add_f32_e32 v32, v48, v32
	v_exp_f32_e32 v44, v42
	v_sub_f32_e32 v42, v45, v66
	v_add_f32_e32 v32, v49, v32
	v_exp_f32_e32 v45, v42
	v_sub_f32_e32 v38, v38, v66
	v_add_f32_e32 v32, v50, v32
	v_exp_f32_e32 v38, v38
	v_sub_f32_e32 v39, v39, v66
	v_add_f32_e32 v32, v51, v32
	v_exp_f32_e32 v39, v39
	v_sub_f32_e32 v40, v40, v66
	v_add_f32_e32 v32, v44, v32
	v_exp_f32_e32 v40, v40
	v_sub_f32_e32 v41, v41, v66
	v_add_f32_e32 v32, v45, v32
	v_exp_f32_e32 v41, v41
	v_sub_f32_e32 v34, v34, v66
	v_add_f32_e32 v32, v38, v32
	v_exp_f32_e32 v42, v34
	v_sub_f32_e32 v34, v35, v66
	v_add_f32_e32 v32, v39, v32
	v_exp_f32_e32 v43, v34
	v_sub_f32_e32 v34, v36, v66
	v_add_f32_e32 v32, v40, v32
	v_exp_f32_e32 v36, v34
	v_sub_f32_e32 v34, v37, v66
	v_add_f32_e32 v32, v41, v32
	v_exp_f32_e32 v37, v34
	v_sub_f32_e32 v28, v28, v66
	v_add_f32_e32 v32, v42, v32
	v_exp_f32_e32 v28, v28
	v_sub_f32_e32 v29, v29, v66
	v_add_f32_e32 v32, v43, v32
	v_exp_f32_e32 v29, v29
	v_sub_f32_e32 v30, v30, v66
	v_add_f32_e32 v32, v36, v32
	v_exp_f32_e32 v30, v30
	v_sub_f32_e32 v31, v31, v66
	v_add_f32_e32 v32, v37, v32
	v_exp_f32_e32 v31, v31
	v_add_f32_e32 v32, v28, v32
	v_add_f32_e32 v32, v29, v32
	v_add_f32_e32 v32, v30, v32
	v_sub_f32_e32 v24, v24, v66
	v_add_f32_e32 v34, v31, v32
	v_exp_f32_e32 v32, v24
	v_sub_f32_e32 v25, v25, v66
	v_sub_f32_e32 v20, v20, v66
	v_exp_f32_e32 v20, v20
	v_add_f32_e32 v24, v32, v34
	v_exp_f32_e32 v34, v25
	v_sub_f32_e32 v25, v26, v66
	v_exp_f32_e32 v35, v25
	v_sub_f32_e32 v25, v27, v66
	v_exp_f32_e32 v27, v25
	v_sub_f32_e32 v21, v21, v66
	v_add_f32_e32 v24, v34, v24
	v_exp_f32_e32 v21, v21
	v_sub_f32_e32 v22, v22, v66
	v_add_f32_e32 v24, v35, v24
	v_exp_f32_e32 v22, v22
	v_sub_f32_e32 v23, v23, v66
	v_add_f32_e32 v24, v27, v24
	v_exp_f32_e32 v23, v23
	v_add_f32_e32 v24, v20, v24
	v_add_f32_e32 v24, v21, v24
	v_add_f32_e32 v24, v22, v24
	v_sub_f32_e32 v16, v16, v66
	v_add_f32_e32 v25, v23, v24
	v_exp_f32_e32 v24, v16
	v_sub_f32_e32 v17, v17, v66
	v_sub_f32_e32 v12, v12, v66
	v_exp_f32_e32 v12, v12
	v_add_f32_e32 v16, v24, v25
	v_exp_f32_e32 v25, v17
	v_sub_f32_e32 v17, v18, v66
	v_exp_f32_e32 v26, v17
	v_sub_f32_e32 v17, v19, v66
	v_exp_f32_e32 v19, v17
	v_sub_f32_e32 v13, v13, v66
	v_add_f32_e32 v16, v25, v16
	v_exp_f32_e32 v13, v13
	v_sub_f32_e32 v14, v14, v66
	v_add_f32_e32 v16, v26, v16
	v_exp_f32_e32 v14, v14
	v_sub_f32_e32 v15, v15, v66
	v_add_f32_e32 v16, v19, v16
	v_exp_f32_e32 v15, v15
	v_add_f32_e32 v16, v12, v16
	v_add_f32_e32 v16, v13, v16
	v_add_f32_e32 v16, v14, v16
	v_sub_f32_e32 v8, v8, v66
	v_add_f32_e32 v17, v15, v16
	v_exp_f32_e32 v16, v8
	v_sub_f32_e32 v9, v9, v66
	v_sub_f32_e32 v4, v4, v66
	v_exp_f32_e32 v4, v4
	v_add_f32_e32 v8, v16, v17
	v_exp_f32_e32 v17, v9
	v_sub_f32_e32 v9, v10, v66
	v_exp_f32_e32 v18, v9
	v_sub_f32_e32 v9, v11, v66
	v_exp_f32_e32 v11, v9
	v_sub_f32_e32 v5, v5, v66
	v_add_f32_e32 v8, v17, v8
	v_exp_f32_e32 v5, v5
	v_sub_f32_e32 v6, v6, v66
	v_add_f32_e32 v8, v18, v8
	v_exp_f32_e32 v6, v6
	v_sub_f32_e32 v7, v7, v66
	v_add_f32_e32 v8, v11, v8
	v_exp_f32_e32 v7, v7
	v_add_f32_e32 v8, v4, v8
	v_add_f32_e32 v8, v5, v8
	v_add_f32_e32 v8, v6, v8
	v_sub_f32_e32 v0, v0, v66
	v_add_f32_e32 v9, v7, v8
	v_exp_f32_e32 v8, v0
	v_sub_f32_e32 v1, v1, v66
	v_cvt_pk_bf16_f32 v62, v62, v63
	v_cvt_pk_bf16_f32 v63, v64, v65
	v_add_f32_e32 v0, v8, v9
	v_exp_f32_e32 v9, v1
	v_sub_f32_e32 v1, v2, v66
	v_exp_f32_e32 v10, v1
	v_sub_f32_e32 v1, v3, v66
	v_lshlrev_b32_e32 v66, 3, v98
	v_mul_u32_u24_e32 v2, 0x120, v105
	v_and_b32_e32 v66, 24, v66
	v_add3_u32 v2, s27, v2, v66
	v_cvt_pk_bf16_f32 v64, v67, v68
	ds_read_b64_tr_b16 v[68:69], v2 offset:4608
	ds_read_b64_tr_b16 v[66:67], v2
	ds_read_b64_tr_b16 v[70:71], v2 offset:32
	ds_read_b64_tr_b16 v[72:73], v2 offset:4640
	ds_read_b64_tr_b16 v[74:75], v2 offset:64
	ds_read_b64_tr_b16 v[76:77], v2 offset:4672
	ds_read_b64_tr_b16 v[106:107], v2 offset:96
	ds_read_b64_tr_b16 v[108:109], v2 offset:4704
	ds_read_b64_tr_b16 v[110:111], v2 offset:128
	ds_read_b64_tr_b16 v[112:113], v2 offset:4736
	ds_read_b64_tr_b16 v[114:115], v2 offset:160
	ds_read_b64_tr_b16 v[116:117], v2 offset:4768
	ds_read_b64_tr_b16 v[118:119], v2 offset:192
	ds_read_b64_tr_b16 v[120:121], v2 offset:4800
	ds_read_b64_tr_b16 v[122:123], v2 offset:224
	ds_read_b64_tr_b16 v[124:125], v2 offset:4832
	v_exp_f32_e32 v3, v1
	v_add_f32_e32 v0, v9, v0
	v_add_f32_e32 v0, v10, v0
	v_cvt_pk_bf16_f32 v65, v60, v61
	v_add_f32_e32 v0, v3, v0
	ds_bpermute_b32 v1, v100, v0
	s_waitcnt lgkmcnt(0)
	v_add_f32_e32 v0, v0, v1
	ds_bpermute_b32 v1, v101, v0
	v_mfma_f32_16x16x32_bf16 v[66:69], v[66:69], v[62:65], 0
	v_mfma_f32_16x16x32_bf16 v[70:73], v[70:73], v[62:65], 0
	v_mfma_f32_16x16x32_bf16 v[74:77], v[74:77], v[62:65], 0
	v_mfma_f32_16x16x32_bf16 v[106:109], v[106:109], v[62:65], 0
	v_mfma_f32_16x16x32_bf16 v[110:113], v[110:113], v[62:65], 0
	v_mfma_f32_16x16x32_bf16 v[114:117], v[114:117], v[62:65], 0
	v_mfma_f32_16x16x32_bf16 v[118:121], v[118:121], v[62:65], 0
	v_mfma_f32_16x16x32_bf16 v[60:63], v[122:125], v[62:65], 0
	ds_read_b64_tr_b16 v[124:125], v2 offset:13824
	ds_read_b64_tr_b16 v[122:123], v2 offset:9216
	ds_read_b64_tr_b16 v[126:127], v2 offset:9248
	ds_read_b64_tr_b16 v[128:129], v2 offset:13856
	ds_read_b64_tr_b16 v[130:131], v2 offset:9280
	ds_read_b64_tr_b16 v[132:133], v2 offset:13888
	ds_read_b64_tr_b16 v[134:135], v2 offset:9312
	ds_read_b64_tr_b16 v[136:137], v2 offset:13920
	ds_read_b64_tr_b16 v[138:139], v2 offset:9344
	ds_read_b64_tr_b16 v[140:141], v2 offset:13952
	ds_read_b64_tr_b16 v[142:143], v2 offset:9376
	ds_read_b64_tr_b16 v[144:145], v2 offset:13984
	ds_read_b64_tr_b16 v[146:147], v2 offset:9408
	ds_read_b64_tr_b16 v[148:149], v2 offset:14016
	ds_read_b64_tr_b16 v[150:151], v2 offset:9440
	ds_read_b64_tr_b16 v[152:153], v2 offset:14048
	v_cvt_pk_bf16_f32 v54, v54, v55
	v_cvt_pk_bf16_f32 v55, v56, v57
	v_cvt_pk_bf16_f32 v56, v58, v59
	v_cvt_pk_bf16_f32 v57, v52, v53
	s_waitcnt lgkmcnt(14)
	v_mfma_f32_16x16x32_bf16 v[64:67], v[122:125], v[54:57], v[66:69]
	s_waitcnt lgkmcnt(12)
	v_mfma_f32_16x16x32_bf16 v[68:71], v[126:129], v[54:57], v[70:73]
	s_waitcnt lgkmcnt(10)
	v_mfma_f32_16x16x32_bf16 v[72:75], v[130:133], v[54:57], v[74:77]
	s_waitcnt lgkmcnt(8)
	v_mfma_f32_16x16x32_bf16 v[106:109], v[134:137], v[54:57], v[106:109]
	s_waitcnt lgkmcnt(6)
	v_mfma_f32_16x16x32_bf16 v[110:113], v[138:141], v[54:57], v[110:113]
	s_waitcnt lgkmcnt(4)
	v_mfma_f32_16x16x32_bf16 v[114:117], v[142:145], v[54:57], v[114:117]
	s_waitcnt lgkmcnt(2)
	v_mfma_f32_16x16x32_bf16 v[118:121], v[146:149], v[54:57], v[118:121]
	s_waitcnt lgkmcnt(0)
	v_mfma_f32_16x16x32_bf16 v[52:55], v[150:153], v[54:57], v[60:63]
	ds_read_b64_tr_b16 v[58:59], v2 offset:23040
	ds_read_b64_tr_b16 v[56:57], v2 offset:18432
	s_nop 0
	ds_read_b64_tr_b16 v[60:61], v2 offset:18464
	ds_read_b64_tr_b16 v[62:63], v2 offset:23072
	ds_read_b64_tr_b16 v[122:123], v2 offset:18496
	ds_read_b64_tr_b16 v[124:125], v2 offset:23104
	ds_read_b64_tr_b16 v[126:127], v2 offset:18528
	ds_read_b64_tr_b16 v[128:129], v2 offset:23136
	ds_read_b64_tr_b16 v[130:131], v2 offset:18560
	ds_read_b64_tr_b16 v[132:133], v2 offset:23168
	ds_read_b64_tr_b16 v[134:135], v2 offset:18592
	ds_read_b64_tr_b16 v[136:137], v2 offset:23200
	ds_read_b64_tr_b16 v[138:139], v2 offset:18624
	ds_read_b64_tr_b16 v[140:141], v2 offset:23232
	ds_read_b64_tr_b16 v[142:143], v2 offset:18656
	ds_read_b64_tr_b16 v[144:145], v2 offset:23264
	v_cvt_pk_bf16_f32 v46, v46, v47
	v_cvt_pk_bf16_f32 v47, v48, v49
	v_cvt_pk_bf16_f32 v48, v50, v51
	v_cvt_pk_bf16_f32 v49, v44, v45
	s_waitcnt lgkmcnt(14)
	v_mfma_f32_16x16x32_bf16 v[56:59], v[56:59], v[46:49], v[64:67]
	s_waitcnt lgkmcnt(12)
	v_mfma_f32_16x16x32_bf16 v[60:63], v[60:63], v[46:49], v[68:71]
	s_waitcnt lgkmcnt(10)
	v_mfma_f32_16x16x32_bf16 v[64:67], v[122:125], v[46:49], v[72:75]
	s_waitcnt lgkmcnt(8)
	v_mfma_f32_16x16x32_bf16 v[68:71], v[126:129], v[46:49], v[106:109]
	s_waitcnt lgkmcnt(6)
	v_mfma_f32_16x16x32_bf16 v[72:75], v[130:133], v[46:49], v[110:113]
	s_waitcnt lgkmcnt(4)
	v_mfma_f32_16x16x32_bf16 v[106:109], v[134:137], v[46:49], v[114:117]
	s_waitcnt lgkmcnt(2)
	v_mfma_f32_16x16x32_bf16 v[110:113], v[138:141], v[46:49], v[118:121]
	s_waitcnt lgkmcnt(0)
	v_mfma_f32_16x16x32_bf16 v[44:47], v[142:145], v[46:49], v[52:55]
	ds_read_b64_tr_b16 v[50:51], v2 offset:32256
	ds_read_b64_tr_b16 v[48:49], v2 offset:27648
	s_nop 0
	ds_read_b64_tr_b16 v[52:53], v2 offset:27680
	ds_read_b64_tr_b16 v[54:55], v2 offset:32288
	ds_read_b64_tr_b16 v[114:115], v2 offset:27712
	ds_read_b64_tr_b16 v[116:117], v2 offset:32320
	ds_read_b64_tr_b16 v[118:119], v2 offset:27744
	ds_read_b64_tr_b16 v[120:121], v2 offset:32352
	ds_read_b64_tr_b16 v[122:123], v2 offset:27776
	ds_read_b64_tr_b16 v[124:125], v2 offset:32384
	ds_read_b64_tr_b16 v[126:127], v2 offset:27808
	ds_read_b64_tr_b16 v[128:129], v2 offset:32416
	ds_read_b64_tr_b16 v[130:131], v2 offset:27840
	ds_read_b64_tr_b16 v[132:133], v2 offset:32448
	ds_read_b64_tr_b16 v[134:135], v2 offset:27872
	ds_read_b64_tr_b16 v[136:137], v2 offset:32480
	v_cvt_pk_bf16_f32 v38, v38, v39
	v_cvt_pk_bf16_f32 v39, v40, v41
	v_cvt_pk_bf16_f32 v40, v42, v43
	v_cvt_pk_bf16_f32 v41, v36, v37
	s_waitcnt lgkmcnt(14)
	v_mfma_f32_16x16x32_bf16 v[48:51], v[48:51], v[38:41], v[56:59]
	s_waitcnt lgkmcnt(12)
	v_mfma_f32_16x16x32_bf16 v[52:55], v[52:55], v[38:41], v[60:63]
	s_waitcnt lgkmcnt(10)
	v_mfma_f32_16x16x32_bf16 v[56:59], v[114:117], v[38:41], v[64:67]
	s_waitcnt lgkmcnt(8)
	v_mfma_f32_16x16x32_bf16 v[60:63], v[118:121], v[38:41], v[68:71]
	s_waitcnt lgkmcnt(6)
	v_mfma_f32_16x16x32_bf16 v[64:67], v[122:125], v[38:41], v[72:75]
	s_waitcnt lgkmcnt(4)
	v_mfma_f32_16x16x32_bf16 v[68:71], v[126:129], v[38:41], v[106:109]
	s_waitcnt lgkmcnt(2)
	v_mfma_f32_16x16x32_bf16 v[72:75], v[130:133], v[38:41], v[110:113]
	s_waitcnt lgkmcnt(0)
	v_mfma_f32_16x16x32_bf16 v[36:39], v[134:137], v[38:41], v[44:47]
	ds_read_b64_tr_b16 v[42:43], v2 offset:41472
	ds_read_b64_tr_b16 v[40:41], v2 offset:36864
	s_nop 0
	ds_read_b64_tr_b16 v[44:45], v2 offset:36896
	ds_read_b64_tr_b16 v[46:47], v2 offset:41504
	ds_read_b64_tr_b16 v[106:107], v2 offset:36928
	ds_read_b64_tr_b16 v[108:109], v2 offset:41536
	ds_read_b64_tr_b16 v[110:111], v2 offset:36960
	ds_read_b64_tr_b16 v[112:113], v2 offset:41568
	ds_read_b64_tr_b16 v[114:115], v2 offset:36992
	ds_read_b64_tr_b16 v[116:117], v2 offset:41600
	ds_read_b64_tr_b16 v[118:119], v2 offset:37024
	ds_read_b64_tr_b16 v[120:121], v2 offset:41632
	ds_read_b64_tr_b16 v[122:123], v2 offset:37056
	ds_read_b64_tr_b16 v[124:125], v2 offset:41664
	ds_read_b64_tr_b16 v[126:127], v2 offset:37088
	ds_read_b64_tr_b16 v[128:129], v2 offset:41696
	v_cvt_pk_bf16_f32 v28, v28, v29
	v_cvt_pk_bf16_f32 v29, v30, v31
	v_cvt_pk_bf16_f32 v30, v32, v34
	v_cvt_pk_bf16_f32 v31, v35, v27
	s_waitcnt lgkmcnt(14)
	v_mfma_f32_16x16x32_bf16 v[40:43], v[40:43], v[28:31], v[48:51]
	s_waitcnt lgkmcnt(12)
	v_mfma_f32_16x16x32_bf16 v[44:47], v[44:47], v[28:31], v[52:55]
	s_waitcnt lgkmcnt(10)
	v_mfma_f32_16x16x32_bf16 v[48:51], v[106:109], v[28:31], v[56:59]
	s_waitcnt lgkmcnt(8)
	v_mfma_f32_16x16x32_bf16 v[52:55], v[110:113], v[28:31], v[60:63]
	s_waitcnt lgkmcnt(6)
	v_mfma_f32_16x16x32_bf16 v[56:59], v[114:117], v[28:31], v[64:67]
	s_waitcnt lgkmcnt(4)
	v_mfma_f32_16x16x32_bf16 v[60:63], v[118:121], v[28:31], v[68:71]
	s_waitcnt lgkmcnt(2)
	v_mfma_f32_16x16x32_bf16 v[64:67], v[122:125], v[28:31], v[72:75]
	s_waitcnt lgkmcnt(0)
	v_mfma_f32_16x16x32_bf16 v[28:31], v[126:129], v[28:31], v[36:39]
	v_cvt_pk_bf16_f32 v20, v20, v21
	v_cvt_pk_bf16_f32 v21, v22, v23
	v_cvt_pk_bf16_f32 v22, v24, v25
	v_cvt_pk_bf16_f32 v23, v26, v19
	ds_read_b64_tr_b16 v[26:27], v2 offset:50688
	ds_read_b64_tr_b16 v[24:25], v2 offset:46080
	ds_read_b64_tr_b16 v[34:35], v2 offset:46112
	ds_read_b64_tr_b16 v[36:37], v2 offset:50720
	ds_read_b64_tr_b16 v[68:69], v2 offset:46144
	ds_read_b64_tr_b16 v[70:71], v2 offset:50752
	ds_read_b64_tr_b16 v[72:73], v2 offset:46176
	ds_read_b64_tr_b16 v[74:75], v2 offset:50784
	ds_read_b64_tr_b16 v[106:107], v2 offset:46208
	ds_read_b64_tr_b16 v[108:109], v2 offset:50816
	ds_read_b64_tr_b16 v[110:111], v2 offset:46240
	ds_read_b64_tr_b16 v[112:113], v2 offset:50848
	ds_read_b64_tr_b16 v[114:115], v2 offset:46272
	ds_read_b64_tr_b16 v[116:117], v2 offset:50880
	ds_read_b64_tr_b16 v[118:119], v2 offset:46304
	ds_read_b64_tr_b16 v[120:121], v2 offset:50912
	s_waitcnt lgkmcnt(14)
	v_mfma_f32_16x16x32_bf16 v[24:27], v[24:27], v[20:23], v[40:43]
	s_waitcnt lgkmcnt(12)
	v_mfma_f32_16x16x32_bf16 v[34:37], v[34:37], v[20:23], v[44:47]
	s_waitcnt lgkmcnt(10)
	v_mfma_f32_16x16x32_bf16 v[38:41], v[68:71], v[20:23], v[48:51]
	s_waitcnt lgkmcnt(8)
	v_mfma_f32_16x16x32_bf16 v[42:45], v[72:75], v[20:23], v[52:55]
	s_waitcnt lgkmcnt(6)
	v_mfma_f32_16x16x32_bf16 v[46:49], v[106:109], v[20:23], v[56:59]
	s_waitcnt lgkmcnt(4)
	v_mfma_f32_16x16x32_bf16 v[50:53], v[110:113], v[20:23], v[60:63]
	s_waitcnt lgkmcnt(2)
	v_mfma_f32_16x16x32_bf16 v[54:57], v[114:117], v[20:23], v[64:67]
	s_waitcnt lgkmcnt(0)
	v_mfma_f32_16x16x32_bf16 v[20:23], v[118:121], v[20:23], v[28:31]
	v_cvt_pk_bf16_f32 v12, v12, v13
	v_cvt_pk_bf16_f32 v13, v14, v15
	v_cvt_pk_bf16_f32 v14, v16, v17
	v_cvt_pk_bf16_f32 v15, v18, v11
	ds_read_b64_tr_b16 v[18:19], v2 offset:59904
	ds_read_b64_tr_b16 v[16:17], v2 offset:55296
	s_nop 0
	ds_read_b64_tr_b16 v[28:29], v2 offset:55328
	ds_read_b64_tr_b16 v[30:31], v2 offset:59936
	ds_read_b64_tr_b16 v[58:59], v2 offset:55360
	ds_read_b64_tr_b16 v[60:61], v2 offset:59968
	ds_read_b64_tr_b16 v[62:63], v2 offset:55392
	ds_read_b64_tr_b16 v[64:65], v2 offset:60000
	ds_read_b64_tr_b16 v[66:67], v2 offset:55424
	ds_read_b64_tr_b16 v[68:69], v2 offset:60032
	ds_read_b64_tr_b16 v[70:71], v2 offset:55456
	ds_read_b64_tr_b16 v[72:73], v2 offset:60064
	ds_read_b64_tr_b16 v[74:75], v2 offset:55488
	ds_read_b64_tr_b16 v[76:77], v2 offset:60096
	ds_read_b64_tr_b16 v[106:107], v2 offset:55520
	ds_read_b64_tr_b16 v[108:109], v2 offset:60128
	s_waitcnt lgkmcnt(14)
	v_mfma_f32_16x16x32_bf16 v[16:19], v[16:19], v[12:15], v[24:27]
	s_waitcnt lgkmcnt(12)
	v_mfma_f32_16x16x32_bf16 v[24:27], v[28:31], v[12:15], v[34:37]
	s_waitcnt lgkmcnt(10)
	v_mfma_f32_16x16x32_bf16 v[28:31], v[58:61], v[12:15], v[38:41]
	s_waitcnt lgkmcnt(8)
	v_mfma_f32_16x16x32_bf16 v[34:37], v[62:65], v[12:15], v[42:45]
	s_waitcnt lgkmcnt(6)
	v_mfma_f32_16x16x32_bf16 v[38:41], v[66:69], v[12:15], v[46:49]
	s_waitcnt lgkmcnt(4)
	v_mfma_f32_16x16x32_bf16 v[42:45], v[70:73], v[12:15], v[50:53]
	s_waitcnt lgkmcnt(2)
	v_mfma_f32_16x16x32_bf16 v[46:49], v[74:77], v[12:15], v[54:57]
	s_waitcnt lgkmcnt(0)
	v_mfma_f32_16x16x32_bf16 v[12:15], v[106:109], v[12:15], v[20:23]
	v_cvt_pk_bf16_f32 v4, v4, v5
	v_cvt_pk_bf16_f32 v5, v6, v7
	v_cvt_pk_bf16_f32 v7, v10, v3
	v_add_u32_e32 v3, 0x10e00, v2
	v_cvt_pk_bf16_f32 v6, v8, v9
	ds_read_b64_tr_b16 v[10:11], v3
	ds_read_b64_tr_b16 v[8:9], v2 offset:64512
	ds_read_b64_tr_b16 v[20:21], v2 offset:64544
	v_add_u32_e32 v3, 0x10e20, v2
	ds_read_b64_tr_b16 v[22:23], v3
	ds_read_b64_tr_b16 v[50:51], v2 offset:64576
	v_add_u32_e32 v3, 0x10e40, v2
	ds_read_b64_tr_b16 v[52:53], v3
	ds_read_b64_tr_b16 v[54:55], v2 offset:64608
	v_add_u32_e32 v3, 0x10e60, v2
	ds_read_b64_tr_b16 v[56:57], v3
	ds_read_b64_tr_b16 v[58:59], v2 offset:64640
	v_add_u32_e32 v3, 0x10e80, v2
	ds_read_b64_tr_b16 v[60:61], v3
	ds_read_b64_tr_b16 v[62:63], v2 offset:64672
	v_add_u32_e32 v3, 0x10ea0, v2
	ds_read_b64_tr_b16 v[64:65], v3
	ds_read_b64_tr_b16 v[66:67], v2 offset:64704
	v_add_u32_e32 v3, 0x10ec0, v2
	ds_read_b64_tr_b16 v[68:69], v3
	ds_read_b64_tr_b16 v[70:71], v2 offset:64736
	v_add_u32_e32 v2, 0x10ee0, v2
	ds_read_b64_tr_b16 v[72:73], v2
	s_waitcnt lgkmcnt(14)
	v_mfma_f32_16x16x32_bf16 v[8:11], v[8:11], v[4:7], v[16:19]
	s_waitcnt lgkmcnt(12)
	v_mfma_f32_16x16x32_bf16 v[16:19], v[20:23], v[4:7], v[24:27]
	s_waitcnt lgkmcnt(10)
	v_mfma_f32_16x16x32_bf16 v[20:23], v[50:53], v[4:7], v[28:31]
	s_waitcnt lgkmcnt(8)
	v_mfma_f32_16x16x32_bf16 v[24:27], v[54:57], v[4:7], v[34:37]
	s_waitcnt lgkmcnt(6)
	v_mfma_f32_16x16x32_bf16 v[28:31], v[58:61], v[4:7], v[38:41]
	s_waitcnt lgkmcnt(4)
	v_mfma_f32_16x16x32_bf16 v[34:37], v[62:65], v[4:7], v[42:45]
	s_waitcnt lgkmcnt(2)
	v_mfma_f32_16x16x32_bf16 v[38:41], v[66:69], v[4:7], v[46:49]
	s_waitcnt lgkmcnt(0)
	v_mfma_f32_16x16x32_bf16 v[2:5], v[70:73], v[4:7], v[12:15]
	v_add_f32_e32 v0, v0, v1
	v_rcp_f32_e32 v6, v0
	s_waitcnt vmcnt(7)
	v_lshlrev_b32_e32 v0, 16, v96
	v_and_b32_e32 v1, 0xffff0000, v96
	s_mov_b64 s[10:11], 0
	v_mul_f32_e32 v7, v6, v8
	v_mul_f32_e32 v8, v6, v9
	v_mul_f32_e32 v0, v7, v0
	v_mul_f32_e32 v1, v8, v1
	v_cvt_pk_bf16_f32 v0, v0, v1
	v_mul_f32_e32 v1, v6, v10
	v_lshlrev_b32_e32 v7, 16, v97
	v_mul_f32_e32 v1, v1, v7
	v_mul_f32_e32 v7, v6, v11
	v_and_b32_e32 v8, 0xffff0000, v97
	v_mul_f32_e32 v7, v7, v8
	v_cvt_pk_bf16_f32 v1, v1, v7
	global_store_dwordx2 v[94:95], v[0:1], off
	v_mul_f32_e32 v0, v6, v16
	s_waitcnt vmcnt(7)
	v_lshlrev_b32_e32 v1, 16, v92
	v_mul_f32_e32 v0, v0, v1
	v_mul_f32_e32 v1, v6, v17
	v_and_b32_e32 v7, 0xffff0000, v92
	v_mul_f32_e32 v1, v1, v7
	v_cvt_pk_bf16_f32 v0, v0, v1
	v_mul_f32_e32 v1, v6, v18
	v_lshlrev_b32_e32 v7, 16, v93
	v_mul_f32_e32 v1, v1, v7
	v_mul_f32_e32 v7, v6, v19
	v_and_b32_e32 v8, 0xffff0000, v93
	v_mul_f32_e32 v7, v7, v8
	v_cvt_pk_bf16_f32 v1, v1, v7
	global_store_dwordx2 v[78:79], v[0:1], off offset:32
	v_mul_f32_e32 v0, v6, v20
	s_waitcnt vmcnt(7)
	v_lshlrev_b32_e32 v1, 16, v90
	v_mul_f32_e32 v0, v0, v1
	v_mul_f32_e32 v1, v6, v21
	v_and_b32_e32 v7, 0xffff0000, v90
	v_mul_f32_e32 v1, v1, v7
	v_cvt_pk_bf16_f32 v0, v0, v1
	v_mul_f32_e32 v1, v6, v22
	v_lshlrev_b32_e32 v7, 16, v91
	v_mul_f32_e32 v1, v1, v7
	v_mul_f32_e32 v7, v6, v23
	v_and_b32_e32 v8, 0xffff0000, v91
	v_mul_f32_e32 v7, v7, v8
	v_cvt_pk_bf16_f32 v1, v1, v7
	global_store_dwordx2 v[78:79], v[0:1], off offset:64
	v_mul_f32_e32 v0, v6, v24
	s_waitcnt vmcnt(7)
	v_lshlrev_b32_e32 v1, 16, v88
	v_mul_f32_e32 v0, v0, v1
	v_mul_f32_e32 v1, v6, v25
	v_and_b32_e32 v7, 0xffff0000, v88
	v_mul_f32_e32 v1, v1, v7
	v_cvt_pk_bf16_f32 v0, v0, v1
	v_mul_f32_e32 v1, v6, v26
	v_lshlrev_b32_e32 v7, 16, v89
	v_mul_f32_e32 v1, v1, v7
	v_mul_f32_e32 v7, v6, v27
	v_and_b32_e32 v8, 0xffff0000, v89
	v_mul_f32_e32 v7, v7, v8
	v_cvt_pk_bf16_f32 v1, v1, v7
	global_store_dwordx2 v[78:79], v[0:1], off offset:96
	v_mul_f32_e32 v0, v6, v28
	s_waitcnt vmcnt(7)
	v_lshlrev_b32_e32 v1, 16, v86
	v_mul_f32_e32 v0, v0, v1
	v_mul_f32_e32 v1, v6, v29
	v_and_b32_e32 v7, 0xffff0000, v86
	v_mul_f32_e32 v1, v1, v7
	v_cvt_pk_bf16_f32 v0, v0, v1
	v_mul_f32_e32 v1, v6, v30
	v_lshlrev_b32_e32 v7, 16, v87
	v_mul_f32_e32 v1, v1, v7
	v_mul_f32_e32 v7, v6, v31
	v_and_b32_e32 v8, 0xffff0000, v87
	v_mul_f32_e32 v7, v7, v8
	v_cvt_pk_bf16_f32 v1, v1, v7
	global_store_dwordx2 v[78:79], v[0:1], off offset:128
	v_mul_f32_e32 v0, v6, v34
	s_waitcnt vmcnt(7)
	v_lshlrev_b32_e32 v1, 16, v84
	v_mul_f32_e32 v0, v0, v1
	v_mul_f32_e32 v1, v6, v35
	v_and_b32_e32 v7, 0xffff0000, v84
	v_mul_f32_e32 v1, v1, v7
	v_cvt_pk_bf16_f32 v0, v0, v1
	v_mul_f32_e32 v1, v6, v36
	v_lshlrev_b32_e32 v7, 16, v85
	v_mul_f32_e32 v1, v1, v7
	v_mul_f32_e32 v7, v6, v37
	v_and_b32_e32 v8, 0xffff0000, v85
	v_mul_f32_e32 v7, v7, v8
	v_cvt_pk_bf16_f32 v1, v1, v7
	global_store_dwordx2 v[78:79], v[0:1], off offset:160
	v_mul_f32_e32 v0, v6, v38
	s_waitcnt vmcnt(7)
	v_lshlrev_b32_e32 v1, 16, v82
	v_mul_f32_e32 v0, v0, v1
	v_mul_f32_e32 v1, v6, v39
	v_and_b32_e32 v7, 0xffff0000, v82
	v_mul_f32_e32 v1, v1, v7
	v_cvt_pk_bf16_f32 v0, v0, v1
	v_mul_f32_e32 v1, v6, v40
	v_lshlrev_b32_e32 v7, 16, v83
	v_mul_f32_e32 v1, v1, v7
	v_mul_f32_e32 v7, v6, v41
	v_and_b32_e32 v8, 0xffff0000, v83
	v_mul_f32_e32 v7, v7, v8
	v_cvt_pk_bf16_f32 v1, v1, v7
	global_store_dwordx2 v[78:79], v[0:1], off offset:192
	v_mul_f32_e32 v0, v6, v2
	s_waitcnt vmcnt(7)
	v_lshlrev_b32_e32 v1, 16, v80
	v_mul_f32_e32 v0, v0, v1
	v_mul_f32_e32 v1, v6, v3
	v_and_b32_e32 v2, 0xffff0000, v80
	v_mul_f32_e32 v1, v1, v2
	v_cvt_pk_bf16_f32 v0, v0, v1
	v_mul_f32_e32 v1, v6, v4
	v_lshlrev_b32_e32 v2, 16, v81
	v_mul_f32_e32 v1, v1, v2
	v_mul_f32_e32 v2, v6, v5
	v_and_b32_e32 v3, 0xffff0000, v81
	v_mul_f32_e32 v2, v2, v3
	v_cvt_pk_bf16_f32 v1, v1, v2
	global_store_dwordx2 v[78:79], v[0:1], off offset:224
	s_barrier
.LBB0_1276:
	s_andn2_b64 vcc, exec, s[10:11]
	s_cbranch_vccnz .LBB0_1313
	s_lshl_b32 s13, s74, 12
	v_readlane_b32 s8, v252, 59
	s_or_b32 s83, s8, s13
	s_lshl_b32 s28, s12, 1
	v_readlane_b32 s8, v252, 15
	s_add_u32 s8, s8, s28
	v_readlane_b32 s9, v252, 16
	v_lshlrev_b32_e32 v0, 4, v99
	s_addc_u32 s9, s9, 0
	v_readlane_b32 s10, v252, 17
	v_and_b32_e32 v32, 0xf0, v0
	s_add_u32 s10, s10, s28
	v_readlane_b32 s11, v252, 18
	v_lshl_add_u64 v[16:17], s[8:9], 0, v[32:33]
	v_readlane_b32 s8, v252, 60
	s_addc_u32 s11, s11, 0
	v_and_b32_e32 v0, -16, v99
	s_add_i32 s8, s8, s13
	v_lshl_add_u64 v[18:19], s[10:11], 0, v[32:33]
	v_add_u32_e32 v24, s8, v0
	s_movk_i32 s8, 0x80
	v_readlane_b32 s10, v252, 57
	v_cmp_gt_i32_e32 vcc, s8, v104
	v_readlane_b32 s11, v252, 58
	v_mov_b32_e32 v25, s83
	s_and_b64 vcc, s[10:11], vcc
	v_cndmask_b32_e32 v2, v24, v25, vcc
	v_mad_i64_i32 v[0:1], s[8:9], v2, s70, v[16:17]
	v_mad_i64_i32 v[4:5], s[8:9], v2, s70, v[18:19]
	s_movk_i32 s8, 0x60
	s_nop 0
	v_cmp_gt_i32_e32 vcc, s8, v104
	v_add_u32_e32 v8, 0x200, v24
	s_and_b64 vcc, s[10:11], vcc
	v_cndmask_b32_e32 v10, v8, v25, vcc
	v_cmp_gt_i32_e32 vcc, 64, v104
	v_add_u32_e32 v20, 0x400, v24
	s_and_b64 vcc, s[10:11], vcc
	v_cndmask_b32_e32 v22, v20, v25, vcc
	v_mad_i64_i32 v[8:9], s[8:9], v10, s70, v[16:17]
	v_mad_i64_i32 v[12:13], s[8:9], v10, s70, v[18:19]
	v_mad_i64_i32 v[20:21], s[8:9], v22, s70, v[16:17]
	v_cmp_gt_i32_e32 vcc, 32, v104
	s_nop 0
	s_nop 0
	s_nop 0
	v_mad_i64_i32 v[22:23], s[8:9], v22, s70, v[18:19]
	v_add_u32_e32 v20, 0x600, v24
	s_and_b64 vcc, s[10:11], vcc
	v_cndmask_b32_e32 v22, v20, v25, vcc
	v_mad_i64_i32 v[20:21], s[8:9], v22, s70, v[16:17]
	v_cmp_gt_i32_e32 vcc, 0, v104
	v_mad_i64_i32 v[22:23], s[8:9], v22, s70, v[18:19]
	v_add_u32_e32 v20, 0x800, v24
	s_and_b64 vcc, s[10:11], vcc
	v_cndmask_b32_e32 v22, v20, v25, vcc
	v_mad_i64_i32 v[20:21], s[8:9], v22, s70, v[16:17]
	v_mad_i64_i32 v[22:23], s[8:9], v22, s70, v[18:19]
	s_movk_i32 s8, 0xffe0
	s_nop 0
	v_cmp_gt_i32_e32 vcc, s8, v104
	v_add_u32_e32 v20, 0xa00, v24
	s_and_b64 vcc, s[10:11], vcc
	v_cndmask_b32_e32 v22, v20, v25, vcc
	v_mad_i64_i32 v[20:21], s[8:9], v22, s70, v[16:17]
	v_mad_i64_i32 v[22:23], s[8:9], v22, s70, v[18:19]
	s_movk_i32 s8, 0xffc0
	s_nop 0
	v_cmp_gt_i32_e32 vcc, s8, v104
	v_add_u32_e32 v20, 0xc00, v24
	s_and_b64 vcc, s[10:11], vcc
	v_cndmask_b32_e32 v22, v20, v25, vcc
	v_mad_i64_i32 v[20:21], s[8:9], v22, s70, v[16:17]
	v_mad_i64_i32 v[22:23], s[8:9], v22, s70, v[18:19]
	s_movk_i32 s8, 0xffa0
	s_nop 0
	v_cmp_gt_i32_e32 vcc, s8, v104
	v_add_u32_e32 v20, 0xe00, v24
	s_and_b64 vcc, s[10:11], vcc
	v_cndmask_b32_e32 v20, v20, v25, vcc
	v_mad_i64_i32 v[16:17], s[8:9], v20, s70, v[16:17]
	v_mad_i64_i32 v[18:19], s[8:9], v20, s70, v[18:19]
	v_readlane_b32 s8, v252, 19
	s_add_u32 s8, s8, s28
	v_readlane_b32 s9, v252, 20
	s_addc_u32 s9, s9, 0
	s_lshl_b32 s10, s73, 8
	v_lshlrev_b32_e32 v16, 4, v98
	v_and_b32_e32 v16, 0xf0, v16
	s_add_i32 s10, s10, s83
	v_or_b32_e32 v18, s10, v16
	v_mov_b64_e32 v[16:17], s[8:9]
	v_mad_i64_i32 v[16:17], s[8:9], v18, s70, v[16:17]
	v_and_b32_e32 v82, 48, v99
	v_mov_b32_e32 v83, v33
	v_lshl_add_u64 v[28:29], v[16:17], 0, v[82:83]
	s_nop 0
	v_add3_u32 v83, 0, v32, v102
	s_add_i32 s8, s73, -2
	v_add_u32_e32 v82, 0, v82
	s_cmp_gt_u32 s8, -11
	s_cselect_b64 s[44:45], -1, 0
	s_cmp_lt_u32 s8, -10
	v_add3_u32 v0, s27, v32, v103
	v_and_b32_e32 v32, 15, v99
	v_mov_b32_e32 v0, 0
	v_mad_u32_u24 v83, v32, s33, v82
	v_mov_b32_e32 v8, 0
	v_mov_b32_e32 v9, 0
	v_mov_b32_e32 v10, 0
	v_mov_b32_e32 v11, 0
	v_mov_b32_e32 v12, 0
	v_mov_b32_e32 v13, 0
	v_mov_b32_e32 v14, 0
	v_mov_b32_e32 v15, 0
	s_waitcnt lgkmcnt(0)
	s_cselect_b32 s49, 1, 0
	v_mov_b64_e32 v[16:17], v[228:229]
	v_mov_b64_e32 v[18:19], v[230:231]
	v_mov_b64_e32 v[20:21], v[232:233]
	v_mov_b64_e32 v[22:23], v[234:235]
	v_mov_b64_e32 v[24:25], v[236:237]
	v_mov_b64_e32 v[26:27], v[238:239]
	v_mov_b64_e32 v[28:29], v[240:241]
	v_mov_b64_e32 v[30:31], v[242:243]
	s_add_u32 s48, s72, 1
	s_cmp_lt_u32 s48, 8
	s_cbranch_scc1 .Lpf_issue
.Lpf_ret_k2:
	s_cmp_lg_u32 s49, 0
	s_cbranch_scc1 .LBB0_1279
	ds_read_b128 v[2:5], v83
	ds_read_b128 v[6:9], v83 offset:64
	ds_read_b128 v[10:13], v83 offset:128
	ds_read_b128 v[34:37], v83 offset:192
	ds_read_b128 v[38:41], v83 offset:4352
	ds_read_b128 v[42:45], v83 offset:4416
	ds_read_b128 v[46:49], v83 offset:4480
	ds_read_b128 v[50:53], v83 offset:4544
	s_waitcnt lgkmcnt(7)
	v_mfma_f32_16x16x32_bf16 v[2:5], v[2:5], v[16:19], 0
	s_waitcnt lgkmcnt(6)
	v_mfma_f32_16x16x32_bf16 v[2:5], v[6:9], v[20:23], v[2:5]
	s_waitcnt lgkmcnt(5)
	v_mfma_f32_16x16x32_bf16 v[2:5], v[10:13], v[24:27], v[2:5]
	s_waitcnt lgkmcnt(4)
	v_mfma_f32_16x16x32_bf16 v[12:15], v[34:37], v[28:31], v[2:5]
	s_waitcnt lgkmcnt(3)
	v_mfma_f32_16x16x32_bf16 v[2:5], v[38:41], v[16:19], 0
	s_waitcnt lgkmcnt(2)
	v_mfma_f32_16x16x32_bf16 v[2:5], v[42:45], v[20:23], v[2:5]
	s_waitcnt lgkmcnt(1)
	v_mfma_f32_16x16x32_bf16 v[2:5], v[46:49], v[24:27], v[2:5]
	s_waitcnt lgkmcnt(0)
	v_mfma_f32_16x16x32_bf16 v[8:11], v[50:53], v[28:31], v[2:5]
.LBB0_1279:
	s_add_i32 s8, s73, -4
	s_cmp_gt_u32 s8, -11
	s_cselect_b64 s[34:35], -1, 0
	s_cmp_lt_u32 s8, -10
	v_mov_b32_e32 v1, 0
	s_nop 0
	v_mov_b32_e32 v2, 0
	v_mov_b32_e32 v3, 0
	v_mov_b32_e32 v42, 0
	v_mov_b32_e32 v43, 0
	v_mov_b32_e32 v44, 0
	v_mov_b32_e32 v45, 0
	s_cbranch_scc1 .LBB0_1281
	v_or_b32_e32 v42, 48, v98
	v_mad_u32_u24 v42, v42, s33, v82
	ds_read_b128 v[0:3], v83 offset:8704
	ds_read_b128 v[4:7], v83 offset:8768
	ds_read_b128 v[34:37], v83 offset:8832
	ds_read_b128 v[38:41], v83 offset:8896
	ds_read_b128 v[46:49], v42
	ds_read_b128 v[50:53], v42 offset:64
	ds_read_b128 v[54:57], v42 offset:128
	ds_read_b128 v[58:61], v42 offset:192
	s_waitcnt lgkmcnt(7)
	v_mfma_f32_16x16x32_bf16 v[0:3], v[0:3], v[16:19], 0
	s_waitcnt lgkmcnt(6)
	v_mfma_f32_16x16x32_bf16 v[0:3], v[4:7], v[20:23], v[0:3]
	s_waitcnt lgkmcnt(5)
	v_mfma_f32_16x16x32_bf16 v[0:3], v[34:37], v[24:27], v[0:3]
	s_waitcnt lgkmcnt(4)
	v_mfma_f32_16x16x32_bf16 v[42:45], v[38:41], v[28:31], v[0:3]
	s_waitcnt lgkmcnt(3)
	v_mfma_f32_16x16x32_bf16 v[0:3], v[46:49], v[16:19], 0
	s_waitcnt lgkmcnt(2)
	v_mfma_f32_16x16x32_bf16 v[0:3], v[50:53], v[20:23], v[0:3]
	s_waitcnt lgkmcnt(1)
	v_mfma_f32_16x16x32_bf16 v[0:3], v[54:57], v[24:27], v[0:3]
	s_waitcnt lgkmcnt(0)
	v_mfma_f32_16x16x32_bf16 v[0:3], v[58:61], v[28:31], v[0:3]
.LBB0_1281:
	s_add_i32 s8, s73, -6
	s_cmp_gt_u32 s8, -11
	v_mov_b32_e32 v4, 0
	s_cselect_b64 s[30:31], -1, 0
	s_cmp_lt_u32 s8, -10
	v_mov_b32_e32 v38, 0
	v_mov_b32_e32 v39, 0
	v_mov_b32_e32 v40, 0
	v_mov_b32_e32 v41, 0
	v_mov_b32_e32 v46, 0
	v_mov_b32_e32 v47, 0
	v_mov_b32_e32 v48, 0
	v_mov_b32_e32 v49, 0
	s_cbranch_scc1 .LBB0_1283
	ds_read_b128 v[34:37], v83 offset:17408
	ds_read_b128 v[38:41], v83 offset:17472
	ds_read_b128 v[46:49], v83 offset:17536
	ds_read_b128 v[50:53], v83 offset:17600
	ds_read_b128 v[54:57], v83 offset:21760
	ds_read_b128 v[58:61], v83 offset:21824
	ds_read_b128 v[62:65], v83 offset:21888
	ds_read_b128 v[66:69], v83 offset:21952
	s_waitcnt lgkmcnt(7)
	v_mfma_f32_16x16x32_bf16 v[34:37], v[34:37], v[16:19], 0
	s_waitcnt lgkmcnt(6)
	v_mfma_f32_16x16x32_bf16 v[34:37], v[38:41], v[20:23], v[34:37]
	s_waitcnt lgkmcnt(5)
	v_mfma_f32_16x16x32_bf16 v[34:37], v[46:49], v[24:27], v[34:37]
	s_waitcnt lgkmcnt(4)
	v_mfma_f32_16x16x32_bf16 v[46:49], v[50:53], v[28:31], v[34:37]
	s_waitcnt lgkmcnt(3)
	v_mfma_f32_16x16x32_bf16 v[34:37], v[54:57], v[16:19], 0
	s_waitcnt lgkmcnt(2)
	v_mfma_f32_16x16x32_bf16 v[34:37], v[58:61], v[20:23], v[34:37]
	s_waitcnt lgkmcnt(1)
	v_mfma_f32_16x16x32_bf16 v[34:37], v[62:65], v[24:27], v[34:37]
	s_waitcnt lgkmcnt(0)
	v_mfma_f32_16x16x32_bf16 v[38:41], v[66:69], v[28:31], v[34:37]
.LBB0_1283:
	s_add_i32 s8, s73, -8
	s_cmp_gt_u32 s8, -11
	s_cselect_b64 s[20:21], -1, 0
	s_cmp_lt_u32 s8, -10
	v_mov_b32_e32 v5, 0
	v_mov_b32_e32 v6, 0
	v_mov_b32_e32 v7, 0
	v_mov_b32_e32 v58, 0
	v_mov_b32_e32 v59, 0
	v_mov_b32_e32 v60, 0
	v_mov_b32_e32 v61, 0
	s_cbranch_scc1 .LBB0_1285
	v_or_b32_e32 v58, 0x70, v98
	v_mad_u32_u24 v58, v58, s33, v82
	ds_read_b128 v[4:7], v83 offset:26112
	ds_read_b128 v[34:37], v83 offset:26176
	ds_read_b128 v[50:53], v83 offset:26240
	ds_read_b128 v[54:57], v83 offset:26304
	ds_read_b128 v[62:65], v58
	ds_read_b128 v[66:69], v58 offset:64
	ds_read_b128 v[70:73], v58 offset:128
	ds_read_b128 v[74:77], v58 offset:192
	s_waitcnt lgkmcnt(7)
	v_mfma_f32_16x16x32_bf16 v[4:7], v[4:7], v[16:19], 0
	s_waitcnt lgkmcnt(6)
	v_mfma_f32_16x16x32_bf16 v[4:7], v[34:37], v[20:23], v[4:7]
	s_waitcnt lgkmcnt(5)
	v_mfma_f32_16x16x32_bf16 v[4:7], v[50:53], v[24:27], v[4:7]
	s_waitcnt lgkmcnt(4)
	v_mfma_f32_16x16x32_bf16 v[58:61], v[54:57], v[28:31], v[4:7]
	s_waitcnt lgkmcnt(3)
	v_mfma_f32_16x16x32_bf16 v[4:7], v[62:65], v[16:19], 0
	s_waitcnt lgkmcnt(2)
	v_mfma_f32_16x16x32_bf16 v[4:7], v[66:69], v[20:23], v[4:7]
	s_waitcnt lgkmcnt(1)
	v_mfma_f32_16x16x32_bf16 v[4:7], v[70:73], v[24:27], v[4:7]
	s_waitcnt lgkmcnt(0)
	v_mfma_f32_16x16x32_bf16 v[4:7], v[74:77], v[28:31], v[4:7]
.LBB0_1285:
	s_cmp_lt_u32 s73, 10
	v_mov_b32_e32 v34, 0
	s_cselect_b64 s[18:19], -1, 0
	s_cmp_gt_u32 s73, 9
	v_mov_b32_e32 v54, 0
	v_mov_b32_e32 v55, 0
	v_mov_b32_e32 v56, 0
	v_mov_b32_e32 v57, 0
	v_mov_b32_e32 v62, 0
	v_mov_b32_e32 v63, 0
	v_mov_b32_e32 v64, 0
	v_mov_b32_e32 v65, 0
	s_cbranch_scc1 .LBB0_1287
	ds_read_b128 v[50:53], v83 offset:34816
	ds_read_b128 v[54:57], v83 offset:34880
	ds_read_b128 v[62:65], v83 offset:34944
	ds_read_b128 v[66:69], v83 offset:35008
	ds_read_b128 v[70:73], v83 offset:39168
	ds_read_b128 v[74:77], v83 offset:39232
	ds_read_b128 v[78:81], v83 offset:39296
	ds_read_b128 v[84:87], v83 offset:39360
	s_waitcnt lgkmcnt(7)
	v_mfma_f32_16x16x32_bf16 v[50:53], v[50:53], v[16:19], 0
	s_waitcnt lgkmcnt(6)
	v_mfma_f32_16x16x32_bf16 v[50:53], v[54:57], v[20:23], v[50:53]
	s_waitcnt lgkmcnt(5)
	v_mfma_f32_16x16x32_bf16 v[50:53], v[62:65], v[24:27], v[50:53]
	s_waitcnt lgkmcnt(4)
	v_mfma_f32_16x16x32_bf16 v[62:65], v[66:69], v[28:31], v[50:53]
	s_waitcnt lgkmcnt(3)
	v_mfma_f32_16x16x32_bf16 v[50:53], v[70:73], v[16:19], 0
	s_waitcnt lgkmcnt(2)
	v_mfma_f32_16x16x32_bf16 v[50:53], v[74:77], v[20:23], v[50:53]
	s_waitcnt lgkmcnt(1)
	v_mfma_f32_16x16x32_bf16 v[50:53], v[78:81], v[24:27], v[50:53]
	s_waitcnt lgkmcnt(0)
	v_mfma_f32_16x16x32_bf16 v[54:57], v[84:87], v[28:31], v[50:53]
.LBB0_1287:
	s_add_i32 s8, s73, -12
	s_cmp_gt_u32 s8, -11
	s_cselect_b64 s[16:17], -1, 0
	s_cmp_lt_u32 s8, -10
	v_mov_b32_e32 v35, 0
	v_mov_b32_e32 v36, 0
	v_mov_b32_e32 v37, 0
	v_mov_b32_e32 v70, 0
	v_mov_b32_e32 v71, 0
	v_mov_b32_e32 v72, 0
	v_mov_b32_e32 v73, 0
	s_cbranch_scc1 .LBB0_1289
	v_or_b32_e32 v74, 0xb0, v98
	v_mad_u32_u24 v88, v74, s33, v82
	ds_read_b128 v[34:37], v83 offset:43520
	ds_read_b128 v[50:53], v83 offset:43584
	ds_read_b128 v[66:69], v83 offset:43648
	ds_read_b128 v[70:73], v83 offset:43712
	ds_read_b128 v[74:77], v88
	ds_read_b128 v[78:81], v88 offset:64
	ds_read_b128 v[84:87], v88 offset:128
	ds_read_b128 v[88:91], v88 offset:192
	s_waitcnt lgkmcnt(7)
	v_mfma_f32_16x16x32_bf16 v[34:37], v[34:37], v[16:19], 0
	s_waitcnt lgkmcnt(6)
	v_mfma_f32_16x16x32_bf16 v[34:37], v[50:53], v[20:23], v[34:37]
	s_waitcnt lgkmcnt(5)
	v_mfma_f32_16x16x32_bf16 v[34:37], v[66:69], v[24:27], v[34:37]
	s_waitcnt lgkmcnt(4)
	v_mfma_f32_16x16x32_bf16 v[70:73], v[70:73], v[28:31], v[34:37]
	s_waitcnt lgkmcnt(3)
	v_mfma_f32_16x16x32_bf16 v[34:37], v[74:77], v[16:19], 0
	s_waitcnt lgkmcnt(2)
	v_mfma_f32_16x16x32_bf16 v[34:37], v[78:81], v[20:23], v[34:37]
	s_waitcnt lgkmcnt(1)
	v_mfma_f32_16x16x32_bf16 v[34:37], v[84:87], v[24:27], v[34:37]
	s_waitcnt lgkmcnt(0)
	v_mfma_f32_16x16x32_bf16 v[34:37], v[88:91], v[28:31], v[34:37]
.LBB0_1289:
	s_add_i32 s8, s73, -14
	s_cmp_gt_u32 s8, -11
	v_mov_b32_e32 v50, 0
	s_cselect_b64 s[14:15], -1, 0
	s_cmp_lt_u32 s8, -10
	v_mov_b32_e32 v66, 0
	v_mov_b32_e32 v67, 0
	v_mov_b32_e32 v68, 0
	v_mov_b32_e32 v69, 0
	v_mov_b32_e32 v74, 0
	v_mov_b32_e32 v75, 0
	v_mov_b32_e32 v76, 0
	v_mov_b32_e32 v77, 0
	s_cbranch_scc1 .LBB0_1291
	ds_read_b128 v[66:69], v83 offset:52224
	ds_read_b128 v[74:77], v83 offset:52288
	ds_read_b128 v[78:81], v83 offset:52352
	ds_read_b128 v[84:87], v83 offset:52416
	ds_read_b128 v[88:91], v83 offset:56576
	ds_read_b128 v[92:95], v83 offset:56640
	ds_read_b128 v[102:105], v83 offset:56704
	ds_read_b128 v[106:109], v83 offset:56768
	s_waitcnt lgkmcnt(7)
	v_mfma_f32_16x16x32_bf16 v[66:69], v[66:69], v[16:19], 0
	s_waitcnt lgkmcnt(6)
	v_mfma_f32_16x16x32_bf16 v[66:69], v[74:77], v[20:23], v[66:69]
	s_waitcnt lgkmcnt(5)
	v_mfma_f32_16x16x32_bf16 v[66:69], v[78:81], v[24:27], v[66:69]
	s_waitcnt lgkmcnt(4)
	v_mfma_f32_16x16x32_bf16 v[74:77], v[84:87], v[28:31], v[66:69]
	s_waitcnt lgkmcnt(3)
	v_mfma_f32_16x16x32_bf16 v[66:69], v[88:91], v[16:19], 0
	s_waitcnt lgkmcnt(2)
	v_mfma_f32_16x16x32_bf16 v[66:69], v[92:95], v[20:23], v[66:69]
	s_waitcnt lgkmcnt(1)
	v_mfma_f32_16x16x32_bf16 v[66:69], v[102:105], v[24:27], v[66:69]
	s_waitcnt lgkmcnt(0)
	v_mfma_f32_16x16x32_bf16 v[66:69], v[106:109], v[28:31], v[66:69]
.LBB0_1291:
	s_add_i32 s8, s73, -16
	s_cmp_gt_u32 s8, -11
	s_cselect_b64 s[12:13], -1, 0
	s_cmp_lt_u32 s8, -10
	v_mov_b32_e32 v51, 0
	v_mov_b32_e32 v52, 0
	v_mov_b32_e32 v53, 0
	v_mov_b32_e32 v78, 0
	v_mov_b32_e32 v79, 0
	v_mov_b32_e32 v80, 0
	v_mov_b32_e32 v81, 0
	s_cbranch_scc1 .LBB0_1293
	ds_read_b128 v[50:53], v83 offset:60928
	ds_read_b128 v[78:81], v83 offset:60992
	ds_read_b128 v[84:87], v83 offset:61056
	ds_read_b128 v[88:91], v83 offset:61120
	v_or_b32_e32 v83, 0xf0, v98
	v_mad_u32_u24 v82, v83, s33, v82
	ds_read_b128 v[92:95], v82
	ds_read_b128 v[102:105], v82 offset:64
	ds_read_b128 v[106:109], v82 offset:128
	ds_read_b128 v[110:113], v82 offset:192
	s_waitcnt lgkmcnt(7)
	v_mfma_f32_16x16x32_bf16 v[50:53], v[50:53], v[16:19], 0
	s_waitcnt lgkmcnt(3)
	v_mfma_f32_16x16x32_bf16 v[16:19], v[92:95], v[16:19], 0
	v_mfma_f32_16x16x32_bf16 v[50:53], v[78:81], v[20:23], v[50:53]
	s_waitcnt lgkmcnt(2)
	v_mfma_f32_16x16x32_bf16 v[16:19], v[102:105], v[20:23], v[16:19]
	v_mfma_f32_16x16x32_bf16 v[50:53], v[84:87], v[24:27], v[50:53]
	s_waitcnt lgkmcnt(1)
	v_mfma_f32_16x16x32_bf16 v[16:19], v[106:109], v[24:27], v[16:19]
	v_mfma_f32_16x16x32_bf16 v[78:81], v[88:91], v[28:31], v[50:53]
	s_waitcnt lgkmcnt(0)
	v_mfma_f32_16x16x32_bf16 v[50:53], v[110:113], v[28:31], v[16:19]
.LBB0_1293:
	v_lshl_or_b32 v82, s73, 4, v32
	v_readlane_b32 s8, v252, 57
	s_nop 0
	v_max_i32_e32 v16, 0x80, v82
	v_readlane_b32 s9, v252, 58
	v_lshrrev_b32_e32 v18, 2, v98
	v_add_u32_e32 v17, 0x80, v82
	v_cndmask_b32_e64 v16, v82, v16, s[8:9]
	v_and_b32_e32 v83, 12, v18
	v_cmp_lt_i32_e32 vcc, v83, v16
	v_cmp_gt_i32_e64 s[10:11], v83, v17
	s_or_b64 vcc, vcc, s[10:11]
	v_or_b32_e32 v19, 1, v83
	v_cndmask_b32_e32 v12, v12, v225, vcc
	v_cmp_lt_i32_e32 vcc, v19, v16
	v_cmp_ge_i32_e64 s[10:11], v83, v17
	s_or_b64 vcc, vcc, s[10:11]
	v_or_b32_e32 v19, 2, v83
	v_cndmask_b32_e32 v13, v13, v225, vcc
	v_cmp_lt_i32_e32 vcc, v19, v16
	v_cmp_gt_i32_e64 s[10:11], v19, v17
	s_or_b64 vcc, vcc, s[10:11]
	v_or_b32_e32 v19, 3, v18
	v_cndmask_b32_e32 v14, v14, v225, vcc
	v_cmp_lt_i32_e32 vcc, v19, v16
	v_cmp_gt_i32_e64 s[10:11], v19, v17
	s_or_b64 vcc, vcc, s[10:11]
	v_or_b32_e32 v19, 16, v83
	v_cndmask_b32_e32 v15, v15, v225, vcc
	v_cmp_lt_i32_e32 vcc, v19, v16
	v_cmp_gt_i32_e64 s[10:11], v19, v17
	s_or_b64 vcc, vcc, s[10:11]
	v_or_b32_e32 v19, 17, v83
	v_cndmask_b32_e32 v8, v8, v225, vcc
	v_cmp_lt_i32_e32 vcc, v19, v16
	v_cmp_gt_i32_e64 s[10:11], v19, v17
	s_or_b64 vcc, vcc, s[10:11]
	v_or_b32_e32 v19, 18, v83
	v_cndmask_b32_e32 v9, v9, v225, vcc
	v_cmp_lt_i32_e32 vcc, v19, v16
	v_cmp_gt_i32_e64 s[10:11], v19, v17
	s_or_b64 vcc, vcc, s[10:11]
	v_or_b32_e32 v19, 19, v18
	v_cndmask_b32_e32 v10, v10, v225, vcc
	v_cmp_lt_i32_e32 vcc, v19, v16
	v_cmp_gt_i32_e64 s[10:11], v19, v17
	s_or_b64 vcc, vcc, s[10:11]
	v_or_b32_e32 v19, 32, v83
	v_cndmask_b32_e32 v11, v11, v225, vcc
	v_cmp_lt_i32_e32 vcc, v19, v16
	v_cmp_gt_i32_e64 s[10:11], v19, v17
	s_or_b64 vcc, vcc, s[10:11]
	v_or_b32_e32 v20, 33, v83
	v_cndmask_b32_e32 v19, v42, v225, vcc
	v_cmp_lt_i32_e32 vcc, v20, v16
	v_cmp_gt_i32_e64 s[10:11], v20, v17
	s_or_b64 vcc, vcc, s[10:11]
	v_or_b32_e32 v21, 34, v83
	v_cndmask_b32_e32 v20, v43, v225, vcc
	v_cmp_lt_i32_e32 vcc, v21, v16
	v_cmp_gt_i32_e64 s[10:11], v21, v17
	s_or_b64 vcc, vcc, s[10:11]
	v_or_b32_e32 v22, 35, v18
	v_cndmask_b32_e32 v21, v44, v225, vcc
	v_cmp_lt_i32_e32 vcc, v22, v16
	v_cmp_gt_i32_e64 s[10:11], v22, v17
	s_or_b64 vcc, vcc, s[10:11]
	v_or_b32_e32 v23, 48, v83
	v_cndmask_b32_e32 v22, v45, v225, vcc
	v_cmp_lt_i32_e32 vcc, v23, v16
	v_cmp_gt_i32_e64 s[10:11], v23, v17
	s_or_b64 vcc, vcc, s[10:11]
	v_or_b32_e32 v23, 49, v83
	v_cndmask_b32_e32 v0, v0, v225, vcc
	v_cmp_lt_i32_e32 vcc, v23, v16
	v_cmp_gt_i32_e64 s[10:11], v23, v17
	s_or_b64 vcc, vcc, s[10:11]
	v_or_b32_e32 v23, 50, v83
	v_cndmask_b32_e32 v1, v1, v225, vcc
	v_cmp_lt_i32_e32 vcc, v23, v16
	v_cmp_gt_i32_e64 s[10:11], v23, v17
	s_or_b64 vcc, vcc, s[10:11]
	v_or_b32_e32 v23, 51, v18
	v_cndmask_b32_e32 v2, v2, v225, vcc
	v_cmp_lt_i32_e32 vcc, v23, v16
	v_cmp_gt_i32_e64 s[10:11], v23, v17
	s_or_b64 vcc, vcc, s[10:11]
	v_or_b32_e32 v23, 64, v83
	v_cndmask_b32_e32 v3, v3, v225, vcc
	v_cmp_lt_i32_e32 vcc, v23, v16
	v_cmp_gt_i32_e64 s[10:11], v23, v17
	s_or_b64 vcc, vcc, s[10:11]
	v_or_b32_e32 v24, 0x41, v83
	v_cndmask_b32_e32 v23, v46, v225, vcc
	v_cmp_lt_i32_e32 vcc, v24, v16
	v_cmp_gt_i32_e64 s[10:11], v24, v17
	s_or_b64 vcc, vcc, s[10:11]
	v_or_b32_e32 v25, 0x42, v83
	v_cndmask_b32_e32 v24, v47, v225, vcc
	v_cmp_lt_i32_e32 vcc, v25, v16
	v_cmp_gt_i32_e64 s[10:11], v25, v17
	s_or_b64 vcc, vcc, s[10:11]
	v_or_b32_e32 v26, 0x43, v18
	v_cndmask_b32_e32 v25, v48, v225, vcc
	v_cmp_lt_i32_e32 vcc, v26, v16
	v_cmp_gt_i32_e64 s[10:11], v26, v17
	s_or_b64 vcc, vcc, s[10:11]
	v_or_b32_e32 v27, 0x50, v83
	v_cndmask_b32_e32 v26, v49, v225, vcc
	v_cmp_lt_i32_e32 vcc, v27, v16
	v_cmp_gt_i32_e64 s[10:11], v27, v17
	s_or_b64 vcc, vcc, s[10:11]
	v_or_b32_e32 v28, 0x51, v83
	v_cndmask_b32_e32 v27, v38, v225, vcc
	v_cmp_lt_i32_e32 vcc, v28, v16
	v_cmp_gt_i32_e64 s[10:11], v28, v17
	s_or_b64 vcc, vcc, s[10:11]
	v_or_b32_e32 v29, 0x52, v83
	v_cndmask_b32_e32 v28, v39, v225, vcc
	v_cmp_lt_i32_e32 vcc, v29, v16
	v_cmp_gt_i32_e64 s[10:11], v29, v17
	s_or_b64 vcc, vcc, s[10:11]
	v_or_b32_e32 v30, 0x53, v18
	v_cndmask_b32_e32 v29, v40, v225, vcc
	v_cmp_lt_i32_e32 vcc, v30, v16
	v_cmp_gt_i32_e64 s[10:11], v30, v17
	s_or_b64 vcc, vcc, s[10:11]
	v_or_b32_e32 v31, 0x60, v83
	v_cndmask_b32_e32 v30, v41, v225, vcc
	v_cmp_lt_i32_e32 vcc, v31, v16
	v_cmp_gt_i32_e64 s[10:11], v31, v17
	s_or_b64 vcc, vcc, s[10:11]
	v_or_b32_e32 v38, 0x61, v83
	v_cndmask_b32_e32 v31, v58, v225, vcc
	v_cmp_lt_i32_e32 vcc, v38, v16
	v_cmp_gt_i32_e64 s[10:11], v38, v17
	s_or_b64 vcc, vcc, s[10:11]
	v_or_b32_e32 v38, 0x62, v83
	v_cndmask_b32_e32 v39, v59, v225, vcc
	v_cmp_lt_i32_e32 vcc, v38, v16
	v_cmp_gt_i32_e64 s[10:11], v38, v17
	s_or_b64 vcc, vcc, s[10:11]
	v_or_b32_e32 v38, 0x63, v18
	v_cndmask_b32_e32 v40, v60, v225, vcc
	v_cmp_lt_i32_e32 vcc, v38, v16
	v_cmp_gt_i32_e64 s[10:11], v38, v17
	s_or_b64 vcc, vcc, s[10:11]
	v_or_b32_e32 v38, 0x70, v83
	v_cndmask_b32_e32 v41, v61, v225, vcc
	v_cmp_lt_i32_e32 vcc, v38, v16
	v_cmp_gt_i32_e64 s[10:11], v38, v17
	s_or_b64 vcc, vcc, s[10:11]
	v_or_b32_e32 v38, 0x71, v83
	v_cndmask_b32_e32 v4, v4, v225, vcc
	v_cmp_lt_i32_e32 vcc, v38, v16
	v_cmp_gt_i32_e64 s[10:11], v38, v17
	s_or_b64 vcc, vcc, s[10:11]
	v_or_b32_e32 v38, 0x72, v83
	v_cndmask_b32_e32 v5, v5, v225, vcc
	v_cmp_lt_i32_e32 vcc, v38, v16
	v_cmp_gt_i32_e64 s[10:11], v38, v17
	s_or_b64 vcc, vcc, s[10:11]
	v_or_b32_e32 v38, 0x73, v18
	v_cndmask_b32_e32 v6, v6, v225, vcc
	v_cmp_lt_i32_e32 vcc, v38, v16
	v_cmp_gt_i32_e64 s[10:11], v38, v17
	s_or_b64 vcc, vcc, s[10:11]
	v_or_b32_e32 v38, 0x80, v83
	v_cndmask_b32_e32 v7, v7, v225, vcc
	v_cmp_lt_i32_e32 vcc, v38, v16
	v_cmp_gt_i32_e64 s[10:11], v83, v82
	s_or_b64 vcc, vcc, s[10:11]
	v_or_b32_e32 v38, 0x81, v83
	v_cndmask_b32_e32 v42, v62, v225, vcc
	v_cmp_lt_i32_e32 vcc, v38, v16
	v_cmp_gt_i32_e64 s[10:11], v38, v17
	s_or_b64 vcc, vcc, s[10:11]
	v_or_b32_e32 v38, 0x82, v83
	v_cndmask_b32_e32 v43, v63, v225, vcc
	v_cmp_lt_i32_e32 vcc, v38, v16
	v_cmp_gt_i32_e64 s[10:11], v38, v17
	s_or_b64 vcc, vcc, s[10:11]
	v_or_b32_e32 v38, 0x83, v18
	v_cndmask_b32_e32 v44, v64, v225, vcc
	v_cmp_lt_i32_e32 vcc, v38, v16
	v_cmp_gt_i32_e64 s[10:11], v38, v17
	s_or_b64 vcc, vcc, s[10:11]
	v_or_b32_e32 v38, 0x90, v83
	v_cndmask_b32_e32 v45, v65, v225, vcc
	v_cmp_lt_i32_e32 vcc, v38, v16
	v_cmp_gt_i32_e64 s[10:11], v38, v17
	s_or_b64 vcc, vcc, s[10:11]
	v_or_b32_e32 v38, 0x91, v83
	v_cndmask_b32_e32 v46, v54, v225, vcc
	v_cmp_lt_i32_e32 vcc, v38, v16
	v_cmp_gt_i32_e64 s[10:11], v38, v17
	s_or_b64 vcc, vcc, s[10:11]
	v_or_b32_e32 v38, 0x92, v83
	v_cndmask_b32_e32 v47, v55, v225, vcc
	v_cmp_lt_i32_e32 vcc, v38, v16
	v_cmp_gt_i32_e64 s[10:11], v38, v17
	s_or_b64 vcc, vcc, s[10:11]
	v_or_b32_e32 v38, 0x93, v18
	v_cndmask_b32_e32 v48, v56, v225, vcc
	v_cmp_lt_i32_e32 vcc, v38, v16
	v_cmp_gt_i32_e64 s[10:11], v38, v17
	s_or_b64 vcc, vcc, s[10:11]
	v_or_b32_e32 v38, 0xa0, v83
	v_cndmask_b32_e32 v49, v57, v225, vcc
	v_cmp_lt_i32_e32 vcc, v38, v16
	v_cmp_gt_i32_e64 s[10:11], v38, v17
	s_or_b64 vcc, vcc, s[10:11]
	v_or_b32_e32 v38, 0xa1, v83
	v_cndmask_b32_e32 v54, v70, v225, vcc
	v_cmp_lt_i32_e32 vcc, v38, v16
	v_cmp_gt_i32_e64 s[10:11], v38, v17
	s_or_b64 vcc, vcc, s[10:11]
	v_or_b32_e32 v38, 0xa2, v83
	v_cndmask_b32_e32 v55, v71, v225, vcc
	v_cmp_lt_i32_e32 vcc, v38, v16
	v_cmp_gt_i32_e64 s[10:11], v38, v17
	s_or_b64 vcc, vcc, s[10:11]
	v_or_b32_e32 v38, 0xa3, v18
	v_cndmask_b32_e32 v56, v72, v225, vcc
	v_cmp_lt_i32_e32 vcc, v38, v16
	v_cmp_gt_i32_e64 s[10:11], v38, v17
	s_or_b64 vcc, vcc, s[10:11]
	v_or_b32_e32 v38, 0xb0, v83
	v_cndmask_b32_e32 v57, v73, v225, vcc
	v_cmp_lt_i32_e32 vcc, v38, v16
	v_cmp_gt_i32_e64 s[10:11], v38, v17
	s_or_b64 vcc, vcc, s[10:11]
	v_or_b32_e32 v38, 0xb1, v83
	v_cndmask_b32_e32 v34, v34, v225, vcc
	v_cmp_lt_i32_e32 vcc, v38, v16
	v_cmp_gt_i32_e64 s[10:11], v38, v17
	s_or_b64 vcc, vcc, s[10:11]
	v_or_b32_e32 v38, 0xb2, v83
	v_cndmask_b32_e32 v35, v35, v225, vcc
	v_cmp_lt_i32_e32 vcc, v38, v16
	v_cmp_gt_i32_e64 s[10:11], v38, v17
	s_or_b64 vcc, vcc, s[10:11]
	v_cndmask_b32_e32 v62, v36, v225, vcc
	v_or_b32_e32 v36, 0xb3, v18
	v_cmp_lt_i32_e32 vcc, v36, v16
	v_cmp_gt_i32_e64 s[10:11], v36, v17
	s_or_b64 vcc, vcc, s[10:11]
	v_or_b32_e32 v36, 0xc0, v83
	v_cndmask_b32_e32 v64, v37, v225, vcc
	v_cmp_lt_i32_e32 vcc, v36, v16
	v_cmp_gt_i32_e64 s[10:11], v36, v17
	s_or_b64 vcc, vcc, s[10:11]
	v_or_b32_e32 v36, 0xc1, v83
	v_cndmask_b32_e32 v102, v74, v225, vcc
	v_cmp_lt_i32_e32 vcc, v36, v16
	v_cmp_gt_i32_e64 s[10:11], v36, v17
	s_or_b64 vcc, vcc, s[10:11]
	v_or_b32_e32 v36, 0xc2, v83
	v_cndmask_b32_e32 v103, v75, v225, vcc
	v_cmp_lt_i32_e32 vcc, v36, v16
	v_cmp_gt_i32_e64 s[10:11], v36, v17
	s_or_b64 vcc, vcc, s[10:11]
	v_or_b32_e32 v36, 0xc3, v18
	v_cndmask_b32_e32 v104, v76, v225, vcc
	v_cmp_lt_i32_e32 vcc, v36, v16
	v_cmp_gt_i32_e64 s[10:11], v36, v17
	s_or_b64 vcc, vcc, s[10:11]
	v_or_b32_e32 v36, 0xd0, v83
	v_cndmask_b32_e32 v105, v77, v225, vcc
	v_cmp_lt_i32_e32 vcc, v36, v16
	v_cmp_gt_i32_e64 s[10:11], v36, v17
	s_or_b64 vcc, vcc, s[10:11]
	v_or_b32_e32 v36, 0xd1, v83
	v_cndmask_b32_e32 v106, v66, v225, vcc
	v_cmp_lt_i32_e32 vcc, v36, v16
	v_cmp_gt_i32_e64 s[10:11], v36, v17
	s_or_b64 vcc, vcc, s[10:11]
	v_or_b32_e32 v36, 0xd2, v83
	v_cndmask_b32_e32 v107, v67, v225, vcc
	v_cmp_lt_i32_e32 vcc, v36, v16
	v_cmp_gt_i32_e64 s[10:11], v36, v17
	s_or_b64 vcc, vcc, s[10:11]
	v_or_b32_e32 v36, 0xd3, v18
	v_cndmask_b32_e32 v108, v68, v225, vcc
	v_cmp_lt_i32_e32 vcc, v36, v16
	v_cmp_gt_i32_e64 s[10:11], v36, v17
	s_or_b64 vcc, vcc, s[10:11]
	v_or_b32_e32 v36, 0xe0, v83
	v_cndmask_b32_e32 v109, v69, v225, vcc
	v_cmp_lt_i32_e32 vcc, v36, v16
	v_cmp_gt_i32_e64 s[10:11], v36, v17
	s_or_b64 vcc, vcc, s[10:11]
	v_or_b32_e32 v36, 0xe1, v83
	v_cndmask_b32_e32 v110, v78, v225, vcc
	v_cmp_lt_i32_e32 vcc, v36, v16
	v_cmp_gt_i32_e64 s[10:11], v36, v17
	s_or_b64 vcc, vcc, s[10:11]
	v_or_b32_e32 v36, 0xe2, v83
	v_cndmask_b32_e32 v111, v79, v225, vcc
	v_cmp_lt_i32_e32 vcc, v36, v16
	v_cmp_gt_i32_e64 s[10:11], v36, v17
	s_or_b64 vcc, vcc, s[10:11]
	v_or_b32_e32 v36, 0xe3, v18
	v_cndmask_b32_e32 v112, v80, v225, vcc
	v_cmp_lt_i32_e32 vcc, v36, v16
	v_cmp_gt_i32_e64 s[10:11], v36, v17
	s_or_b64 vcc, vcc, s[10:11]
	v_or_b32_e32 v36, 0xf0, v83
	v_cndmask_b32_e32 v113, v81, v225, vcc
	v_cmp_lt_i32_e32 vcc, v36, v16
	v_cmp_gt_i32_e64 s[10:11], v36, v17
	s_or_b64 vcc, vcc, s[10:11]
	v_or_b32_e32 v36, 0xf1, v83
	v_cndmask_b32_e32 v114, v50, v225, vcc
	v_cmp_lt_i32_e32 vcc, v36, v16
	v_cmp_gt_i32_e64 s[10:11], v36, v17
	s_or_b64 vcc, vcc, s[10:11]
	v_or_b32_e32 v36, 0xf2, v83
	v_cndmask_b32_e32 v115, v51, v225, vcc
	v_cmp_lt_i32_e32 vcc, v36, v16
	v_cmp_gt_i32_e64 s[10:11], v36, v17
	s_or_b64 vcc, vcc, s[10:11]
	v_or_b32_e32 v18, 0xf3, v18
	v_cndmask_b32_e32 v116, v52, v225, vcc
	v_cmp_lt_i32_e32 vcc, v18, v16
	v_cmp_gt_i32_e64 s[10:11], v18, v17
	v_max_f32_e32 v17, v13, v13
	v_max_f32_e32 v18, v12, v12
	v_max_f32_e32 v17, v18, v17
	v_max_f32_e32 v18, v15, v15
	v_max_f32_e32 v36, v14, v14
	v_max_f32_e32 v18, v36, v18
	s_mov_b32 s8, 0xff61b1e6
	v_max3_f32 v17, v17, v18, s8
	v_max_f32_e32 v18, v9, v9
	v_max_f32_e32 v36, v8, v8
	v_max_f32_e32 v18, v36, v18
	v_max_f32_e32 v36, v11, v11
	v_max_f32_e32 v37, v10, v10
	v_max_f32_e32 v36, v37, v36
	v_max3_f32 v17, v18, v36, v17
	v_max_f32_e32 v18, v20, v20
	v_max_f32_e32 v36, v19, v19
	v_max_f32_e32 v18, v36, v18
	v_max_f32_e32 v36, v22, v22
	v_max_f32_e32 v37, v21, v21
	v_max_f32_e32 v36, v37, v36
	v_max3_f32 v17, v18, v36, v17
	v_max_f32_e32 v18, v1, v1
	v_max_f32_e32 v36, v0, v0
	v_max_f32_e32 v18, v36, v18
	v_max_f32_e32 v36, v3, v3
	v_max_f32_e32 v37, v2, v2
	v_max_f32_e32 v36, v37, v36
	v_max3_f32 v17, v18, v36, v17
	v_max_f32_e32 v18, v24, v24
	v_max_f32_e32 v36, v23, v23
	v_max_f32_e32 v18, v36, v18
	v_max_f32_e32 v36, v26, v26
	v_max_f32_e32 v37, v25, v25
	v_max_f32_e32 v36, v37, v36
	v_max3_f32 v17, v18, v36, v17
	v_max_f32_e32 v18, v28, v28
	v_max_f32_e32 v36, v27, v27
	v_max_f32_e32 v18, v36, v18
	v_max_f32_e32 v36, v30, v30
	v_max_f32_e32 v37, v29, v29
	v_max_f32_e32 v36, v37, v36
	v_max3_f32 v17, v18, v36, v17
	v_max_f32_e32 v18, v39, v39
	v_max_f32_e32 v36, v31, v31
	v_max_f32_e32 v18, v36, v18
	v_max_f32_e32 v36, v41, v41
	v_max_f32_e32 v37, v40, v40
	v_max_f32_e32 v36, v37, v36
	v_max3_f32 v17, v18, v36, v17
	v_max_f32_e32 v18, v5, v5
	v_max_f32_e32 v36, v4, v4
	v_max_f32_e32 v18, v36, v18
	v_max_f32_e32 v36, v7, v7
	v_max_f32_e32 v37, v6, v6
	v_max_f32_e32 v36, v37, v36
	v_max3_f32 v17, v18, v36, v17
	v_max_f32_e32 v18, v43, v43
	v_max_f32_e32 v36, v42, v42
	v_max_f32_e32 v18, v36, v18
	v_max_f32_e32 v36, v45, v45
	v_max_f32_e32 v37, v44, v44
	v_max_f32_e32 v36, v37, v36
	v_max3_f32 v17, v18, v36, v17
	v_max_f32_e32 v18, v47, v47
	v_max_f32_e32 v36, v46, v46
	v_max_f32_e32 v18, v36, v18
	v_max_f32_e32 v36, v49, v49
	v_max_f32_e32 v37, v48, v48
	v_max_f32_e32 v36, v37, v36
	v_max3_f32 v17, v18, v36, v17
	v_max_f32_e32 v18, v55, v55
	v_max_f32_e32 v36, v54, v54
	v_max_f32_e32 v18, v36, v18
	v_max_f32_e32 v36, v57, v57
	v_max_f32_e32 v37, v56, v56
	v_max_f32_e32 v36, v37, v36
	v_max3_f32 v17, v18, v36, v17
	v_max_f32_e32 v18, v35, v35
	v_max_f32_e32 v36, v34, v34
	v_max_f32_e32 v18, v36, v18
	v_max_f32_e32 v36, v64, v64
	v_max_f32_e32 v37, v62, v62
	v_max_f32_e32 v36, v37, v36
	v_max3_f32 v17, v18, v36, v17
	v_max_f32_e32 v18, v103, v103
	v_max_f32_e32 v36, v102, v102
	v_max_f32_e32 v18, v36, v18
	v_max_f32_e32 v36, v105, v105
	v_max_f32_e32 v37, v104, v104
	v_max_f32_e32 v36, v37, v36
	v_max3_f32 v17, v18, v36, v17
	v_max_f32_e32 v18, v107, v107
	v_max_f32_e32 v36, v106, v106
	v_max_f32_e32 v18, v36, v18
	v_max_f32_e32 v36, v109, v109
	v_max_f32_e32 v37, v108, v108
	v_max_f32_e32 v36, v37, v36
	v_max3_f32 v17, v18, v36, v17
	v_max_f32_e32 v18, v111, v111
	v_max_f32_e32 v36, v110, v110
	v_max_f32_e32 v18, v36, v18
	v_max_f32_e32 v36, v113, v113
	v_max_f32_e32 v37, v112, v112
	s_or_b64 vcc, vcc, s[10:11]
	v_max_f32_e32 v36, v37, v36
	v_cndmask_b32_e32 v16, v53, v225, vcc
	v_max3_f32 v17, v18, v36, v17
	v_max_f32_e32 v18, v115, v115
	v_max_f32_e32 v36, v114, v114
	v_max_f32_e32 v18, v36, v18
	v_max_f32_e32 v36, v16, v16
	v_max_f32_e32 v37, v116, v116
	v_max_f32_e32 v36, v37, v36
	v_max3_f32 v17, v18, v36, v17
	ds_bpermute_b32 v18, v100, v17
	s_andn2_b64 vcc, exec, s[44:45]
	s_waitcnt lgkmcnt(0)
	v_max_f32_e32 v18, v18, v18
	v_max_f32_e32 v17, v17, v18
	ds_bpermute_b32 v18, v101, v17
	s_waitcnt lgkmcnt(0)
	v_max_f32_e32 v18, v18, v18
	v_max_f32_e32 v38, v17, v18
	v_sub_f32_e32 v12, v12, v38
	v_exp_f32_e32 v12, v12
	v_sub_f32_e32 v13, v13, v38
	v_exp_f32_e32 v13, v13
	v_sub_f32_e32 v14, v14, v38
	v_exp_f32_e32 v14, v14
	v_sub_f32_e32 v15, v15, v38
	v_exp_f32_e32 v15, v15
	v_sub_f32_e32 v8, v8, v38
	v_add_f32_e32 v17, 0, v12
	v_exp_f32_e32 v8, v8
	v_sub_f32_e32 v9, v9, v38
	v_add_f32_e32 v17, v13, v17
	v_exp_f32_e32 v9, v9
	v_sub_f32_e32 v10, v10, v38
	v_add_f32_e32 v17, v14, v17
	v_exp_f32_e32 v10, v10
	v_sub_f32_e32 v11, v11, v38
	v_add_f32_e32 v17, v15, v17
	v_exp_f32_e32 v11, v11
	v_sub_f32_e32 v18, v19, v38
	v_add_f32_e32 v17, v8, v17
	v_exp_f32_e32 v36, v18
	v_sub_f32_e32 v18, v20, v38
	v_add_f32_e32 v17, v9, v17
	v_exp_f32_e32 v37, v18
	v_sub_f32_e32 v18, v21, v38
	v_add_f32_e32 v17, v10, v17
	v_exp_f32_e32 v92, v18
	v_sub_f32_e32 v18, v22, v38
	v_add_f32_e32 v17, v11, v17
	v_exp_f32_e32 v93, v18
	v_sub_f32_e32 v0, v0, v38
	v_add_f32_e32 v17, v36, v17
	v_exp_f32_e32 v95, v0
	v_sub_f32_e32 v0, v1, v38
	v_add_f32_e32 v17, v37, v17
	v_exp_f32_e32 v97, v0
	v_sub_f32_e32 v0, v2, v38
	v_add_f32_e32 v17, v92, v17
	v_exp_f32_e32 v94, v0
	v_sub_f32_e32 v0, v3, v38
	v_add_f32_e32 v17, v93, v17
	v_exp_f32_e32 v96, v0
	v_sub_f32_e32 v1, v23, v38
	v_add_f32_e32 v0, v95, v17
	v_exp_f32_e32 v84, v1
	v_sub_f32_e32 v1, v24, v38
	v_add_f32_e32 v0, v97, v0
	v_exp_f32_e32 v85, v1
	v_sub_f32_e32 v1, v25, v38
	v_add_f32_e32 v0, v94, v0
	v_exp_f32_e32 v86, v1
	v_sub_f32_e32 v1, v26, v38
	v_add_f32_e32 v0, v96, v0
	v_exp_f32_e32 v87, v1
	v_sub_f32_e32 v1, v27, v38
	v_add_f32_e32 v0, v84, v0
	v_exp_f32_e32 v89, v1
	v_sub_f32_e32 v1, v28, v38
	v_add_f32_e32 v0, v85, v0
	v_exp_f32_e32 v91, v1
	v_sub_f32_e32 v1, v29, v38
	v_add_f32_e32 v0, v86, v0
	v_exp_f32_e32 v88, v1
	v_sub_f32_e32 v1, v30, v38
	v_add_f32_e32 v0, v87, v0
	v_exp_f32_e32 v90, v1
	v_sub_f32_e32 v1, v31, v38
	v_add_f32_e32 v0, v89, v0
	v_exp_f32_e32 v74, v1
	v_sub_f32_e32 v1, v39, v38
	v_add_f32_e32 v0, v91, v0
	v_exp_f32_e32 v75, v1
	v_sub_f32_e32 v1, v40, v38
	v_add_f32_e32 v0, v88, v0
	v_exp_f32_e32 v76, v1
	v_sub_f32_e32 v1, v41, v38
	v_add_f32_e32 v0, v90, v0
	v_exp_f32_e32 v77, v1
	v_sub_f32_e32 v1, v4, v38
	v_add_f32_e32 v0, v74, v0
	v_exp_f32_e32 v79, v1
	v_sub_f32_e32 v1, v5, v38
	v_add_f32_e32 v0, v75, v0
	v_exp_f32_e32 v81, v1
	v_sub_f32_e32 v1, v6, v38
	v_add_f32_e32 v0, v76, v0
	v_exp_f32_e32 v78, v1
	v_sub_f32_e32 v1, v7, v38
	v_add_f32_e32 v0, v77, v0
	v_exp_f32_e32 v80, v1
	v_sub_f32_e32 v1, v42, v38
	v_add_f32_e32 v0, v79, v0
	v_exp_f32_e32 v66, v1
	v_sub_f32_e32 v1, v43, v38
	v_add_f32_e32 v0, v81, v0
	v_exp_f32_e32 v67, v1
	v_sub_f32_e32 v1, v44, v38
	v_add_f32_e32 v0, v78, v0
	v_exp_f32_e32 v68, v1
	v_sub_f32_e32 v1, v45, v38
	v_add_f32_e32 v0, v80, v0
	v_exp_f32_e32 v69, v1
	v_sub_f32_e32 v1, v46, v38
	v_add_f32_e32 v0, v66, v0
	v_exp_f32_e32 v71, v1
	v_sub_f32_e32 v1, v47, v38
	v_add_f32_e32 v0, v67, v0
	v_exp_f32_e32 v73, v1
	v_sub_f32_e32 v1, v48, v38
	v_add_f32_e32 v0, v68, v0
	v_exp_f32_e32 v70, v1
	v_sub_f32_e32 v1, v49, v38
	v_add_f32_e32 v0, v69, v0
	v_exp_f32_e32 v72, v1
	v_sub_f32_e32 v1, v54, v38
	v_add_f32_e32 v0, v71, v0
	v_exp_f32_e32 v58, v1
	v_sub_f32_e32 v1, v55, v38
	v_add_f32_e32 v0, v73, v0
	v_exp_f32_e32 v59, v1
	v_sub_f32_e32 v1, v56, v38
	v_add_f32_e32 v0, v70, v0
	v_exp_f32_e32 v60, v1
	v_sub_f32_e32 v1, v57, v38
	v_add_f32_e32 v0, v72, v0
	v_exp_f32_e32 v61, v1
	v_sub_f32_e32 v1, v34, v38
	v_add_f32_e32 v0, v58, v0
	v_exp_f32_e32 v63, v1
	v_sub_f32_e32 v1, v35, v38
	v_add_f32_e32 v0, v59, v0
	v_exp_f32_e32 v65, v1
	v_sub_f32_e32 v1, v62, v38
	v_add_f32_e32 v0, v60, v0
	v_exp_f32_e32 v62, v1
	v_sub_f32_e32 v1, v64, v38
	v_add_f32_e32 v0, v61, v0
	v_exp_f32_e32 v64, v1
	v_sub_f32_e32 v1, v102, v38
	v_add_f32_e32 v0, v63, v0
	v_exp_f32_e32 v50, v1
	v_sub_f32_e32 v1, v103, v38
	v_add_f32_e32 v0, v65, v0
	v_exp_f32_e32 v51, v1
	v_sub_f32_e32 v1, v104, v38
	v_add_f32_e32 v0, v62, v0
	v_exp_f32_e32 v52, v1
	v_sub_f32_e32 v1, v105, v38
	v_add_f32_e32 v0, v64, v0
	v_exp_f32_e32 v53, v1
	v_sub_f32_e32 v1, v106, v38
	v_add_f32_e32 v0, v50, v0
	v_exp_f32_e32 v55, v1
	v_sub_f32_e32 v1, v107, v38
	v_add_f32_e32 v0, v51, v0
	v_exp_f32_e32 v57, v1
	v_sub_f32_e32 v1, v108, v38
	v_add_f32_e32 v0, v52, v0
	v_exp_f32_e32 v54, v1
	v_sub_f32_e32 v1, v109, v38
	v_add_f32_e32 v0, v53, v0
	v_exp_f32_e32 v56, v1
	v_sub_f32_e32 v1, v110, v38
	v_add_f32_e32 v0, v55, v0
	v_exp_f32_e32 v42, v1
	v_sub_f32_e32 v1, v111, v38
	v_add_f32_e32 v0, v57, v0
	v_exp_f32_e32 v43, v1
	v_sub_f32_e32 v1, v112, v38
	v_add_f32_e32 v0, v54, v0
	v_exp_f32_e32 v44, v1
	v_sub_f32_e32 v1, v113, v38
	v_add_f32_e32 v0, v56, v0
	v_exp_f32_e32 v45, v1
	v_sub_f32_e32 v1, v114, v38
	v_add_f32_e32 v0, v42, v0
	v_exp_f32_e32 v47, v1
	v_sub_f32_e32 v1, v115, v38
	v_add_f32_e32 v0, v43, v0
	v_exp_f32_e32 v49, v1
	v_sub_f32_e32 v1, v116, v38
	v_add_f32_e32 v0, v44, v0
	v_exp_f32_e32 v46, v1
	v_sub_f32_e32 v1, v16, v38
	v_add_f32_e32 v0, v45, v0
	v_exp_f32_e32 v48, v1
	v_add_f32_e32 v0, v47, v0
	v_add_f32_e32 v0, v49, v0
	v_add_f32_e32 v0, v46, v0
	v_add_f32_e32 v0, v48, v0
	ds_bpermute_b32 v1, v100, v0
	v_cvt_pk_bf16_f32 v2, v8, v9
	v_cvt_pk_bf16_f32 v3, v10, v11
	s_waitcnt lgkmcnt(0)
	v_add_f32_e32 v39, v0, v1
	ds_bpermute_b32 v40, v101, v39
	v_lshrrev_b32_e32 v0, 2, v32
	v_or_b32_e32 v0, v83, v0
	v_lshlrev_b32_e32 v1, 3, v98
	v_mul_u32_u24_e32 v0, 0x120, v0
	v_and_b32_e32 v1, 24, v1
	v_add3_u32 v41, s27, v0, v1
	v_cvt_pk_bf16_f32 v0, v12, v13
	v_cvt_pk_bf16_f32 v1, v14, v15
	s_cbranch_vccnz .LBB0_1295
	ds_read_b64_tr_b16 v[4:5], v41
	ds_read_b64_tr_b16 v[8:9], v41 offset:32
	ds_read_b64_tr_b16 v[12:13], v41 offset:64
	ds_read_b64_tr_b16 v[16:17], v41 offset:96
	ds_read_b64_tr_b16 v[6:7], v41 offset:4608
	ds_read_b64_tr_b16 v[10:11], v41 offset:4640
	ds_read_b64_tr_b16 v[14:15], v41 offset:4672
	ds_read_b64_tr_b16 v[18:19], v41 offset:4704
	ds_read_b64_tr_b16 v[102:103], v41 offset:128
	ds_read_b64_tr_b16 v[106:107], v41 offset:160
	ds_read_b64_tr_b16 v[110:111], v41 offset:192
	ds_read_b64_tr_b16 v[114:115], v41 offset:224
	ds_read_b64_tr_b16 v[104:105], v41 offset:4736
	ds_read_b64_tr_b16 v[108:109], v41 offset:4768
	ds_read_b64_tr_b16 v[112:113], v41 offset:4800
	ds_read_b64_tr_b16 v[116:117], v41 offset:4832
	s_waitcnt lgkmcnt(11)
	v_mfma_f32_16x16x32_bf16 v[28:31], v[4:7], v[0:3], 0
	s_waitcnt lgkmcnt(10)
	v_mfma_f32_16x16x32_bf16 v[24:27], v[8:11], v[0:3], 0
	s_waitcnt lgkmcnt(9)
	v_mfma_f32_16x16x32_bf16 v[20:23], v[12:15], v[0:3], 0
	s_waitcnt lgkmcnt(8)
	v_mfma_f32_16x16x32_bf16 v[16:19], v[16:19], v[0:3], 0
	s_waitcnt lgkmcnt(3)
	v_mfma_f32_16x16x32_bf16 v[12:15], v[102:105], v[0:3], 0
	s_waitcnt lgkmcnt(2)
	v_mfma_f32_16x16x32_bf16 v[8:11], v[106:109], v[0:3], 0
	s_waitcnt lgkmcnt(1)
	v_mfma_f32_16x16x32_bf16 v[4:7], v[110:113], v[0:3], 0
	s_waitcnt lgkmcnt(0)
	v_mfma_f32_16x16x32_bf16 v[0:3], v[114:117], v[0:3], 0
	s_branch .LBB0_1296

.LBB0_1314:
	s_andn2_b64 vcc, exec, s[10:11]
	s_cbranch_vccnz .LBB0_1351
	s_lshl_b32 s12, s74, 12
	v_readlane_b32 s8, v252, 63
	s_lshl_b32 s77, s75, 7
	s_or_b32 s83, s8, s12
	s_and_b32 s8, s77, 0x180
	s_lshl_b32 s28, s8, 1
	v_readlane_b32 s8, v252, 15
	s_add_u32 s8, s8, s28
	v_readlane_b32 s9, v252, 16
	v_lshlrev_b32_e32 v0, 4, v99
	s_addc_u32 s9, s9, 0
	v_readlane_b32 s10, v252, 17
	v_and_b32_e32 v32, 0xf0, v0
	s_add_u32 s10, s10, s28
	v_readlane_b32 s11, v252, 18
	v_lshl_add_u64 v[16:17], s[8:9], 0, v[32:33]
	v_readlane_b32 s8, v253, 0
	s_addc_u32 s11, s11, 0
	v_ashrrev_i32_e32 v84, 4, v99
	s_add_i32 s8, s8, s12
	v_lshl_add_u64 v[18:19], s[10:11], 0, v[32:33]
	v_lshl_add_u32 v24, v84, 2, s8
	s_movk_i32 s8, 0x80
	v_readlane_b32 s10, v252, 61
	v_cmp_gt_i32_e32 vcc, s8, v84
	v_readlane_b32 s11, v252, 62
	v_mov_b32_e32 v25, s83
	s_and_b64 vcc, s[10:11], vcc
	v_cndmask_b32_e32 v2, v24, v25, vcc
	v_mad_i64_i32 v[0:1], s[8:9], v2, s70, v[16:17]
	v_mad_i64_i32 v[4:5], s[8:9], v2, s70, v[18:19]
	s_movk_i32 s8, 0x60
	s_nop 0
	v_cmp_gt_i32_e32 vcc, s8, v84
	v_add_u32_e32 v8, 0x80, v24
	s_and_b64 vcc, s[10:11], vcc
	v_cndmask_b32_e32 v10, v8, v25, vcc
	v_cmp_gt_i32_e32 vcc, 64, v84
	v_add_u32_e32 v20, 0x100, v24
	s_and_b64 vcc, s[10:11], vcc
	v_cndmask_b32_e32 v22, v20, v25, vcc
	v_mad_i64_i32 v[8:9], s[8:9], v10, s70, v[16:17]
	v_mad_i64_i32 v[12:13], s[8:9], v10, s70, v[18:19]
	v_mad_i64_i32 v[20:21], s[8:9], v22, s70, v[16:17]
	v_cmp_gt_i32_e32 vcc, 32, v84
	s_nop 0
	s_nop 0
	s_nop 0
	v_mad_i64_i32 v[22:23], s[8:9], v22, s70, v[18:19]
	v_add_u32_e32 v20, 0x180, v24
	s_and_b64 vcc, s[10:11], vcc
	v_cndmask_b32_e32 v22, v20, v25, vcc
	v_mad_i64_i32 v[20:21], s[8:9], v22, s70, v[16:17]
	v_cmp_gt_i32_e32 vcc, 0, v84
	v_mad_i64_i32 v[22:23], s[8:9], v22, s70, v[18:19]
	v_add_u32_e32 v20, 0x200, v24
	s_and_b64 vcc, s[10:11], vcc
	v_cndmask_b32_e32 v22, v20, v25, vcc
	v_mad_i64_i32 v[20:21], s[8:9], v22, s70, v[16:17]
	v_mad_i64_i32 v[22:23], s[8:9], v22, s70, v[18:19]
	s_movk_i32 s8, 0xffe0
	s_nop 0
	v_cmp_gt_i32_e32 vcc, s8, v84
	v_add_u32_e32 v20, 0x280, v24
	s_and_b64 vcc, s[10:11], vcc
	v_cndmask_b32_e32 v22, v20, v25, vcc
	v_mad_i64_i32 v[20:21], s[8:9], v22, s70, v[16:17]
	v_mad_i64_i32 v[22:23], s[8:9], v22, s70, v[18:19]
	s_movk_i32 s8, 0xffc0
	s_nop 0
	v_cmp_gt_i32_e32 vcc, s8, v84
	v_add_u32_e32 v20, 0x300, v24
	s_and_b64 vcc, s[10:11], vcc
	v_cndmask_b32_e32 v22, v20, v25, vcc
	v_mad_i64_i32 v[20:21], s[8:9], v22, s70, v[16:17]
	v_mad_i64_i32 v[22:23], s[8:9], v22, s70, v[18:19]
	s_movk_i32 s8, 0xffa0
	s_nop 0
	v_cmp_gt_i32_e32 vcc, s8, v84
	v_add_u32_e32 v20, 0x380, v24
	s_and_b64 vcc, s[10:11], vcc
	v_cndmask_b32_e32 v20, v20, v25, vcc
	v_mad_i64_i32 v[16:17], s[8:9], v20, s70, v[16:17]
	v_mad_i64_i32 v[18:19], s[8:9], v20, s70, v[18:19]
	v_readlane_b32 s8, v252, 23
	s_add_u32 s8, s8, s28
	v_readlane_b32 s9, v252, 24
	s_addc_u32 s9, s9, 0
	s_and_b32 s10, s76, 0xffffffc0
	v_lshlrev_b32_e32 v16, 2, v98
	s_add_i32 s10, s10, s83
	v_and_or_b32 v18, v16, 60, s10
	v_mov_b64_e32 v[16:17], s[8:9]
	v_mad_i64_i32 v[16:17], s[8:9], v18, s70, v[16:17]
	v_and_b32_e32 v82, 48, v99
	v_mov_b32_e32 v83, v33
	v_lshl_add_u64 v[28:29], v[16:17], 0, v[82:83]
	s_nop 0
	v_mul_lo_u32 v83, v84, s33
	v_add3_u32 v83, 0, v32, v83
	s_movk_i32 s8, 0x120
	v_add_u32_e32 v82, 0, v82
	v_mul_lo_u32 v0, v84, s8
	s_add_i32 s8, s73, -2
	v_add3_u32 v0, s27, v32, v0
	v_and_b32_e32 v32, 15, v99
	s_cmp_gt_u32 s8, -11
	v_mov_b32_e32 v0, 0
	s_cselect_b64 s[44:45], -1, 0
	s_cmp_lt_u32 s8, -10
	v_mad_u32_u24 v83, v32, s33, v82
	v_mov_b32_e32 v8, 0
	v_mov_b32_e32 v9, 0
	v_mov_b32_e32 v10, 0
	v_mov_b32_e32 v11, 0
	v_mov_b32_e32 v12, 0
	v_mov_b32_e32 v13, 0
	v_mov_b32_e32 v14, 0
	v_mov_b32_e32 v15, 0
	s_waitcnt lgkmcnt(0)
	s_cselect_b32 s49, 1, 0
	v_mov_b64_e32 v[16:17], v[228:229]
	v_mov_b64_e32 v[18:19], v[230:231]
	v_mov_b64_e32 v[20:21], v[232:233]
	v_mov_b64_e32 v[22:23], v[234:235]
	v_mov_b64_e32 v[24:25], v[236:237]
	v_mov_b64_e32 v[26:27], v[238:239]
	v_mov_b64_e32 v[28:29], v[240:241]
	v_mov_b64_e32 v[30:31], v[242:243]
	s_add_u32 s48, s72, 1
	s_cmp_lt_u32 s48, 8
	s_cbranch_scc1 .Lpf_issue

.LBB0_1331:
	v_lshl_or_b32 v82, s73, 4, v32
	v_readlane_b32 s8, v252, 61
	s_nop 0
	v_max_i32_e32 v16, 0x80, v82
	v_readlane_b32 s9, v252, 62
	v_lshrrev_b32_e32 v18, 2, v98
	v_add_u32_e32 v17, 0x80, v82
	v_cndmask_b32_e64 v16, v82, v16, s[8:9]
	v_and_b32_e32 v83, 12, v18
	v_cmp_lt_i32_e32 vcc, v83, v16
	v_cmp_gt_i32_e64 s[10:11], v83, v17
	s_or_b64 vcc, vcc, s[10:11]
	v_or_b32_e32 v19, 1, v83
	v_cndmask_b32_e32 v12, v12, v225, vcc
	v_cmp_lt_i32_e32 vcc, v19, v16
	v_cmp_ge_i32_e64 s[10:11], v83, v17
	s_or_b64 vcc, vcc, s[10:11]
	v_or_b32_e32 v19, 2, v83
	v_cndmask_b32_e32 v13, v13, v225, vcc
	v_cmp_lt_i32_e32 vcc, v19, v16
	v_cmp_gt_i32_e64 s[10:11], v19, v17
	s_or_b64 vcc, vcc, s[10:11]
	v_or_b32_e32 v19, 3, v18
	v_cndmask_b32_e32 v14, v14, v225, vcc
	v_cmp_lt_i32_e32 vcc, v19, v16
	v_cmp_gt_i32_e64 s[10:11], v19, v17
	s_or_b64 vcc, vcc, s[10:11]
	v_or_b32_e32 v19, 16, v83
	v_cndmask_b32_e32 v15, v15, v225, vcc
	v_cmp_lt_i32_e32 vcc, v19, v16
	v_cmp_gt_i32_e64 s[10:11], v19, v17
	s_or_b64 vcc, vcc, s[10:11]
	v_or_b32_e32 v19, 17, v83
	v_cndmask_b32_e32 v8, v8, v225, vcc
	v_cmp_lt_i32_e32 vcc, v19, v16
	v_cmp_gt_i32_e64 s[10:11], v19, v17
	s_or_b64 vcc, vcc, s[10:11]
	v_or_b32_e32 v19, 18, v83
	v_cndmask_b32_e32 v9, v9, v225, vcc
	v_cmp_lt_i32_e32 vcc, v19, v16
	v_cmp_gt_i32_e64 s[10:11], v19, v17
	s_or_b64 vcc, vcc, s[10:11]
	v_or_b32_e32 v19, 19, v18
	v_cndmask_b32_e32 v10, v10, v225, vcc
	v_cmp_lt_i32_e32 vcc, v19, v16
	v_cmp_gt_i32_e64 s[10:11], v19, v17
	s_or_b64 vcc, vcc, s[10:11]
	v_or_b32_e32 v19, 32, v83
	v_cndmask_b32_e32 v11, v11, v225, vcc
	v_cmp_lt_i32_e32 vcc, v19, v16
	v_cmp_gt_i32_e64 s[10:11], v19, v17
	s_or_b64 vcc, vcc, s[10:11]
	v_or_b32_e32 v20, 33, v83
	v_cndmask_b32_e32 v19, v42, v225, vcc
	v_cmp_lt_i32_e32 vcc, v20, v16
	v_cmp_gt_i32_e64 s[10:11], v20, v17
	s_or_b64 vcc, vcc, s[10:11]
	v_or_b32_e32 v21, 34, v83
	v_cndmask_b32_e32 v20, v43, v225, vcc
	v_cmp_lt_i32_e32 vcc, v21, v16
	v_cmp_gt_i32_e64 s[10:11], v21, v17
	s_or_b64 vcc, vcc, s[10:11]
	v_or_b32_e32 v22, 35, v18
	v_cndmask_b32_e32 v21, v44, v225, vcc
	v_cmp_lt_i32_e32 vcc, v22, v16
	v_cmp_gt_i32_e64 s[10:11], v22, v17
	s_or_b64 vcc, vcc, s[10:11]
	v_or_b32_e32 v23, 48, v83
	v_cndmask_b32_e32 v22, v45, v225, vcc
	v_cmp_lt_i32_e32 vcc, v23, v16
	v_cmp_gt_i32_e64 s[10:11], v23, v17
	s_or_b64 vcc, vcc, s[10:11]
	v_or_b32_e32 v23, 49, v83
	v_cndmask_b32_e32 v0, v0, v225, vcc
	v_cmp_lt_i32_e32 vcc, v23, v16
	v_cmp_gt_i32_e64 s[10:11], v23, v17
	s_or_b64 vcc, vcc, s[10:11]
	v_or_b32_e32 v23, 50, v83
	v_cndmask_b32_e32 v1, v1, v225, vcc
	v_cmp_lt_i32_e32 vcc, v23, v16
	v_cmp_gt_i32_e64 s[10:11], v23, v17
	s_or_b64 vcc, vcc, s[10:11]
	v_or_b32_e32 v23, 51, v18
	v_cndmask_b32_e32 v2, v2, v225, vcc
	v_cmp_lt_i32_e32 vcc, v23, v16
	v_cmp_gt_i32_e64 s[10:11], v23, v17
	s_or_b64 vcc, vcc, s[10:11]
	v_or_b32_e32 v23, 64, v83
	v_cndmask_b32_e32 v3, v3, v225, vcc
	v_cmp_lt_i32_e32 vcc, v23, v16
	v_cmp_gt_i32_e64 s[10:11], v23, v17
	s_or_b64 vcc, vcc, s[10:11]
	v_or_b32_e32 v24, 0x41, v83
	v_cndmask_b32_e32 v23, v46, v225, vcc
	v_cmp_lt_i32_e32 vcc, v24, v16
	v_cmp_gt_i32_e64 s[10:11], v24, v17
	s_or_b64 vcc, vcc, s[10:11]
	v_or_b32_e32 v25, 0x42, v83
	v_cndmask_b32_e32 v24, v47, v225, vcc
	v_cmp_lt_i32_e32 vcc, v25, v16
	v_cmp_gt_i32_e64 s[10:11], v25, v17
	s_or_b64 vcc, vcc, s[10:11]
	v_or_b32_e32 v26, 0x43, v18
	v_cndmask_b32_e32 v25, v48, v225, vcc
	v_cmp_lt_i32_e32 vcc, v26, v16
	v_cmp_gt_i32_e64 s[10:11], v26, v17
	s_or_b64 vcc, vcc, s[10:11]
	v_or_b32_e32 v27, 0x50, v83
	v_cndmask_b32_e32 v26, v49, v225, vcc
	v_cmp_lt_i32_e32 vcc, v27, v16
	v_cmp_gt_i32_e64 s[10:11], v27, v17
	s_or_b64 vcc, vcc, s[10:11]
	v_or_b32_e32 v28, 0x51, v83
	v_cndmask_b32_e32 v27, v38, v225, vcc
	v_cmp_lt_i32_e32 vcc, v28, v16
	v_cmp_gt_i32_e64 s[10:11], v28, v17
	s_or_b64 vcc, vcc, s[10:11]
	v_or_b32_e32 v29, 0x52, v83
	v_cndmask_b32_e32 v28, v39, v225, vcc
	v_cmp_lt_i32_e32 vcc, v29, v16
	v_cmp_gt_i32_e64 s[10:11], v29, v17
	s_or_b64 vcc, vcc, s[10:11]
	v_or_b32_e32 v30, 0x53, v18
	v_cndmask_b32_e32 v29, v40, v225, vcc
	v_cmp_lt_i32_e32 vcc, v30, v16
	v_cmp_gt_i32_e64 s[10:11], v30, v17
	s_or_b64 vcc, vcc, s[10:11]
	v_or_b32_e32 v31, 0x60, v83
	v_cndmask_b32_e32 v30, v41, v225, vcc
	v_cmp_lt_i32_e32 vcc, v31, v16
	v_cmp_gt_i32_e64 s[10:11], v31, v17
	s_or_b64 vcc, vcc, s[10:11]
	v_or_b32_e32 v38, 0x61, v83
	v_cndmask_b32_e32 v31, v58, v225, vcc
	v_cmp_lt_i32_e32 vcc, v38, v16
	v_cmp_gt_i32_e64 s[10:11], v38, v17
	s_or_b64 vcc, vcc, s[10:11]
	v_or_b32_e32 v38, 0x62, v83
	v_cndmask_b32_e32 v39, v59, v225, vcc
	v_cmp_lt_i32_e32 vcc, v38, v16
	v_cmp_gt_i32_e64 s[10:11], v38, v17
	s_or_b64 vcc, vcc, s[10:11]
	v_or_b32_e32 v38, 0x63, v18
	v_cndmask_b32_e32 v40, v60, v225, vcc
	v_cmp_lt_i32_e32 vcc, v38, v16
	v_cmp_gt_i32_e64 s[10:11], v38, v17
	s_or_b64 vcc, vcc, s[10:11]
	v_or_b32_e32 v38, 0x70, v83
	v_cndmask_b32_e32 v41, v61, v225, vcc
	v_cmp_lt_i32_e32 vcc, v38, v16
	v_cmp_gt_i32_e64 s[10:11], v38, v17
	s_or_b64 vcc, vcc, s[10:11]
	v_or_b32_e32 v38, 0x71, v83
	v_cndmask_b32_e32 v4, v4, v225, vcc
	v_cmp_lt_i32_e32 vcc, v38, v16
	v_cmp_gt_i32_e64 s[10:11], v38, v17
	s_or_b64 vcc, vcc, s[10:11]
	v_or_b32_e32 v38, 0x72, v83
	v_cndmask_b32_e32 v5, v5, v225, vcc
	v_cmp_lt_i32_e32 vcc, v38, v16
	v_cmp_gt_i32_e64 s[10:11], v38, v17
	s_or_b64 vcc, vcc, s[10:11]
	v_or_b32_e32 v38, 0x73, v18
	v_cndmask_b32_e32 v6, v6, v225, vcc
	v_cmp_lt_i32_e32 vcc, v38, v16
	v_cmp_gt_i32_e64 s[10:11], v38, v17
	s_or_b64 vcc, vcc, s[10:11]
	v_or_b32_e32 v38, 0x80, v83
	v_cndmask_b32_e32 v7, v7, v225, vcc
	v_cmp_lt_i32_e32 vcc, v38, v16
	v_cmp_gt_i32_e64 s[10:11], v83, v82
	s_or_b64 vcc, vcc, s[10:11]
	v_or_b32_e32 v38, 0x81, v83
	v_cndmask_b32_e32 v42, v62, v225, vcc
	v_cmp_lt_i32_e32 vcc, v38, v16
	v_cmp_gt_i32_e64 s[10:11], v38, v17
	s_or_b64 vcc, vcc, s[10:11]
	v_or_b32_e32 v38, 0x82, v83
	v_cndmask_b32_e32 v43, v63, v225, vcc
	v_cmp_lt_i32_e32 vcc, v38, v16
	v_cmp_gt_i32_e64 s[10:11], v38, v17
	s_or_b64 vcc, vcc, s[10:11]
	v_or_b32_e32 v38, 0x83, v18
	v_cndmask_b32_e32 v44, v64, v225, vcc
	v_cmp_lt_i32_e32 vcc, v38, v16
	v_cmp_gt_i32_e64 s[10:11], v38, v17
	s_or_b64 vcc, vcc, s[10:11]
	v_or_b32_e32 v38, 0x90, v83
	v_cndmask_b32_e32 v45, v65, v225, vcc
	v_cmp_lt_i32_e32 vcc, v38, v16
	v_cmp_gt_i32_e64 s[10:11], v38, v17
	s_or_b64 vcc, vcc, s[10:11]
	v_or_b32_e32 v38, 0x91, v83
	v_cndmask_b32_e32 v46, v54, v225, vcc
	v_cmp_lt_i32_e32 vcc, v38, v16
	v_cmp_gt_i32_e64 s[10:11], v38, v17
	s_or_b64 vcc, vcc, s[10:11]
	v_or_b32_e32 v38, 0x92, v83
	v_cndmask_b32_e32 v47, v55, v225, vcc
	v_cmp_lt_i32_e32 vcc, v38, v16
	v_cmp_gt_i32_e64 s[10:11], v38, v17
	s_or_b64 vcc, vcc, s[10:11]
	v_or_b32_e32 v38, 0x93, v18
	v_cndmask_b32_e32 v48, v56, v225, vcc
	v_cmp_lt_i32_e32 vcc, v38, v16
	v_cmp_gt_i32_e64 s[10:11], v38, v17
	s_or_b64 vcc, vcc, s[10:11]
	v_or_b32_e32 v38, 0xa0, v83
	v_cndmask_b32_e32 v49, v57, v225, vcc
	v_cmp_lt_i32_e32 vcc, v38, v16
	v_cmp_gt_i32_e64 s[10:11], v38, v17
	s_or_b64 vcc, vcc, s[10:11]
	v_or_b32_e32 v38, 0xa1, v83
	v_cndmask_b32_e32 v54, v70, v225, vcc
	v_cmp_lt_i32_e32 vcc, v38, v16
	v_cmp_gt_i32_e64 s[10:11], v38, v17
	s_or_b64 vcc, vcc, s[10:11]
	v_or_b32_e32 v38, 0xa2, v83
	v_cndmask_b32_e32 v55, v71, v225, vcc
	v_cmp_lt_i32_e32 vcc, v38, v16
	v_cmp_gt_i32_e64 s[10:11], v38, v17
	s_or_b64 vcc, vcc, s[10:11]
	v_or_b32_e32 v38, 0xa3, v18
	v_cndmask_b32_e32 v56, v72, v225, vcc
	v_cmp_lt_i32_e32 vcc, v38, v16
	v_cmp_gt_i32_e64 s[10:11], v38, v17
	s_or_b64 vcc, vcc, s[10:11]
	v_or_b32_e32 v38, 0xb0, v83
	v_cndmask_b32_e32 v57, v73, v225, vcc
	v_cmp_lt_i32_e32 vcc, v38, v16
	v_cmp_gt_i32_e64 s[10:11], v38, v17
	s_or_b64 vcc, vcc, s[10:11]
	v_or_b32_e32 v38, 0xb1, v83
	v_cndmask_b32_e32 v34, v34, v225, vcc
	v_cmp_lt_i32_e32 vcc, v38, v16
	v_cmp_gt_i32_e64 s[10:11], v38, v17
	s_or_b64 vcc, vcc, s[10:11]
	v_or_b32_e32 v38, 0xb2, v83
	v_cndmask_b32_e32 v35, v35, v225, vcc
	v_cmp_lt_i32_e32 vcc, v38, v16
	v_cmp_gt_i32_e64 s[10:11], v38, v17
	s_or_b64 vcc, vcc, s[10:11]
	v_cndmask_b32_e32 v62, v36, v225, vcc
	v_or_b32_e32 v36, 0xb3, v18
	v_cmp_lt_i32_e32 vcc, v36, v16
	v_cmp_gt_i32_e64 s[10:11], v36, v17
	s_or_b64 vcc, vcc, s[10:11]
	v_or_b32_e32 v36, 0xc0, v83
	v_cndmask_b32_e32 v64, v37, v225, vcc
	v_cmp_lt_i32_e32 vcc, v36, v16
	v_cmp_gt_i32_e64 s[10:11], v36, v17
	s_or_b64 vcc, vcc, s[10:11]
	v_or_b32_e32 v36, 0xc1, v83
	v_cndmask_b32_e32 v102, v74, v225, vcc
	v_cmp_lt_i32_e32 vcc, v36, v16
	v_cmp_gt_i32_e64 s[10:11], v36, v17
	s_or_b64 vcc, vcc, s[10:11]
	v_or_b32_e32 v36, 0xc2, v83
	v_cndmask_b32_e32 v103, v75, v225, vcc
	v_cmp_lt_i32_e32 vcc, v36, v16
	v_cmp_gt_i32_e64 s[10:11], v36, v17
	s_or_b64 vcc, vcc, s[10:11]
	v_or_b32_e32 v36, 0xc3, v18
	v_cndmask_b32_e32 v104, v76, v225, vcc
	v_cmp_lt_i32_e32 vcc, v36, v16
	v_cmp_gt_i32_e64 s[10:11], v36, v17
	s_or_b64 vcc, vcc, s[10:11]
	v_or_b32_e32 v36, 0xd0, v83
	v_cndmask_b32_e32 v105, v77, v225, vcc
	v_cmp_lt_i32_e32 vcc, v36, v16
	v_cmp_gt_i32_e64 s[10:11], v36, v17
	s_or_b64 vcc, vcc, s[10:11]
	v_or_b32_e32 v36, 0xd1, v83
	v_cndmask_b32_e32 v106, v66, v225, vcc
	v_cmp_lt_i32_e32 vcc, v36, v16
	v_cmp_gt_i32_e64 s[10:11], v36, v17
	s_or_b64 vcc, vcc, s[10:11]
	v_or_b32_e32 v36, 0xd2, v83
	v_cndmask_b32_e32 v107, v67, v225, vcc
	v_cmp_lt_i32_e32 vcc, v36, v16
	v_cmp_gt_i32_e64 s[10:11], v36, v17
	s_or_b64 vcc, vcc, s[10:11]
	v_or_b32_e32 v36, 0xd3, v18
	v_cndmask_b32_e32 v108, v68, v225, vcc
	v_cmp_lt_i32_e32 vcc, v36, v16
	v_cmp_gt_i32_e64 s[10:11], v36, v17
	s_or_b64 vcc, vcc, s[10:11]
	v_or_b32_e32 v36, 0xe0, v83
	v_cndmask_b32_e32 v109, v69, v225, vcc
	v_cmp_lt_i32_e32 vcc, v36, v16
	v_cmp_gt_i32_e64 s[10:11], v36, v17
	s_or_b64 vcc, vcc, s[10:11]
	v_or_b32_e32 v36, 0xe1, v83
	v_cndmask_b32_e32 v110, v78, v225, vcc
	v_cmp_lt_i32_e32 vcc, v36, v16
	v_cmp_gt_i32_e64 s[10:11], v36, v17
	s_or_b64 vcc, vcc, s[10:11]
	v_or_b32_e32 v36, 0xe2, v83
	v_cndmask_b32_e32 v111, v79, v225, vcc
	v_cmp_lt_i32_e32 vcc, v36, v16
	v_cmp_gt_i32_e64 s[10:11], v36, v17
	s_or_b64 vcc, vcc, s[10:11]
	v_or_b32_e32 v36, 0xe3, v18
	v_cndmask_b32_e32 v112, v80, v225, vcc
	v_cmp_lt_i32_e32 vcc, v36, v16
	v_cmp_gt_i32_e64 s[10:11], v36, v17
	s_or_b64 vcc, vcc, s[10:11]
	v_or_b32_e32 v36, 0xf0, v83
	v_cndmask_b32_e32 v113, v81, v225, vcc
	v_cmp_lt_i32_e32 vcc, v36, v16
	v_cmp_gt_i32_e64 s[10:11], v36, v17
	s_or_b64 vcc, vcc, s[10:11]
	v_or_b32_e32 v36, 0xf1, v83
	v_cndmask_b32_e32 v114, v50, v225, vcc
	v_cmp_lt_i32_e32 vcc, v36, v16
	v_cmp_gt_i32_e64 s[10:11], v36, v17
	s_or_b64 vcc, vcc, s[10:11]
	v_or_b32_e32 v36, 0xf2, v83
	v_cndmask_b32_e32 v115, v51, v225, vcc
	v_cmp_lt_i32_e32 vcc, v36, v16
	v_cmp_gt_i32_e64 s[10:11], v36, v17
	s_or_b64 vcc, vcc, s[10:11]
	v_or_b32_e32 v18, 0xf3, v18
	v_cndmask_b32_e32 v116, v52, v225, vcc
	v_cmp_lt_i32_e32 vcc, v18, v16
	v_cmp_gt_i32_e64 s[10:11], v18, v17
	v_max_f32_e32 v17, v13, v13
	v_max_f32_e32 v18, v12, v12
	v_max_f32_e32 v17, v18, v17
	v_max_f32_e32 v18, v15, v15
	v_max_f32_e32 v36, v14, v14
	v_max_f32_e32 v18, v36, v18
	s_mov_b32 s8, 0xff61b1e6
	v_max3_f32 v17, v17, v18, s8
	v_max_f32_e32 v18, v9, v9
	v_max_f32_e32 v36, v8, v8
	v_max_f32_e32 v18, v36, v18
	v_max_f32_e32 v36, v11, v11
	v_max_f32_e32 v37, v10, v10
	v_max_f32_e32 v36, v37, v36
	v_max3_f32 v17, v18, v36, v17
	v_max_f32_e32 v18, v20, v20
	v_max_f32_e32 v36, v19, v19
	v_max_f32_e32 v18, v36, v18
	v_max_f32_e32 v36, v22, v22
	v_max_f32_e32 v37, v21, v21
	v_max_f32_e32 v36, v37, v36
	v_max3_f32 v17, v18, v36, v17
	v_max_f32_e32 v18, v1, v1
	v_max_f32_e32 v36, v0, v0
	v_max_f32_e32 v18, v36, v18
	v_max_f32_e32 v36, v3, v3
	v_max_f32_e32 v37, v2, v2
	v_max_f32_e32 v36, v37, v36
	v_max3_f32 v17, v18, v36, v17
	v_max_f32_e32 v18, v24, v24
	v_max_f32_e32 v36, v23, v23
	v_max_f32_e32 v18, v36, v18
	v_max_f32_e32 v36, v26, v26
	v_max_f32_e32 v37, v25, v25
	v_max_f32_e32 v36, v37, v36
	v_max3_f32 v17, v18, v36, v17
	v_max_f32_e32 v18, v28, v28
	v_max_f32_e32 v36, v27, v27
	v_max_f32_e32 v18, v36, v18
	v_max_f32_e32 v36, v30, v30
	v_max_f32_e32 v37, v29, v29
	v_max_f32_e32 v36, v37, v36
	v_max3_f32 v17, v18, v36, v17
	v_max_f32_e32 v18, v39, v39
	v_max_f32_e32 v36, v31, v31
	v_max_f32_e32 v18, v36, v18
	v_max_f32_e32 v36, v41, v41
	v_max_f32_e32 v37, v40, v40
	v_max_f32_e32 v36, v37, v36
	v_max3_f32 v17, v18, v36, v17
	v_max_f32_e32 v18, v5, v5
	v_max_f32_e32 v36, v4, v4
	v_max_f32_e32 v18, v36, v18
	v_max_f32_e32 v36, v7, v7
	v_max_f32_e32 v37, v6, v6
	v_max_f32_e32 v36, v37, v36
	v_max3_f32 v17, v18, v36, v17
	v_max_f32_e32 v18, v43, v43
	v_max_f32_e32 v36, v42, v42
	v_max_f32_e32 v18, v36, v18
	v_max_f32_e32 v36, v45, v45
	v_max_f32_e32 v37, v44, v44
	v_max_f32_e32 v36, v37, v36
	v_max3_f32 v17, v18, v36, v17
	v_max_f32_e32 v18, v47, v47
	v_max_f32_e32 v36, v46, v46
	v_max_f32_e32 v18, v36, v18
	v_max_f32_e32 v36, v49, v49
	v_max_f32_e32 v37, v48, v48
	v_max_f32_e32 v36, v37, v36
	v_max3_f32 v17, v18, v36, v17
	v_max_f32_e32 v18, v55, v55
	v_max_f32_e32 v36, v54, v54
	v_max_f32_e32 v18, v36, v18
	v_max_f32_e32 v36, v57, v57
	v_max_f32_e32 v37, v56, v56
	v_max_f32_e32 v36, v37, v36
	v_max3_f32 v17, v18, v36, v17
	v_max_f32_e32 v18, v35, v35
	v_max_f32_e32 v36, v34, v34
	v_max_f32_e32 v18, v36, v18
	v_max_f32_e32 v36, v64, v64
	v_max_f32_e32 v37, v62, v62
	v_max_f32_e32 v36, v37, v36
	v_max3_f32 v17, v18, v36, v17
	v_max_f32_e32 v18, v103, v103
	v_max_f32_e32 v36, v102, v102
	v_max_f32_e32 v18, v36, v18
	v_max_f32_e32 v36, v105, v105
	v_max_f32_e32 v37, v104, v104
	v_max_f32_e32 v36, v37, v36
	v_max3_f32 v17, v18, v36, v17
	v_max_f32_e32 v18, v107, v107
	v_max_f32_e32 v36, v106, v106
	v_max_f32_e32 v18, v36, v18
	v_max_f32_e32 v36, v109, v109
	v_max_f32_e32 v37, v108, v108
	v_max_f32_e32 v36, v37, v36
	v_max3_f32 v17, v18, v36, v17
	v_max_f32_e32 v18, v111, v111
	v_max_f32_e32 v36, v110, v110
	v_max_f32_e32 v18, v36, v18
	v_max_f32_e32 v36, v113, v113
	v_max_f32_e32 v37, v112, v112
	s_or_b64 vcc, vcc, s[10:11]
	v_max_f32_e32 v36, v37, v36
	v_cndmask_b32_e32 v16, v53, v225, vcc
	v_max3_f32 v17, v18, v36, v17
	v_max_f32_e32 v18, v115, v115
	v_max_f32_e32 v36, v114, v114
	v_max_f32_e32 v18, v36, v18
	v_max_f32_e32 v36, v16, v16
	v_max_f32_e32 v37, v116, v116
	v_max_f32_e32 v36, v37, v36
	v_max3_f32 v17, v18, v36, v17
	ds_bpermute_b32 v18, v100, v17
	s_andn2_b64 vcc, exec, s[44:45]
	s_waitcnt lgkmcnt(0)
	v_max_f32_e32 v18, v18, v18
	v_max_f32_e32 v17, v17, v18
	ds_bpermute_b32 v18, v101, v17
	s_waitcnt lgkmcnt(0)
	v_max_f32_e32 v18, v18, v18
	v_max_f32_e32 v38, v17, v18
	v_sub_f32_e32 v12, v12, v38
	v_exp_f32_e32 v12, v12
	v_sub_f32_e32 v13, v13, v38
	v_exp_f32_e32 v13, v13
	v_sub_f32_e32 v14, v14, v38
	v_exp_f32_e32 v14, v14
	v_sub_f32_e32 v15, v15, v38
	v_exp_f32_e32 v15, v15
	v_sub_f32_e32 v8, v8, v38
	v_add_f32_e32 v17, 0, v12
	v_exp_f32_e32 v8, v8
	v_sub_f32_e32 v9, v9, v38
	v_add_f32_e32 v17, v13, v17
	v_exp_f32_e32 v9, v9
	v_sub_f32_e32 v10, v10, v38
	v_add_f32_e32 v17, v14, v17
	v_exp_f32_e32 v10, v10
	v_sub_f32_e32 v11, v11, v38
	v_add_f32_e32 v17, v15, v17
	v_exp_f32_e32 v11, v11
	v_sub_f32_e32 v18, v19, v38
	v_add_f32_e32 v17, v8, v17
	v_exp_f32_e32 v36, v18
	v_sub_f32_e32 v18, v20, v38
	v_add_f32_e32 v17, v9, v17
	v_exp_f32_e32 v37, v18
	v_sub_f32_e32 v18, v21, v38
	v_add_f32_e32 v17, v10, v17
	v_exp_f32_e32 v92, v18
	v_sub_f32_e32 v18, v22, v38
	v_add_f32_e32 v17, v11, v17
	v_exp_f32_e32 v93, v18
	v_sub_f32_e32 v0, v0, v38
	v_add_f32_e32 v17, v36, v17
	v_exp_f32_e32 v95, v0
	v_sub_f32_e32 v0, v1, v38
	v_add_f32_e32 v17, v37, v17
	v_exp_f32_e32 v97, v0
	v_sub_f32_e32 v0, v2, v38
	v_add_f32_e32 v17, v92, v17
	v_exp_f32_e32 v94, v0
	v_sub_f32_e32 v0, v3, v38
	v_add_f32_e32 v17, v93, v17
	v_exp_f32_e32 v96, v0
	v_sub_f32_e32 v1, v23, v38
	v_add_f32_e32 v0, v95, v17
	v_exp_f32_e32 v84, v1
	v_sub_f32_e32 v1, v24, v38
	v_add_f32_e32 v0, v97, v0
	v_exp_f32_e32 v85, v1
	v_sub_f32_e32 v1, v25, v38
	v_add_f32_e32 v0, v94, v0
	v_exp_f32_e32 v86, v1
	v_sub_f32_e32 v1, v26, v38
	v_add_f32_e32 v0, v96, v0
	v_exp_f32_e32 v87, v1
	v_sub_f32_e32 v1, v27, v38
	v_add_f32_e32 v0, v84, v0
	v_exp_f32_e32 v89, v1
	v_sub_f32_e32 v1, v28, v38
	v_add_f32_e32 v0, v85, v0
	v_exp_f32_e32 v91, v1
	v_sub_f32_e32 v1, v29, v38
	v_add_f32_e32 v0, v86, v0
	v_exp_f32_e32 v88, v1
	v_sub_f32_e32 v1, v30, v38
	v_add_f32_e32 v0, v87, v0
	v_exp_f32_e32 v90, v1
	v_sub_f32_e32 v1, v31, v38
	v_add_f32_e32 v0, v89, v0
	v_exp_f32_e32 v74, v1
	v_sub_f32_e32 v1, v39, v38
	v_add_f32_e32 v0, v91, v0
	v_exp_f32_e32 v75, v1
	v_sub_f32_e32 v1, v40, v38
	v_add_f32_e32 v0, v88, v0
	v_exp_f32_e32 v76, v1
	v_sub_f32_e32 v1, v41, v38
	v_add_f32_e32 v0, v90, v0
	v_exp_f32_e32 v77, v1
	v_sub_f32_e32 v1, v4, v38
	v_add_f32_e32 v0, v74, v0
	v_exp_f32_e32 v79, v1
	v_sub_f32_e32 v1, v5, v38
	v_add_f32_e32 v0, v75, v0
	v_exp_f32_e32 v81, v1
	v_sub_f32_e32 v1, v6, v38
	v_add_f32_e32 v0, v76, v0
	v_exp_f32_e32 v78, v1
	v_sub_f32_e32 v1, v7, v38
	v_add_f32_e32 v0, v77, v0
	v_exp_f32_e32 v80, v1
	v_sub_f32_e32 v1, v42, v38
	v_add_f32_e32 v0, v79, v0
	v_exp_f32_e32 v66, v1
	v_sub_f32_e32 v1, v43, v38
	v_add_f32_e32 v0, v81, v0
	v_exp_f32_e32 v67, v1
	v_sub_f32_e32 v1, v44, v38
	v_add_f32_e32 v0, v78, v0
	v_exp_f32_e32 v68, v1
	v_sub_f32_e32 v1, v45, v38
	v_add_f32_e32 v0, v80, v0
	v_exp_f32_e32 v69, v1
	v_sub_f32_e32 v1, v46, v38
	v_add_f32_e32 v0, v66, v0
	v_exp_f32_e32 v71, v1
	v_sub_f32_e32 v1, v47, v38
	v_add_f32_e32 v0, v67, v0
	v_exp_f32_e32 v73, v1
	v_sub_f32_e32 v1, v48, v38
	v_add_f32_e32 v0, v68, v0
	v_exp_f32_e32 v70, v1
	v_sub_f32_e32 v1, v49, v38
	v_add_f32_e32 v0, v69, v0
	v_exp_f32_e32 v72, v1
	v_sub_f32_e32 v1, v54, v38
	v_add_f32_e32 v0, v71, v0
	v_exp_f32_e32 v58, v1
	v_sub_f32_e32 v1, v55, v38
	v_add_f32_e32 v0, v73, v0
	v_exp_f32_e32 v59, v1
	v_sub_f32_e32 v1, v56, v38
	v_add_f32_e32 v0, v70, v0
	v_exp_f32_e32 v60, v1
	v_sub_f32_e32 v1, v57, v38
	v_add_f32_e32 v0, v72, v0
	v_exp_f32_e32 v61, v1
	v_sub_f32_e32 v1, v34, v38
	v_add_f32_e32 v0, v58, v0
	v_exp_f32_e32 v63, v1
	v_sub_f32_e32 v1, v35, v38
	v_add_f32_e32 v0, v59, v0
	v_exp_f32_e32 v65, v1
	v_sub_f32_e32 v1, v62, v38
	v_add_f32_e32 v0, v60, v0
	v_exp_f32_e32 v62, v1
	v_sub_f32_e32 v1, v64, v38
	v_add_f32_e32 v0, v61, v0
	v_exp_f32_e32 v64, v1
	v_sub_f32_e32 v1, v102, v38
	v_add_f32_e32 v0, v63, v0
	v_exp_f32_e32 v50, v1
	v_sub_f32_e32 v1, v103, v38
	v_add_f32_e32 v0, v65, v0
	v_exp_f32_e32 v51, v1
	v_sub_f32_e32 v1, v104, v38
	v_add_f32_e32 v0, v62, v0
	v_exp_f32_e32 v52, v1
	v_sub_f32_e32 v1, v105, v38
	v_add_f32_e32 v0, v64, v0
	v_exp_f32_e32 v53, v1
	v_sub_f32_e32 v1, v106, v38
	v_add_f32_e32 v0, v50, v0
	v_exp_f32_e32 v55, v1
	v_sub_f32_e32 v1, v107, v38
	v_add_f32_e32 v0, v51, v0
	v_exp_f32_e32 v57, v1
	v_sub_f32_e32 v1, v108, v38
	v_add_f32_e32 v0, v52, v0
	v_exp_f32_e32 v54, v1
	v_sub_f32_e32 v1, v109, v38
	v_add_f32_e32 v0, v53, v0
	v_exp_f32_e32 v56, v1
	v_sub_f32_e32 v1, v110, v38
	v_add_f32_e32 v0, v55, v0
	v_exp_f32_e32 v42, v1
	v_sub_f32_e32 v1, v111, v38
	v_add_f32_e32 v0, v57, v0
	v_exp_f32_e32 v43, v1
	v_sub_f32_e32 v1, v112, v38
	v_add_f32_e32 v0, v54, v0
	v_exp_f32_e32 v44, v1
	v_sub_f32_e32 v1, v113, v38
	v_add_f32_e32 v0, v56, v0
	v_exp_f32_e32 v45, v1
	v_sub_f32_e32 v1, v114, v38
	v_add_f32_e32 v0, v42, v0
	v_exp_f32_e32 v47, v1
	v_sub_f32_e32 v1, v115, v38
	v_add_f32_e32 v0, v43, v0
	v_exp_f32_e32 v49, v1
	v_sub_f32_e32 v1, v116, v38
	v_add_f32_e32 v0, v44, v0
	v_exp_f32_e32 v46, v1
	v_sub_f32_e32 v1, v16, v38
	v_add_f32_e32 v0, v45, v0
	v_exp_f32_e32 v48, v1
	v_add_f32_e32 v0, v47, v0
	v_add_f32_e32 v0, v49, v0
	v_add_f32_e32 v0, v46, v0
	v_add_f32_e32 v0, v48, v0
	ds_bpermute_b32 v1, v100, v0
	v_cvt_pk_bf16_f32 v2, v8, v9
	v_cvt_pk_bf16_f32 v3, v10, v11
	s_waitcnt lgkmcnt(0)
	v_add_f32_e32 v39, v0, v1
	ds_bpermute_b32 v40, v101, v39
	v_lshrrev_b32_e32 v0, 2, v32
	v_or_b32_e32 v0, v83, v0
	v_lshlrev_b32_e32 v1, 3, v98
	v_mul_u32_u24_e32 v0, 0x120, v0
	v_and_b32_e32 v1, 24, v1
	v_add3_u32 v41, s27, v0, v1
	v_cvt_pk_bf16_f32 v0, v12, v13
	v_cvt_pk_bf16_f32 v1, v14, v15
	s_cbranch_vccnz .LBB0_1333
	ds_read_b64_tr_b16 v[4:5], v41
	ds_read_b64_tr_b16 v[8:9], v41 offset:32
	ds_read_b64_tr_b16 v[12:13], v41 offset:64
	ds_read_b64_tr_b16 v[16:17], v41 offset:96
	ds_read_b64_tr_b16 v[6:7], v41 offset:4608
	ds_read_b64_tr_b16 v[10:11], v41 offset:4640
	ds_read_b64_tr_b16 v[14:15], v41 offset:4672
	ds_read_b64_tr_b16 v[18:19], v41 offset:4704
	ds_read_b64_tr_b16 v[102:103], v41 offset:128
	ds_read_b64_tr_b16 v[106:107], v41 offset:160
	ds_read_b64_tr_b16 v[110:111], v41 offset:192
	ds_read_b64_tr_b16 v[114:115], v41 offset:224
	ds_read_b64_tr_b16 v[104:105], v41 offset:4736
	ds_read_b64_tr_b16 v[108:109], v41 offset:4768
	ds_read_b64_tr_b16 v[112:113], v41 offset:4800
	ds_read_b64_tr_b16 v[116:117], v41 offset:4832
	s_waitcnt lgkmcnt(11)
	v_mfma_f32_16x16x32_bf16 v[28:31], v[4:7], v[0:3], 0
	s_waitcnt lgkmcnt(10)
	v_mfma_f32_16x16x32_bf16 v[24:27], v[8:11], v[0:3], 0
	s_waitcnt lgkmcnt(9)
	v_mfma_f32_16x16x32_bf16 v[20:23], v[12:15], v[0:3], 0
	s_waitcnt lgkmcnt(8)
	v_mfma_f32_16x16x32_bf16 v[16:19], v[16:19], v[0:3], 0
	s_waitcnt lgkmcnt(3)
	v_mfma_f32_16x16x32_bf16 v[12:15], v[102:105], v[0:3], 0
	s_waitcnt lgkmcnt(2)
	v_mfma_f32_16x16x32_bf16 v[8:11], v[106:109], v[0:3], 0
	s_waitcnt lgkmcnt(1)
	v_mfma_f32_16x16x32_bf16 v[4:7], v[110:113], v[0:3], 0
	s_waitcnt lgkmcnt(0)
	v_mfma_f32_16x16x32_bf16 v[0:3], v[114:117], v[0:3], 0
	s_branch .LBB0_1334

.LBB0_1352:
	s_andn2_b64 vcc, exec, s[10:11]
	s_cbranch_vccnz .LBB0_1271
	s_lshl_b32 s8, s74, 12
	v_readlane_b32 s9, v253, 1
	s_or_b32 s12, s8, s9
	v_readlane_b32 s9, v253, 2
	s_lshl_b32 s74, s75, 7
	s_add_i32 s13, s9, s8
	s_and_b32 s8, s74, 0x180
	s_lshl_b32 s28, s8, 1
	v_readlane_b32 s8, v252, 15
	s_add_u32 s8, s8, s28
	v_readlane_b32 s9, v252, 16
	s_addc_u32 s9, s9, 0
	v_readlane_b32 s10, v252, 17
	s_add_u32 s10, s10, s28
	v_readlane_b32 s11, v252, 18
	v_lshlrev_b32_e32 v0, 4, v99
	s_addc_u32 s11, s11, 0
	v_and_b32_e32 v32, 0xf0, v0
	v_ashrrev_i32_e32 v83, 4, v99
	v_lshl_add_u64 v[16:17], s[8:9], 0, v[32:33]
	v_lshl_add_u64 v[18:19], s[10:11], 0, v[32:33]
	s_movk_i32 s8, 0x80
	v_readlane_b32 s10, v253, 3
	v_cmp_gt_i32_e32 vcc, s8, v83
	v_readlane_b32 s11, v253, 4
	v_add_u32_e32 v24, s13, v83
	v_mov_b32_e32 v25, s12
	s_and_b64 vcc, s[10:11], vcc
	v_cndmask_b32_e32 v2, v24, v25, vcc
	v_mad_i64_i32 v[0:1], s[8:9], v2, s70, v[16:17]
	v_mad_i64_i32 v[4:5], s[8:9], v2, s70, v[18:19]
	s_movk_i32 s8, 0x60
	s_nop 0
	v_cmp_gt_i32_e32 vcc, s8, v83
	v_add_u32_e32 v8, 32, v24
	s_and_b64 vcc, s[10:11], vcc
	v_cndmask_b32_e32 v10, v8, v25, vcc
	v_cmp_gt_i32_e32 vcc, 64, v83
	v_add_u32_e32 v20, 64, v24
	s_and_b64 vcc, s[10:11], vcc
	v_cndmask_b32_e32 v22, v20, v25, vcc
	v_mad_i64_i32 v[8:9], s[8:9], v10, s70, v[16:17]
	v_mad_i64_i32 v[12:13], s[8:9], v10, s70, v[18:19]
	v_mad_i64_i32 v[20:21], s[8:9], v22, s70, v[16:17]
	v_cmp_gt_i32_e32 vcc, 32, v83
	s_nop 0
	s_nop 0
	s_nop 0
	v_mad_i64_i32 v[22:23], s[8:9], v22, s70, v[18:19]
	v_add_u32_e32 v20, 0x60, v24
	s_and_b64 vcc, s[10:11], vcc
	v_cndmask_b32_e32 v22, v20, v25, vcc
	v_mad_i64_i32 v[20:21], s[8:9], v22, s70, v[16:17]
	v_cmp_gt_i32_e32 vcc, 0, v83
	v_mad_i64_i32 v[22:23], s[8:9], v22, s70, v[18:19]
	v_add_u32_e32 v20, 0x80, v24
	s_and_b64 vcc, s[10:11], vcc
	v_cndmask_b32_e32 v22, v20, v25, vcc
	v_mad_i64_i32 v[20:21], s[8:9], v22, s70, v[16:17]
	v_mad_i64_i32 v[22:23], s[8:9], v22, s70, v[18:19]
	s_movk_i32 s8, 0xffe0
	s_nop 0
	v_cmp_gt_i32_e32 vcc, s8, v83
	v_add_u32_e32 v20, 0xa0, v24
	s_and_b64 vcc, s[10:11], vcc
	v_cndmask_b32_e32 v22, v20, v25, vcc
	v_mad_i64_i32 v[20:21], s[8:9], v22, s70, v[16:17]
	v_mad_i64_i32 v[22:23], s[8:9], v22, s70, v[18:19]
	s_movk_i32 s8, 0xffc0
	s_nop 0
	v_cmp_gt_i32_e32 vcc, s8, v83
	v_add_u32_e32 v20, 0xc0, v24
	s_and_b64 vcc, s[10:11], vcc
	v_cndmask_b32_e32 v22, v20, v25, vcc
	v_mad_i64_i32 v[20:21], s[8:9], v22, s70, v[16:17]
	v_mad_i64_i32 v[22:23], s[8:9], v22, s70, v[18:19]
	s_movk_i32 s8, 0xffa0
	s_nop 0
	v_cmp_gt_i32_e32 vcc, s8, v83
	v_add_u32_e32 v20, 0xe0, v24
	s_and_b64 vcc, s[10:11], vcc
	v_cndmask_b32_e32 v20, v20, v25, vcc
	v_mad_i64_i32 v[16:17], s[8:9], v20, s70, v[16:17]
	v_mad_i64_i32 v[18:19], s[8:9], v20, s70, v[18:19]
	v_readlane_b32 s8, v252, 27
	s_add_u32 s8, s8, s28
	v_readlane_b32 s9, v252, 28
	v_and_b32_e32 v85, 15, v99
	s_addc_u32 s9, s9, 0
	v_lshl_or_b32 v82, s73, 4, v85
	v_add_u32_e32 v84, s12, v82
	v_mov_b64_e32 v[16:17], s[8:9]
	v_mad_i64_i32 v[16:17], s[8:9], v84, s70, v[16:17]
	v_and_b32_e32 v86, 48, v99
	v_mov_b32_e32 v87, v33
	v_lshl_add_u64 v[28:29], v[16:17], 0, v[86:87]
	s_nop 0
	v_mul_lo_u32 v87, v83, s33
	v_add3_u32 v87, 0, v32, v87
	s_movk_i32 s8, 0x120
	v_mul_lo_u32 v0, v83, s8
	s_add_i32 s8, s73, -2
	v_add3_u32 v0, s27, v32, v0
	v_add_u32_e32 v32, 0, v86
	s_cmp_gt_u32 s8, -11
	v_mov_b32_e32 v0, 0
	s_cselect_b64 s[44:45], -1, 0
	s_cmp_lt_u32 s8, -10
	v_mad_u32_u24 v83, v85, s33, v32
	v_mov_b32_e32 v8, 0
	v_mov_b32_e32 v9, 0
	v_mov_b32_e32 v10, 0
	v_mov_b32_e32 v11, 0
	v_mov_b32_e32 v12, 0
	v_mov_b32_e32 v13, 0
	v_mov_b32_e32 v14, 0
	v_mov_b32_e32 v15, 0
	s_waitcnt lgkmcnt(0)
	s_cselect_b32 s49, 1, 0
	v_mov_b64_e32 v[16:17], v[228:229]
	v_mov_b64_e32 v[18:19], v[230:231]
	v_mov_b64_e32 v[20:21], v[232:233]
	v_mov_b64_e32 v[22:23], v[234:235]
	v_mov_b64_e32 v[24:25], v[236:237]
	v_mov_b64_e32 v[26:27], v[238:239]
	v_mov_b64_e32 v[28:29], v[240:241]
	v_mov_b64_e32 v[30:31], v[242:243]
	s_add_u32 s48, s72, 1
	s_cmp_lt_u32 s48, 8
	s_cbranch_scc1 .Lpf_issue

.LBB0_1355:
	s_add_i32 s8, s73, -4
	s_cmp_gt_u32 s8, -11
	s_cselect_b64 s[34:35], -1, 0
	s_cmp_lt_u32 s8, -10
	v_mov_b32_e32 v1, 0
	s_nop 0
	v_mov_b32_e32 v2, 0
	v_mov_b32_e32 v3, 0
	v_mov_b32_e32 v42, 0
	v_mov_b32_e32 v43, 0
	v_mov_b32_e32 v44, 0
	v_mov_b32_e32 v45, 0
	s_cbranch_scc1 .LBB0_1357
	v_or_b32_e32 v42, 48, v98
	v_mad_u32_u24 v42, v42, s33, v32
	ds_read_b128 v[0:3], v83 offset:8704
	ds_read_b128 v[4:7], v83 offset:8768
	ds_read_b128 v[34:37], v83 offset:8832
	ds_read_b128 v[38:41], v83 offset:8896
	ds_read_b128 v[46:49], v42
	ds_read_b128 v[50:53], v42 offset:64
	ds_read_b128 v[54:57], v42 offset:128
	ds_read_b128 v[58:61], v42 offset:192
	s_waitcnt lgkmcnt(7)
	v_mfma_f32_16x16x32_bf16 v[0:3], v[0:3], v[16:19], 0
	s_waitcnt lgkmcnt(6)
	v_mfma_f32_16x16x32_bf16 v[0:3], v[4:7], v[20:23], v[0:3]
	s_waitcnt lgkmcnt(5)
	v_mfma_f32_16x16x32_bf16 v[0:3], v[34:37], v[24:27], v[0:3]
	s_waitcnt lgkmcnt(4)
	v_mfma_f32_16x16x32_bf16 v[42:45], v[38:41], v[28:31], v[0:3]
	s_waitcnt lgkmcnt(3)
	v_mfma_f32_16x16x32_bf16 v[0:3], v[46:49], v[16:19], 0
	s_waitcnt lgkmcnt(2)
	v_mfma_f32_16x16x32_bf16 v[0:3], v[50:53], v[20:23], v[0:3]
	s_waitcnt lgkmcnt(1)
	v_mfma_f32_16x16x32_bf16 v[0:3], v[54:57], v[24:27], v[0:3]
	s_waitcnt lgkmcnt(0)
	v_mfma_f32_16x16x32_bf16 v[0:3], v[58:61], v[28:31], v[0:3]

.LBB0_1359:
	s_add_i32 s8, s73, -8
	s_cmp_gt_u32 s8, -11
	s_cselect_b64 s[20:21], -1, 0
	s_cmp_lt_u32 s8, -10
	v_mov_b32_e32 v5, 0
	v_mov_b32_e32 v6, 0
	v_mov_b32_e32 v7, 0
	v_mov_b32_e32 v58, 0
	v_mov_b32_e32 v59, 0
	v_mov_b32_e32 v60, 0
	v_mov_b32_e32 v61, 0
	s_cbranch_scc1 .LBB0_1361
	v_or_b32_e32 v58, 0x70, v98
	v_mad_u32_u24 v58, v58, s33, v32
	ds_read_b128 v[4:7], v83 offset:26112
	ds_read_b128 v[34:37], v83 offset:26176
	ds_read_b128 v[50:53], v83 offset:26240
	ds_read_b128 v[54:57], v83 offset:26304
	ds_read_b128 v[62:65], v58
	ds_read_b128 v[66:69], v58 offset:64
	ds_read_b128 v[70:73], v58 offset:128
	ds_read_b128 v[74:77], v58 offset:192
	s_waitcnt lgkmcnt(7)
	v_mfma_f32_16x16x32_bf16 v[4:7], v[4:7], v[16:19], 0
	s_waitcnt lgkmcnt(6)
	v_mfma_f32_16x16x32_bf16 v[4:7], v[34:37], v[20:23], v[4:7]
	s_waitcnt lgkmcnt(5)
	v_mfma_f32_16x16x32_bf16 v[4:7], v[50:53], v[24:27], v[4:7]
	s_waitcnt lgkmcnt(4)
	v_mfma_f32_16x16x32_bf16 v[58:61], v[54:57], v[28:31], v[4:7]
	s_waitcnt lgkmcnt(3)
	v_mfma_f32_16x16x32_bf16 v[4:7], v[62:65], v[16:19], 0
	s_waitcnt lgkmcnt(2)
	v_mfma_f32_16x16x32_bf16 v[4:7], v[66:69], v[20:23], v[4:7]
	s_waitcnt lgkmcnt(1)
	v_mfma_f32_16x16x32_bf16 v[4:7], v[70:73], v[24:27], v[4:7]
	s_waitcnt lgkmcnt(0)
	v_mfma_f32_16x16x32_bf16 v[4:7], v[74:77], v[28:31], v[4:7]
.LBB0_1361:
	s_cmp_lt_u32 s73, 10
	v_mov_b32_e32 v34, 0
	s_cselect_b64 s[18:19], -1, 0
	s_cmp_gt_u32 s73, 9
	v_mov_b32_e32 v54, 0
	v_mov_b32_e32 v55, 0
	v_mov_b32_e32 v56, 0
	v_mov_b32_e32 v57, 0
	v_mov_b32_e32 v62, 0
	v_mov_b32_e32 v63, 0
	v_mov_b32_e32 v64, 0
	v_mov_b32_e32 v65, 0
	s_cbranch_scc1 .LBB0_1363
	ds_read_b128 v[50:53], v83 offset:34816
	ds_read_b128 v[54:57], v83 offset:34880
	ds_read_b128 v[62:65], v83 offset:34944
	ds_read_b128 v[66:69], v83 offset:35008
	ds_read_b128 v[70:73], v83 offset:39168
	ds_read_b128 v[74:77], v83 offset:39232
	ds_read_b128 v[78:81], v83 offset:39296
	ds_read_b128 v[86:89], v83 offset:39360
	s_waitcnt lgkmcnt(7)
	v_mfma_f32_16x16x32_bf16 v[50:53], v[50:53], v[16:19], 0
	s_waitcnt lgkmcnt(6)
	v_mfma_f32_16x16x32_bf16 v[50:53], v[54:57], v[20:23], v[50:53]
	s_waitcnt lgkmcnt(5)
	v_mfma_f32_16x16x32_bf16 v[50:53], v[62:65], v[24:27], v[50:53]
	s_waitcnt lgkmcnt(4)
	v_mfma_f32_16x16x32_bf16 v[62:65], v[66:69], v[28:31], v[50:53]
	s_waitcnt lgkmcnt(3)
	v_mfma_f32_16x16x32_bf16 v[50:53], v[70:73], v[16:19], 0
	s_waitcnt lgkmcnt(2)
	v_mfma_f32_16x16x32_bf16 v[50:53], v[74:77], v[20:23], v[50:53]
	s_waitcnt lgkmcnt(1)
	v_mfma_f32_16x16x32_bf16 v[50:53], v[78:81], v[24:27], v[50:53]
	s_waitcnt lgkmcnt(0)
	v_mfma_f32_16x16x32_bf16 v[54:57], v[86:89], v[28:31], v[50:53]
.LBB0_1363:
	s_add_i32 s8, s73, -12
	s_cmp_gt_u32 s8, -11
	s_cselect_b64 s[16:17], -1, 0
	s_cmp_lt_u32 s8, -10
	v_mov_b32_e32 v35, 0
	v_mov_b32_e32 v36, 0
	v_mov_b32_e32 v37, 0
	v_mov_b32_e32 v70, 0
	v_mov_b32_e32 v71, 0
	v_mov_b32_e32 v72, 0
	v_mov_b32_e32 v73, 0
	s_cbranch_scc1 .LBB0_1365
	v_or_b32_e32 v74, 0xb0, v98
	v_mad_u32_u24 v90, v74, s33, v32
	ds_read_b128 v[34:37], v83 offset:43520
	ds_read_b128 v[50:53], v83 offset:43584
	ds_read_b128 v[66:69], v83 offset:43648
	ds_read_b128 v[70:73], v83 offset:43712
	ds_read_b128 v[74:77], v90
	ds_read_b128 v[78:81], v90 offset:64
	ds_read_b128 v[86:89], v90 offset:128
	ds_read_b128 v[90:93], v90 offset:192
	s_waitcnt lgkmcnt(7)
	v_mfma_f32_16x16x32_bf16 v[34:37], v[34:37], v[16:19], 0
	s_waitcnt lgkmcnt(6)
	v_mfma_f32_16x16x32_bf16 v[34:37], v[50:53], v[20:23], v[34:37]
	s_waitcnt lgkmcnt(5)
	v_mfma_f32_16x16x32_bf16 v[34:37], v[66:69], v[24:27], v[34:37]
	s_waitcnt lgkmcnt(4)
	v_mfma_f32_16x16x32_bf16 v[70:73], v[70:73], v[28:31], v[34:37]
	s_waitcnt lgkmcnt(3)
	v_mfma_f32_16x16x32_bf16 v[34:37], v[74:77], v[16:19], 0
	s_waitcnt lgkmcnt(2)
	v_mfma_f32_16x16x32_bf16 v[34:37], v[78:81], v[20:23], v[34:37]
	s_waitcnt lgkmcnt(1)
	v_mfma_f32_16x16x32_bf16 v[34:37], v[86:89], v[24:27], v[34:37]
	s_waitcnt lgkmcnt(0)
	v_mfma_f32_16x16x32_bf16 v[34:37], v[90:93], v[28:31], v[34:37]
.LBB0_1365:
	s_add_i32 s8, s73, -14
	s_cmp_gt_u32 s8, -11
	v_mov_b32_e32 v50, 0
	s_cselect_b64 s[14:15], -1, 0
	s_cmp_lt_u32 s8, -10
	v_mov_b32_e32 v66, 0
	v_mov_b32_e32 v67, 0
	v_mov_b32_e32 v68, 0
	v_mov_b32_e32 v69, 0
	v_mov_b32_e32 v74, 0
	v_mov_b32_e32 v75, 0
	v_mov_b32_e32 v76, 0
	v_mov_b32_e32 v77, 0
	s_cbranch_scc1 .LBB0_1367
	ds_read_b128 v[66:69], v83 offset:52224
	ds_read_b128 v[74:77], v83 offset:52288
	ds_read_b128 v[78:81], v83 offset:52352
	ds_read_b128 v[86:89], v83 offset:52416
	ds_read_b128 v[90:93], v83 offset:56576
	ds_read_b128 v[94:97], v83 offset:56640
	ds_read_b128 v[102:105], v83 offset:56704
	ds_read_b128 v[106:109], v83 offset:56768
	s_waitcnt lgkmcnt(7)
	v_mfma_f32_16x16x32_bf16 v[66:69], v[66:69], v[16:19], 0
	s_waitcnt lgkmcnt(6)
	v_mfma_f32_16x16x32_bf16 v[66:69], v[74:77], v[20:23], v[66:69]
	s_waitcnt lgkmcnt(5)
	v_mfma_f32_16x16x32_bf16 v[66:69], v[78:81], v[24:27], v[66:69]
	s_waitcnt lgkmcnt(4)
	v_mfma_f32_16x16x32_bf16 v[74:77], v[86:89], v[28:31], v[66:69]
	s_waitcnt lgkmcnt(3)
	v_mfma_f32_16x16x32_bf16 v[66:69], v[90:93], v[16:19], 0
	s_waitcnt lgkmcnt(2)
	v_mfma_f32_16x16x32_bf16 v[66:69], v[94:97], v[20:23], v[66:69]
	s_waitcnt lgkmcnt(1)
	v_mfma_f32_16x16x32_bf16 v[66:69], v[102:105], v[24:27], v[66:69]
	s_waitcnt lgkmcnt(0)
	v_mfma_f32_16x16x32_bf16 v[66:69], v[106:109], v[28:31], v[66:69]
.LBB0_1367:
	s_add_i32 s73, s73, -16
	s_cmp_gt_u32 s73, -11
	s_cselect_b64 s[12:13], -1, 0
	s_cmp_lt_u32 s73, -10
	v_mov_b32_e32 v51, 0
	v_mov_b32_e32 v52, 0
	v_mov_b32_e32 v53, 0
	v_mov_b32_e32 v78, 0
	v_mov_b32_e32 v79, 0
	v_mov_b32_e32 v80, 0
	v_mov_b32_e32 v81, 0
	s_cbranch_scc1 .LBB0_1369
	ds_read_b128 v[50:53], v83 offset:60928
	ds_read_b128 v[78:81], v83 offset:60992
	ds_read_b128 v[86:89], v83 offset:61056
	ds_read_b128 v[90:93], v83 offset:61120
	v_or_b32_e32 v83, 0xf0, v98
	v_mad_u32_u24 v32, v83, s33, v32
	ds_read_b128 v[94:97], v32
	ds_read_b128 v[102:105], v32 offset:64
	ds_read_b128 v[106:109], v32 offset:128
	ds_read_b128 v[110:113], v32 offset:192
	s_waitcnt lgkmcnt(7)
	v_mfma_f32_16x16x32_bf16 v[50:53], v[50:53], v[16:19], 0
	s_waitcnt lgkmcnt(3)
	v_mfma_f32_16x16x32_bf16 v[16:19], v[94:97], v[16:19], 0
	v_mfma_f32_16x16x32_bf16 v[50:53], v[78:81], v[20:23], v[50:53]
	s_waitcnt lgkmcnt(2)
	v_mfma_f32_16x16x32_bf16 v[16:19], v[102:105], v[20:23], v[16:19]
	v_mfma_f32_16x16x32_bf16 v[50:53], v[86:89], v[24:27], v[50:53]
	s_waitcnt lgkmcnt(1)
	v_mfma_f32_16x16x32_bf16 v[16:19], v[106:109], v[24:27], v[16:19]
	v_mfma_f32_16x16x32_bf16 v[78:81], v[90:93], v[28:31], v[50:53]
	s_waitcnt lgkmcnt(0)
	v_mfma_f32_16x16x32_bf16 v[50:53], v[110:113], v[28:31], v[16:19]
.LBB0_1369:
	v_readlane_b32 s8, v253, 3
	s_nop 1
	v_max_i32_e32 v16, 0x80, v82
	v_readlane_b32 s9, v253, 4
	v_lshrrev_b32_e32 v18, 2, v98
	v_add_u32_e32 v17, 0x80, v82
	v_cndmask_b32_e64 v16, v82, v16, s[8:9]
	v_and_b32_e32 v83, 12, v18
	v_cmp_lt_i32_e32 vcc, v83, v16
	v_cmp_gt_i32_e64 s[10:11], v83, v17
	s_or_b64 vcc, vcc, s[10:11]
	v_or_b32_e32 v19, 1, v83
	v_cndmask_b32_e32 v12, v12, v225, vcc
	v_cmp_lt_i32_e32 vcc, v19, v16
	v_cmp_ge_i32_e64 s[10:11], v83, v17
	s_or_b64 vcc, vcc, s[10:11]
	v_or_b32_e32 v19, 2, v83
	v_cndmask_b32_e32 v13, v13, v225, vcc
	v_cmp_lt_i32_e32 vcc, v19, v16
	v_cmp_gt_i32_e64 s[10:11], v19, v17
	s_or_b64 vcc, vcc, s[10:11]
	v_or_b32_e32 v19, 3, v18
	v_cndmask_b32_e32 v14, v14, v225, vcc
	v_cmp_lt_i32_e32 vcc, v19, v16
	v_cmp_gt_i32_e64 s[10:11], v19, v17
	s_or_b64 vcc, vcc, s[10:11]
	v_or_b32_e32 v19, 16, v83
	v_cndmask_b32_e32 v15, v15, v225, vcc
	v_cmp_lt_i32_e32 vcc, v19, v16
	v_cmp_gt_i32_e64 s[10:11], v19, v17
	s_or_b64 vcc, vcc, s[10:11]
	v_or_b32_e32 v19, 17, v83
	v_cndmask_b32_e32 v8, v8, v225, vcc
	v_cmp_lt_i32_e32 vcc, v19, v16
	v_cmp_gt_i32_e64 s[10:11], v19, v17
	s_or_b64 vcc, vcc, s[10:11]
	v_or_b32_e32 v19, 18, v83
	v_cndmask_b32_e32 v9, v9, v225, vcc
	v_cmp_lt_i32_e32 vcc, v19, v16
	v_cmp_gt_i32_e64 s[10:11], v19, v17
	s_or_b64 vcc, vcc, s[10:11]
	v_or_b32_e32 v19, 19, v18
	v_cndmask_b32_e32 v10, v10, v225, vcc
	v_cmp_lt_i32_e32 vcc, v19, v16
	v_cmp_gt_i32_e64 s[10:11], v19, v17
	s_or_b64 vcc, vcc, s[10:11]
	v_or_b32_e32 v19, 32, v83
	v_cndmask_b32_e32 v11, v11, v225, vcc
	v_cmp_lt_i32_e32 vcc, v19, v16
	v_cmp_gt_i32_e64 s[10:11], v19, v17
	s_or_b64 vcc, vcc, s[10:11]
	v_or_b32_e32 v20, 33, v83
	v_cndmask_b32_e32 v19, v42, v225, vcc
	v_cmp_lt_i32_e32 vcc, v20, v16
	v_cmp_gt_i32_e64 s[10:11], v20, v17
	s_or_b64 vcc, vcc, s[10:11]
	v_or_b32_e32 v21, 34, v83
	v_cndmask_b32_e32 v20, v43, v225, vcc
	v_cmp_lt_i32_e32 vcc, v21, v16
	v_cmp_gt_i32_e64 s[10:11], v21, v17
	s_or_b64 vcc, vcc, s[10:11]
	v_or_b32_e32 v22, 35, v18
	v_cndmask_b32_e32 v21, v44, v225, vcc
	v_cmp_lt_i32_e32 vcc, v22, v16
	v_cmp_gt_i32_e64 s[10:11], v22, v17
	s_or_b64 vcc, vcc, s[10:11]
	v_or_b32_e32 v23, 48, v83
	v_cndmask_b32_e32 v22, v45, v225, vcc
	v_cmp_lt_i32_e32 vcc, v23, v16
	v_cmp_gt_i32_e64 s[10:11], v23, v17
	s_or_b64 vcc, vcc, s[10:11]
	v_or_b32_e32 v23, 49, v83
	v_cndmask_b32_e32 v0, v0, v225, vcc
	v_cmp_lt_i32_e32 vcc, v23, v16
	v_cmp_gt_i32_e64 s[10:11], v23, v17
	s_or_b64 vcc, vcc, s[10:11]
	v_or_b32_e32 v23, 50, v83
	v_cndmask_b32_e32 v1, v1, v225, vcc
	v_cmp_lt_i32_e32 vcc, v23, v16
	v_cmp_gt_i32_e64 s[10:11], v23, v17
	s_or_b64 vcc, vcc, s[10:11]
	v_or_b32_e32 v23, 51, v18
	v_cndmask_b32_e32 v2, v2, v225, vcc
	v_cmp_lt_i32_e32 vcc, v23, v16
	v_cmp_gt_i32_e64 s[10:11], v23, v17
	s_or_b64 vcc, vcc, s[10:11]
	v_or_b32_e32 v23, 64, v83
	v_cndmask_b32_e32 v3, v3, v225, vcc
	v_cmp_lt_i32_e32 vcc, v23, v16
	v_cmp_gt_i32_e64 s[10:11], v23, v17
	s_or_b64 vcc, vcc, s[10:11]
	v_or_b32_e32 v24, 0x41, v83
	v_cndmask_b32_e32 v23, v46, v225, vcc
	v_cmp_lt_i32_e32 vcc, v24, v16
	v_cmp_gt_i32_e64 s[10:11], v24, v17
	s_or_b64 vcc, vcc, s[10:11]
	v_or_b32_e32 v25, 0x42, v83
	v_cndmask_b32_e32 v24, v47, v225, vcc
	v_cmp_lt_i32_e32 vcc, v25, v16
	v_cmp_gt_i32_e64 s[10:11], v25, v17
	s_or_b64 vcc, vcc, s[10:11]
	v_or_b32_e32 v26, 0x43, v18
	v_cndmask_b32_e32 v25, v48, v225, vcc
	v_cmp_lt_i32_e32 vcc, v26, v16
	v_cmp_gt_i32_e64 s[10:11], v26, v17
	s_or_b64 vcc, vcc, s[10:11]
	v_or_b32_e32 v27, 0x50, v83
	v_cndmask_b32_e32 v26, v49, v225, vcc
	v_cmp_lt_i32_e32 vcc, v27, v16
	v_cmp_gt_i32_e64 s[10:11], v27, v17
	s_or_b64 vcc, vcc, s[10:11]
	v_or_b32_e32 v28, 0x51, v83
	v_cndmask_b32_e32 v27, v38, v225, vcc
	v_cmp_lt_i32_e32 vcc, v28, v16
	v_cmp_gt_i32_e64 s[10:11], v28, v17
	s_or_b64 vcc, vcc, s[10:11]
	v_or_b32_e32 v29, 0x52, v83
	v_cndmask_b32_e32 v28, v39, v225, vcc
	v_cmp_lt_i32_e32 vcc, v29, v16
	v_cmp_gt_i32_e64 s[10:11], v29, v17
	s_or_b64 vcc, vcc, s[10:11]
	v_or_b32_e32 v30, 0x53, v18
	v_cndmask_b32_e32 v29, v40, v225, vcc
	v_cmp_lt_i32_e32 vcc, v30, v16
	v_cmp_gt_i32_e64 s[10:11], v30, v17
	s_or_b64 vcc, vcc, s[10:11]
	v_or_b32_e32 v31, 0x60, v83
	v_cndmask_b32_e32 v30, v41, v225, vcc
	v_cmp_lt_i32_e32 vcc, v31, v16
	v_cmp_gt_i32_e64 s[10:11], v31, v17
	s_or_b64 vcc, vcc, s[10:11]
	v_or_b32_e32 v32, 0x61, v83
	v_cndmask_b32_e32 v31, v58, v225, vcc
	v_cmp_lt_i32_e32 vcc, v32, v16
	v_cmp_gt_i32_e64 s[10:11], v32, v17
	s_or_b64 vcc, vcc, s[10:11]
	v_or_b32_e32 v38, 0x62, v83
	v_cndmask_b32_e32 v32, v59, v225, vcc
	v_cmp_lt_i32_e32 vcc, v38, v16
	v_cmp_gt_i32_e64 s[10:11], v38, v17
	s_or_b64 vcc, vcc, s[10:11]
	v_or_b32_e32 v38, 0x63, v18
	v_cndmask_b32_e32 v39, v60, v225, vcc
	v_cmp_lt_i32_e32 vcc, v38, v16
	v_cmp_gt_i32_e64 s[10:11], v38, v17
	s_or_b64 vcc, vcc, s[10:11]
	v_or_b32_e32 v38, 0x70, v83
	v_cndmask_b32_e32 v40, v61, v225, vcc
	v_cmp_lt_i32_e32 vcc, v38, v16
	v_cmp_gt_i32_e64 s[10:11], v38, v17
	s_or_b64 vcc, vcc, s[10:11]
	v_or_b32_e32 v38, 0x71, v83
	v_cndmask_b32_e32 v4, v4, v225, vcc
	v_cmp_lt_i32_e32 vcc, v38, v16
	v_cmp_gt_i32_e64 s[10:11], v38, v17
	s_or_b64 vcc, vcc, s[10:11]
	v_or_b32_e32 v38, 0x72, v83
	v_cndmask_b32_e32 v5, v5, v225, vcc
	v_cmp_lt_i32_e32 vcc, v38, v16
	v_cmp_gt_i32_e64 s[10:11], v38, v17
	s_or_b64 vcc, vcc, s[10:11]
	v_or_b32_e32 v38, 0x73, v18
	v_cndmask_b32_e32 v6, v6, v225, vcc
	v_cmp_lt_i32_e32 vcc, v38, v16
	v_cmp_gt_i32_e64 s[10:11], v38, v17
	s_or_b64 vcc, vcc, s[10:11]
	v_or_b32_e32 v38, 0x80, v83
	v_cndmask_b32_e32 v7, v7, v225, vcc
	v_cmp_lt_i32_e32 vcc, v38, v16
	v_cmp_gt_i32_e64 s[10:11], v83, v82
	s_or_b64 vcc, s[10:11], vcc
	v_or_b32_e32 v38, 0x81, v83
	v_cndmask_b32_e32 v41, v62, v225, vcc
	v_cmp_lt_i32_e32 vcc, v38, v16
	v_cmp_gt_i32_e64 s[10:11], v38, v17
	s_or_b64 vcc, vcc, s[10:11]
	v_or_b32_e32 v38, 0x82, v83
	v_cndmask_b32_e32 v42, v63, v225, vcc
	v_cmp_lt_i32_e32 vcc, v38, v16
	v_cmp_gt_i32_e64 s[10:11], v38, v17
	s_or_b64 vcc, vcc, s[10:11]
	v_or_b32_e32 v38, 0x83, v18
	v_cndmask_b32_e32 v43, v64, v225, vcc
	v_cmp_lt_i32_e32 vcc, v38, v16
	v_cmp_gt_i32_e64 s[10:11], v38, v17
	s_or_b64 vcc, vcc, s[10:11]
	v_or_b32_e32 v38, 0x90, v83
	v_cndmask_b32_e32 v44, v65, v225, vcc
	v_cmp_lt_i32_e32 vcc, v38, v16
	v_cmp_gt_i32_e64 s[10:11], v38, v17
	s_or_b64 vcc, vcc, s[10:11]
	v_or_b32_e32 v38, 0x91, v83
	v_cndmask_b32_e32 v45, v54, v225, vcc
	v_cmp_lt_i32_e32 vcc, v38, v16
	v_cmp_gt_i32_e64 s[10:11], v38, v17
	s_or_b64 vcc, vcc, s[10:11]
	v_or_b32_e32 v38, 0x92, v83
	v_cndmask_b32_e32 v46, v55, v225, vcc
	v_cmp_lt_i32_e32 vcc, v38, v16
	v_cmp_gt_i32_e64 s[10:11], v38, v17
	s_or_b64 vcc, vcc, s[10:11]
	v_or_b32_e32 v38, 0x93, v18
	v_cndmask_b32_e32 v47, v56, v225, vcc
	v_cmp_lt_i32_e32 vcc, v38, v16
	v_cmp_gt_i32_e64 s[10:11], v38, v17
	s_or_b64 vcc, vcc, s[10:11]
	v_or_b32_e32 v38, 0xa0, v83
	v_cndmask_b32_e32 v48, v57, v225, vcc
	v_cmp_lt_i32_e32 vcc, v38, v16
	v_cmp_gt_i32_e64 s[10:11], v38, v17
	s_or_b64 vcc, vcc, s[10:11]
	v_or_b32_e32 v38, 0xa1, v83
	v_cndmask_b32_e32 v49, v70, v225, vcc
	v_cmp_lt_i32_e32 vcc, v38, v16
	v_cmp_gt_i32_e64 s[10:11], v38, v17
	s_or_b64 vcc, vcc, s[10:11]
	v_or_b32_e32 v38, 0xa2, v83
	v_cndmask_b32_e32 v54, v71, v225, vcc
	v_cmp_lt_i32_e32 vcc, v38, v16
	v_cmp_gt_i32_e64 s[10:11], v38, v17
	s_or_b64 vcc, vcc, s[10:11]
	v_or_b32_e32 v38, 0xa3, v18
	v_cndmask_b32_e32 v55, v72, v225, vcc
	v_cmp_lt_i32_e32 vcc, v38, v16
	v_cmp_gt_i32_e64 s[10:11], v38, v17
	s_or_b64 vcc, vcc, s[10:11]
	v_or_b32_e32 v38, 0xb0, v83
	v_cndmask_b32_e32 v56, v73, v225, vcc
	v_cmp_lt_i32_e32 vcc, v38, v16
	v_cmp_gt_i32_e64 s[10:11], v38, v17
	s_or_b64 vcc, vcc, s[10:11]
	v_or_b32_e32 v38, 0xb1, v83
	v_cndmask_b32_e32 v34, v34, v225, vcc
	v_cmp_lt_i32_e32 vcc, v38, v16
	v_cmp_gt_i32_e64 s[10:11], v38, v17
	s_or_b64 vcc, vcc, s[10:11]
	v_or_b32_e32 v38, 0xb2, v83
	v_cndmask_b32_e32 v35, v35, v225, vcc
	v_cmp_lt_i32_e32 vcc, v38, v16
	v_cmp_gt_i32_e64 s[10:11], v38, v17
	s_or_b64 vcc, vcc, s[10:11]
	v_cndmask_b32_e32 v57, v36, v225, vcc
	v_or_b32_e32 v36, 0xb3, v18
	v_cmp_lt_i32_e32 vcc, v36, v16
	v_cmp_gt_i32_e64 s[10:11], v36, v17
	s_or_b64 vcc, vcc, s[10:11]
	v_or_b32_e32 v36, 0xc0, v83
	v_cndmask_b32_e32 v64, v37, v225, vcc
	v_cmp_lt_i32_e32 vcc, v36, v16
	v_cmp_gt_i32_e64 s[10:11], v36, v17
	s_or_b64 vcc, vcc, s[10:11]
	v_or_b32_e32 v36, 0xc1, v83
	v_cndmask_b32_e32 v103, v74, v225, vcc
	v_cmp_lt_i32_e32 vcc, v36, v16
	v_cmp_gt_i32_e64 s[10:11], v36, v17
	s_or_b64 vcc, vcc, s[10:11]
	v_or_b32_e32 v36, 0xc2, v83
	v_cndmask_b32_e32 v104, v75, v225, vcc
	v_cmp_lt_i32_e32 vcc, v36, v16
	v_cmp_gt_i32_e64 s[10:11], v36, v17
	s_or_b64 vcc, vcc, s[10:11]
	v_or_b32_e32 v36, 0xc3, v18
	v_cndmask_b32_e32 v105, v76, v225, vcc
	v_cmp_lt_i32_e32 vcc, v36, v16
	v_cmp_gt_i32_e64 s[10:11], v36, v17
	s_or_b64 vcc, vcc, s[10:11]
	v_or_b32_e32 v36, 0xd0, v83
	v_cndmask_b32_e32 v106, v77, v225, vcc
	v_cmp_lt_i32_e32 vcc, v36, v16
	v_cmp_gt_i32_e64 s[10:11], v36, v17
	s_or_b64 vcc, vcc, s[10:11]
	v_or_b32_e32 v36, 0xd1, v83
	v_cndmask_b32_e32 v107, v66, v225, vcc
	v_cmp_lt_i32_e32 vcc, v36, v16
	v_cmp_gt_i32_e64 s[10:11], v36, v17
	s_or_b64 vcc, vcc, s[10:11]
	v_or_b32_e32 v36, 0xd2, v83
	v_cndmask_b32_e32 v108, v67, v225, vcc
	v_cmp_lt_i32_e32 vcc, v36, v16
	v_cmp_gt_i32_e64 s[10:11], v36, v17
	s_or_b64 vcc, vcc, s[10:11]
	v_or_b32_e32 v36, 0xd3, v18
	v_cndmask_b32_e32 v109, v68, v225, vcc
	v_cmp_lt_i32_e32 vcc, v36, v16
	v_cmp_gt_i32_e64 s[10:11], v36, v17
	s_or_b64 vcc, vcc, s[10:11]
	v_or_b32_e32 v36, 0xe0, v83
	v_cndmask_b32_e32 v110, v69, v225, vcc
	v_cmp_lt_i32_e32 vcc, v36, v16
	v_cmp_gt_i32_e64 s[10:11], v36, v17
	s_or_b64 vcc, vcc, s[10:11]
	v_or_b32_e32 v36, 0xe1, v83
	v_cndmask_b32_e32 v111, v78, v225, vcc
	v_cmp_lt_i32_e32 vcc, v36, v16
	v_cmp_gt_i32_e64 s[10:11], v36, v17
	s_or_b64 vcc, vcc, s[10:11]
	v_or_b32_e32 v36, 0xe2, v83
	v_cndmask_b32_e32 v112, v79, v225, vcc
	v_cmp_lt_i32_e32 vcc, v36, v16
	v_cmp_gt_i32_e64 s[10:11], v36, v17
	s_or_b64 vcc, vcc, s[10:11]
	v_or_b32_e32 v36, 0xe3, v18
	v_cndmask_b32_e32 v113, v80, v225, vcc
	v_cmp_lt_i32_e32 vcc, v36, v16
	v_cmp_gt_i32_e64 s[10:11], v36, v17
	s_or_b64 vcc, vcc, s[10:11]
	v_or_b32_e32 v36, 0xf0, v83
	v_cndmask_b32_e32 v114, v81, v225, vcc
	v_cmp_lt_i32_e32 vcc, v36, v16
	v_cmp_gt_i32_e64 s[10:11], v36, v17
	s_or_b64 vcc, vcc, s[10:11]
	v_or_b32_e32 v36, 0xf1, v83
	v_cndmask_b32_e32 v115, v50, v225, vcc
	v_cmp_lt_i32_e32 vcc, v36, v16
	v_cmp_gt_i32_e64 s[10:11], v36, v17
	s_or_b64 vcc, vcc, s[10:11]
	v_or_b32_e32 v36, 0xf2, v83
	v_cndmask_b32_e32 v116, v51, v225, vcc
	v_cmp_lt_i32_e32 vcc, v36, v16
	v_cmp_gt_i32_e64 s[10:11], v36, v17
	s_or_b64 vcc, vcc, s[10:11]
	v_or_b32_e32 v18, 0xf3, v18
	v_cndmask_b32_e32 v117, v52, v225, vcc
	v_cmp_lt_i32_e32 vcc, v18, v16
	v_cmp_gt_i32_e64 s[10:11], v18, v17
	v_max_f32_e32 v17, v12, v12
	v_max_f32_e32 v18, v13, v13
	v_max_f32_e32 v17, v17, v18
	v_max_f32_e32 v18, v15, v15
	v_max_f32_e32 v36, v14, v14
	v_max_f32_e32 v18, v36, v18
	s_mov_b32 s8, 0xff61b1e6
	v_max3_f32 v17, v17, v18, s8
	v_max_f32_e32 v18, v9, v9
	v_max_f32_e32 v36, v8, v8
	v_max_f32_e32 v18, v36, v18
	v_max_f32_e32 v36, v11, v11
	v_max_f32_e32 v37, v10, v10
	v_max_f32_e32 v36, v37, v36
	v_max3_f32 v17, v18, v36, v17
	v_max_f32_e32 v18, v20, v20
	v_max_f32_e32 v36, v19, v19
	v_max_f32_e32 v18, v36, v18
	v_max_f32_e32 v36, v22, v22
	v_max_f32_e32 v37, v21, v21
	v_max_f32_e32 v36, v37, v36
	v_max3_f32 v17, v18, v36, v17
	v_max_f32_e32 v18, v1, v1
	v_max_f32_e32 v36, v0, v0
	v_max_f32_e32 v18, v36, v18
	v_max_f32_e32 v36, v3, v3
	v_max_f32_e32 v37, v2, v2
	v_max_f32_e32 v36, v37, v36
	v_max3_f32 v17, v18, v36, v17
	v_max_f32_e32 v18, v24, v24
	v_max_f32_e32 v36, v23, v23
	v_max_f32_e32 v18, v36, v18
	v_max_f32_e32 v36, v26, v26
	v_max_f32_e32 v37, v25, v25
	v_max_f32_e32 v36, v37, v36
	v_max3_f32 v17, v18, v36, v17
	v_max_f32_e32 v18, v28, v28
	v_max_f32_e32 v36, v27, v27
	v_max_f32_e32 v18, v36, v18
	v_max_f32_e32 v36, v30, v30
	v_max_f32_e32 v37, v29, v29
	v_max_f32_e32 v36, v37, v36
	v_max3_f32 v17, v18, v36, v17
	v_max_f32_e32 v18, v32, v32
	v_max_f32_e32 v36, v31, v31
	v_max_f32_e32 v18, v36, v18
	v_max_f32_e32 v36, v40, v40
	v_max_f32_e32 v37, v39, v39
	v_max_f32_e32 v36, v37, v36
	v_max3_f32 v17, v18, v36, v17
	v_max_f32_e32 v18, v5, v5
	v_max_f32_e32 v36, v4, v4
	v_max_f32_e32 v18, v36, v18
	v_max_f32_e32 v36, v7, v7
	v_max_f32_e32 v37, v6, v6
	v_max_f32_e32 v36, v37, v36
	v_max3_f32 v17, v18, v36, v17
	v_max_f32_e32 v18, v42, v42
	v_max_f32_e32 v36, v41, v41
	v_max_f32_e32 v18, v36, v18
	v_max_f32_e32 v36, v44, v44
	v_max_f32_e32 v37, v43, v43
	v_max_f32_e32 v36, v37, v36
	v_max3_f32 v17, v18, v36, v17
	v_max_f32_e32 v18, v46, v46
	v_max_f32_e32 v36, v45, v45
	v_max_f32_e32 v18, v36, v18
	v_max_f32_e32 v36, v48, v48
	v_max_f32_e32 v37, v47, v47
	v_max_f32_e32 v36, v37, v36
	v_max3_f32 v17, v18, v36, v17
	v_max_f32_e32 v18, v54, v54
	v_max_f32_e32 v36, v49, v49
	v_max_f32_e32 v18, v36, v18
	v_max_f32_e32 v36, v56, v56
	v_max_f32_e32 v37, v55, v55
	v_max_f32_e32 v36, v37, v36
	v_max3_f32 v17, v18, v36, v17
	v_max_f32_e32 v18, v35, v35
	v_max_f32_e32 v36, v34, v34
	v_max_f32_e32 v18, v36, v18
	v_max_f32_e32 v36, v64, v64
	v_max_f32_e32 v37, v57, v57
	v_max_f32_e32 v36, v37, v36
	v_max3_f32 v17, v18, v36, v17
	v_max_f32_e32 v18, v104, v104
	v_max_f32_e32 v36, v103, v103
	v_max_f32_e32 v18, v36, v18
	v_max_f32_e32 v36, v106, v106
	v_max_f32_e32 v37, v105, v105
	v_max_f32_e32 v36, v37, v36
	v_max3_f32 v17, v18, v36, v17
	v_max_f32_e32 v18, v108, v108
	v_max_f32_e32 v36, v107, v107
	v_max_f32_e32 v18, v36, v18
	v_max_f32_e32 v36, v110, v110
	v_max_f32_e32 v37, v109, v109
	v_max_f32_e32 v36, v37, v36
	v_max3_f32 v17, v18, v36, v17
	v_max_f32_e32 v18, v112, v112
	v_max_f32_e32 v36, v111, v111
	v_max_f32_e32 v18, v36, v18
	v_max_f32_e32 v36, v114, v114
	v_max_f32_e32 v37, v113, v113
	s_or_b64 vcc, vcc, s[10:11]
	v_max_f32_e32 v36, v37, v36
	v_cndmask_b32_e32 v16, v53, v225, vcc
	v_max3_f32 v17, v18, v36, v17
	v_max_f32_e32 v18, v116, v116
	v_max_f32_e32 v36, v115, v115
	v_max_f32_e32 v18, v36, v18
	v_max_f32_e32 v36, v16, v16
	v_max_f32_e32 v37, v117, v117
	v_max_f32_e32 v36, v37, v36
	v_max3_f32 v17, v18, v36, v17
	ds_bpermute_b32 v18, v100, v17
	s_andn2_b64 vcc, exec, s[44:45]
	s_waitcnt lgkmcnt(0)
	v_max_f32_e32 v18, v18, v18
	v_max_f32_e32 v17, v17, v18
	ds_bpermute_b32 v18, v101, v17
	s_waitcnt lgkmcnt(0)
	v_max_f32_e32 v18, v18, v18
	v_max_f32_e32 v38, v17, v18
	v_sub_f32_e32 v12, v12, v38
	v_exp_f32_e32 v12, v12
	v_sub_f32_e32 v13, v13, v38
	v_exp_f32_e32 v13, v13
	v_sub_f32_e32 v14, v14, v38
	v_exp_f32_e32 v14, v14
	v_sub_f32_e32 v15, v15, v38
	v_exp_f32_e32 v15, v15
	v_sub_f32_e32 v8, v8, v38
	v_add_f32_e32 v17, 0, v12
	v_exp_f32_e32 v8, v8
	v_sub_f32_e32 v9, v9, v38
	v_add_f32_e32 v17, v13, v17
	v_exp_f32_e32 v9, v9
	v_sub_f32_e32 v10, v10, v38
	v_add_f32_e32 v17, v14, v17
	v_exp_f32_e32 v10, v10
	v_sub_f32_e32 v11, v11, v38
	v_add_f32_e32 v17, v15, v17
	v_exp_f32_e32 v11, v11
	v_sub_f32_e32 v18, v19, v38
	v_add_f32_e32 v17, v8, v17
	v_exp_f32_e32 v36, v18
	v_sub_f32_e32 v18, v20, v38
	v_add_f32_e32 v17, v9, v17
	v_exp_f32_e32 v37, v18
	v_sub_f32_e32 v18, v21, v38
	v_add_f32_e32 v17, v10, v17
	v_exp_f32_e32 v94, v18
	v_sub_f32_e32 v18, v22, v38
	v_add_f32_e32 v17, v11, v17
	v_exp_f32_e32 v95, v18
	v_sub_f32_e32 v0, v0, v38
	v_add_f32_e32 v17, v36, v17
	v_exp_f32_e32 v97, v0
	v_sub_f32_e32 v0, v1, v38
	v_add_f32_e32 v17, v37, v17
	v_exp_f32_e32 v102, v0
	v_sub_f32_e32 v0, v2, v38
	v_add_f32_e32 v17, v94, v17
	v_exp_f32_e32 v96, v0
	v_sub_f32_e32 v0, v3, v38
	v_add_f32_e32 v17, v95, v17
	v_exp_f32_e32 v99, v0
	v_sub_f32_e32 v1, v23, v38
	v_add_f32_e32 v0, v97, v17
	v_exp_f32_e32 v86, v1
	v_sub_f32_e32 v1, v24, v38
	v_add_f32_e32 v0, v102, v0
	v_exp_f32_e32 v87, v1
	v_sub_f32_e32 v1, v25, v38
	v_add_f32_e32 v0, v96, v0
	v_exp_f32_e32 v88, v1
	v_sub_f32_e32 v1, v26, v38
	v_add_f32_e32 v0, v99, v0
	v_exp_f32_e32 v89, v1
	v_sub_f32_e32 v1, v27, v38
	v_add_f32_e32 v0, v86, v0
	v_exp_f32_e32 v91, v1
	v_sub_f32_e32 v1, v28, v38
	v_add_f32_e32 v0, v87, v0
	v_exp_f32_e32 v93, v1
	v_sub_f32_e32 v1, v29, v38
	v_add_f32_e32 v0, v88, v0
	v_exp_f32_e32 v90, v1
	v_sub_f32_e32 v1, v30, v38
	v_add_f32_e32 v0, v89, v0
	v_exp_f32_e32 v92, v1
	v_sub_f32_e32 v1, v31, v38
	v_add_f32_e32 v0, v91, v0
	v_exp_f32_e32 v74, v1
	v_sub_f32_e32 v1, v32, v38
	v_add_f32_e32 v0, v93, v0
	v_exp_f32_e32 v75, v1
	v_sub_f32_e32 v1, v39, v38
	v_add_f32_e32 v0, v90, v0
	v_exp_f32_e32 v76, v1
	v_sub_f32_e32 v1, v40, v38
	v_add_f32_e32 v0, v92, v0
	v_exp_f32_e32 v77, v1
	v_sub_f32_e32 v1, v4, v38
	v_add_f32_e32 v0, v74, v0
	v_exp_f32_e32 v79, v1
	v_sub_f32_e32 v1, v5, v38
	v_add_f32_e32 v0, v75, v0
	v_exp_f32_e32 v81, v1
	v_sub_f32_e32 v1, v6, v38
	v_add_f32_e32 v0, v76, v0
	v_exp_f32_e32 v78, v1
	v_sub_f32_e32 v1, v7, v38
	v_add_f32_e32 v0, v77, v0
	v_exp_f32_e32 v80, v1
	v_sub_f32_e32 v1, v41, v38
	v_add_f32_e32 v0, v79, v0
	v_exp_f32_e32 v66, v1
	v_sub_f32_e32 v1, v42, v38
	v_add_f32_e32 v0, v81, v0
	v_exp_f32_e32 v67, v1
	v_sub_f32_e32 v1, v43, v38
	v_add_f32_e32 v0, v78, v0
	v_exp_f32_e32 v68, v1
	v_sub_f32_e32 v1, v44, v38
	v_add_f32_e32 v0, v80, v0
	v_exp_f32_e32 v69, v1
	v_sub_f32_e32 v1, v45, v38
	v_add_f32_e32 v0, v66, v0
	v_exp_f32_e32 v71, v1
	v_sub_f32_e32 v1, v46, v38
	v_add_f32_e32 v0, v67, v0
	v_exp_f32_e32 v73, v1
	v_sub_f32_e32 v1, v47, v38
	v_add_f32_e32 v0, v68, v0
	v_exp_f32_e32 v70, v1
	v_sub_f32_e32 v1, v48, v38
	v_add_f32_e32 v0, v69, v0
	v_exp_f32_e32 v72, v1
	v_sub_f32_e32 v1, v49, v38
	v_add_f32_e32 v0, v71, v0
	v_exp_f32_e32 v58, v1
	v_sub_f32_e32 v1, v54, v38
	v_add_f32_e32 v0, v73, v0
	v_exp_f32_e32 v59, v1
	v_sub_f32_e32 v1, v55, v38
	v_add_f32_e32 v0, v70, v0
	v_exp_f32_e32 v60, v1
	v_sub_f32_e32 v1, v56, v38
	v_add_f32_e32 v0, v72, v0
	v_exp_f32_e32 v61, v1
	v_sub_f32_e32 v1, v34, v38
	v_add_f32_e32 v0, v58, v0
	v_exp_f32_e32 v63, v1
	v_sub_f32_e32 v1, v35, v38
	v_add_f32_e32 v0, v59, v0
	v_exp_f32_e32 v65, v1
	v_sub_f32_e32 v1, v57, v38
	v_add_f32_e32 v0, v60, v0
	v_exp_f32_e32 v62, v1
	v_sub_f32_e32 v1, v64, v38
	v_add_f32_e32 v0, v61, v0
	v_exp_f32_e32 v64, v1
	v_sub_f32_e32 v1, v103, v38
	v_add_f32_e32 v0, v63, v0
	v_exp_f32_e32 v50, v1
	v_sub_f32_e32 v1, v104, v38
	v_add_f32_e32 v0, v65, v0
	v_exp_f32_e32 v51, v1
	v_sub_f32_e32 v1, v105, v38
	v_add_f32_e32 v0, v62, v0
	v_exp_f32_e32 v52, v1
	v_sub_f32_e32 v1, v106, v38
	v_add_f32_e32 v0, v64, v0
	v_exp_f32_e32 v53, v1
	v_sub_f32_e32 v1, v107, v38
	v_add_f32_e32 v0, v50, v0
	v_exp_f32_e32 v55, v1
	v_sub_f32_e32 v1, v108, v38
	v_add_f32_e32 v0, v51, v0
	v_exp_f32_e32 v57, v1
	v_sub_f32_e32 v1, v109, v38
	v_add_f32_e32 v0, v52, v0
	v_exp_f32_e32 v54, v1
	v_sub_f32_e32 v1, v110, v38
	v_add_f32_e32 v0, v53, v0
	v_exp_f32_e32 v56, v1
	v_sub_f32_e32 v1, v111, v38
	v_add_f32_e32 v0, v55, v0
	v_exp_f32_e32 v42, v1
	v_sub_f32_e32 v1, v112, v38
	v_add_f32_e32 v0, v57, v0
	v_exp_f32_e32 v43, v1
	v_sub_f32_e32 v1, v113, v38
	v_add_f32_e32 v0, v54, v0
	v_exp_f32_e32 v44, v1
	v_sub_f32_e32 v1, v114, v38
	v_add_f32_e32 v0, v56, v0
	v_exp_f32_e32 v45, v1
	v_sub_f32_e32 v1, v115, v38
	v_add_f32_e32 v0, v42, v0
	v_exp_f32_e32 v47, v1
	v_sub_f32_e32 v1, v116, v38
	v_add_f32_e32 v0, v43, v0
	v_exp_f32_e32 v49, v1
	v_sub_f32_e32 v1, v117, v38
	v_add_f32_e32 v0, v44, v0
	v_exp_f32_e32 v46, v1
	v_sub_f32_e32 v1, v16, v38
	v_add_f32_e32 v0, v45, v0
	v_exp_f32_e32 v48, v1
	v_add_f32_e32 v0, v47, v0
	v_add_f32_e32 v0, v49, v0
	v_add_f32_e32 v0, v46, v0
	v_add_f32_e32 v0, v48, v0
	ds_bpermute_b32 v1, v100, v0
	v_cvt_pk_bf16_f32 v2, v8, v9
	v_cvt_pk_bf16_f32 v3, v10, v11
	s_waitcnt lgkmcnt(0)
	v_add_f32_e32 v39, v0, v1
	ds_bpermute_b32 v40, v101, v39
	v_lshrrev_b32_e32 v0, 2, v85
	v_or_b32_e32 v0, v83, v0
	v_lshlrev_b32_e32 v1, 3, v98
	v_mul_u32_u24_e32 v0, 0x120, v0
	v_and_b32_e32 v1, 24, v1
	v_add3_u32 v41, s27, v0, v1
	v_cvt_pk_bf16_f32 v0, v12, v13
	v_cvt_pk_bf16_f32 v1, v14, v15
	s_cbranch_vccnz .LBB0_1371
	ds_read_b64_tr_b16 v[4:5], v41
	ds_read_b64_tr_b16 v[8:9], v41 offset:32
	ds_read_b64_tr_b16 v[12:13], v41 offset:64
	ds_read_b64_tr_b16 v[16:17], v41 offset:96
	ds_read_b64_tr_b16 v[6:7], v41 offset:4608
	ds_read_b64_tr_b16 v[10:11], v41 offset:4640
	ds_read_b64_tr_b16 v[14:15], v41 offset:4672
	ds_read_b64_tr_b16 v[18:19], v41 offset:4704
	ds_read_b64_tr_b16 v[104:105], v41 offset:128
	ds_read_b64_tr_b16 v[108:109], v41 offset:160
	ds_read_b64_tr_b16 v[112:113], v41 offset:192
	ds_read_b64_tr_b16 v[116:117], v41 offset:224
	ds_read_b64_tr_b16 v[106:107], v41 offset:4736
	ds_read_b64_tr_b16 v[110:111], v41 offset:4768
	ds_read_b64_tr_b16 v[114:115], v41 offset:4800
	ds_read_b64_tr_b16 v[118:119], v41 offset:4832
	s_waitcnt lgkmcnt(11)
	v_mfma_f32_16x16x32_bf16 v[28:31], v[4:7], v[0:3], 0
	s_waitcnt lgkmcnt(10)
	v_mfma_f32_16x16x32_bf16 v[24:27], v[8:11], v[0:3], 0
	s_waitcnt lgkmcnt(9)
	v_mfma_f32_16x16x32_bf16 v[20:23], v[12:15], v[0:3], 0
	s_waitcnt lgkmcnt(8)
	v_mfma_f32_16x16x32_bf16 v[16:19], v[16:19], v[0:3], 0
	s_waitcnt lgkmcnt(3)
	v_mfma_f32_16x16x32_bf16 v[12:15], v[104:107], v[0:3], 0
	s_waitcnt lgkmcnt(2)
	v_mfma_f32_16x16x32_bf16 v[8:11], v[108:111], v[0:3], 0
	s_waitcnt lgkmcnt(1)
	v_mfma_f32_16x16x32_bf16 v[4:7], v[112:115], v[0:3], 0
	s_waitcnt lgkmcnt(0)
	v_mfma_f32_16x16x32_bf16 v[0:3], v[116:119], v[0:3], 0
	s_branch .LBB0_1372

.Lpf_issue:
	v_readlane_b32 s50, v252, 56
	v_readlane_b32 s51, v252, 55
	v_readlane_b32 s52, v253, 22
	v_lshrrev_b32_e32 v244, 4, v218
	v_and_b32_e32 v227, 15, v218
	v_lshrrev_b32_e32 v245, 6, v218
	v_lshl_or_b32 v245, v245, 4, v227
	v_lshlrev_b32_e32 v227, 4, v227
	s_and_b32 s53, s48, 1
	s_lshl_b32 s53, s53, 1
	s_or_b32 s50, s50, s53
	s_lshr_b32 s51, s51, 2
	s_lshl_b32 s52, s52, 8
	s_lshr_b32 s53, s48, 1
	s_cmp_eq_u32 s53, 3
	s_cbranch_scc1 .Lpf_mem
	s_lshl_b32 s54, s53, 1
	s_mov_b32 s55, 32
	s_lshr_b32 s55, s55, s54
	s_sub_u32 s55, s55, 1
	s_and_b32 s55, s51, s55
	s_sub_u32 s56, 5, s54
	s_lshr_b32 s56, s51, s56
	s_add_u32 s57, s54, 7
	s_lshl_b32 s57, s55, s57
	s_lshl_b32 s58, s50, 12
	s_add_u32 s57, s57, s58
	s_add_u32 s57, s57, s56
	s_mul_i32 s57, s57, 0x5400
	s_add_u32 s58, s24, 0x11102000
	s_addc_u32 s59, s25, 0
	s_add_u32 s58, s58, s52
	s_addc_u32 s59, s59, 0
	s_add_u32 s58, s58, s57
	s_addc_u32 s59, s59, 0
	s_lshl_b32 s60, s53, 10
	s_add_u32 s60, s60, 0x11101400
	s_add_u32 s60, s60, s52
	s_add_u32 s60, s60, s57
	s_add_u32 s60, s24, s60
	s_addc_u32 s61, s25, 0
	s_mov_b32 s62, 0xa8000
	s_lshl_b32 s62, s62, s54
	s_lshl_b32 s63, s62, 2
	s_cmp_eq_u32 s55, 0
	s_cselect_b32 s63, 0, s63
	s_sub_u32 s56, s58, s63
	s_subb_u32 s57, s59, 0
	s_movk_i32 s55, 0x5400
	s_lshl_b32 s55, s55, s54
	v_mul_lo_u32 v244, v244, s55
	v_mul_lo_u32 v245, v245, s55
	s_branch .Lpf_loads
.Lpf_mem:
	s_lshl_b32 s54, s50, 21
	s_add_u32 s56, s66, s52
	s_addc_u32 s57, s67, 0
	s_add_u32 s56, s56, s54
	s_addc_u32 s57, s57, 0
	s_add_u32 s58, s56, 0x100000
	s_addc_u32 s59, s57, 0
	s_mov_b32 s62, 0x40000
	s_lshl_b32 s54, s50, 5
	s_add_u32 s54, s54, s51
	s_lshl_b32 s54, s54, 7
	s_mul_i32 s54, s54, 0x5400
	s_add_u32 s54, s54, 0x11102c00
	s_add_u32 s54, s54, s52
	s_add_u32 s60, s24, s54
	s_addc_u32 s61, s25, 0
	v_lshlrev_b32_e32 v244, 13, v244
	v_mul_u32_u24_e32 v245, 0x5400, v245
.Lpf_loads:
	v_add_u32_e32 v244, v244, v227
	v_bfe_u32 v227, v218, 4, 2
	v_lshl_add_u32 v245, v227, 4, v245
	global_load_dwordx4 v[154:157], v244, s[56:57]
	global_load_dwordx4 v[158:161], v244, s[56:57] offset:1024
	s_add_u32 s56, s56, s62
	s_addc_u32 s57, s57, 0
	global_load_dwordx4 v[162:165], v244, s[56:57]
	global_load_dwordx4 v[166:169], v244, s[56:57] offset:1024
	s_add_u32 s56, s56, s62
	s_addc_u32 s57, s57, 0
	global_load_dwordx4 v[170:173], v244, s[56:57]
	global_load_dwordx4 v[174:177], v244, s[56:57] offset:1024
	s_add_u32 s56, s56, s62
	s_addc_u32 s57, s57, 0
	global_load_dwordx4 v[178:181], v244, s[56:57]
	global_load_dwordx4 v[182:185], v244, s[56:57] offset:1024
	global_load_dwordx4 v[186:189], v244, s[58:59]
	global_load_dwordx4 v[190:193], v244, s[58:59] offset:1024
	s_add_u32 s58, s58, s62
	s_addc_u32 s59, s59, 0
	global_load_dwordx4 v[194:197], v244, s[58:59]
	global_load_dwordx4 v[198:201], v244, s[58:59] offset:1024
	s_add_u32 s58, s58, s62
	s_addc_u32 s59, s59, 0
	global_load_dwordx4 v[202:205], v244, s[58:59]
	global_load_dwordx4 v[206:209], v244, s[58:59] offset:1024
	s_add_u32 s58, s58, s62
	s_addc_u32 s59, s59, 0
	global_load_dwordx4 v[210:213], v244, s[58:59]
	global_load_dwordx4 v[214:217], v244, s[58:59] offset:1024
	global_load_dwordx4 v[228:231], v245, s[60:61]
	global_load_dwordx4 v[232:235], v245, s[60:61] offset:64
	global_load_dwordx4 v[236:239], v245, s[60:61] offset:128
	global_load_dwordx4 v[240:243], v245, s[60:61] offset:192
	s_cmp_eq_u32 s48, 0
	s_cbranch_scc1 .Lpf_ret_pre
	s_cmp_lt_u32 s48, 3
	s_cbranch_scc1 .Lpf_ret_k0
	s_cmp_lt_u32 s48, 5
	s_cbranch_scc1 .Lpf_ret_k1
	s_cmp_lt_u32 s48, 7
	s_cbranch_scc1 .Lpf_ret_k2
	s_branch .Lpf_ret_k3
